# removed s_nop 0 after packed-f32 ops in the four scan loops (compiler false-positive dst_sel hazard); numerics unchanged
# speedup vs baseline: 1.0019x; 1.0019x over previous
.LBB0_417:
	s_add_i32 s19, s26, 1
	s_bitcmp1_b32 s26, 0
	s_cselect_b32 s26, 0x6000, 0
	s_add_i32 s26, s78, s26
	v_add_u32_e32 v41, s26, v9
	ds_read_b128 v[44:47], v41 offset:4096
	ds_read_b128 v[48:51], v41 offset:8192
	v_lshl_add_u32 v42, v8, 2, s26
	v_add_u32_e32 v43, 0x5000, v42
	ds_read2_b32 v[68:69], v43 offset1:32
	ds_read_b128 v[52:55], v41
	ds_read_b128 v[56:59], v41 offset:16
	ds_read_b128 v[60:63], v41 offset:4112
	ds_read_b128 v[64:67], v41 offset:8208
	s_andn2_b64 vcc, exec, s[20:21]
	s_waitcnt lgkmcnt(4)
	v_pk_mul_f32 v[70:71], v[48:49], v[68:69] op_sel_hi:[1,0]
	v_pk_fma_f32 v[34:35], v[34:35], v[44:45], v[70:71]
	v_pk_mul_f32 v[70:71], v[50:51], v[68:69] op_sel_hi:[1,0]
	v_pk_fma_f32 v[70:71], v[32:33], v[46:47], v[70:71]
	s_waitcnt lgkmcnt(0)
	v_pk_mul_f32 v[32:33], v[64:65], v[68:69] op_sel_hi:[1,0]
	v_pk_fma_f32 v[72:73], v[30:31], v[60:61], v[32:33]
	v_pk_mul_f32 v[30:31], v[66:67], v[68:69] op_sel_hi:[1,0]
	v_pk_fma_f32 v[74:75], v[28:29], v[62:63], v[30:31]
	v_pk_mul_f32 v[28:29], v[54:55], v[70:71]
	v_pk_fma_f32 v[28:29], v[52:53], v[34:35], v[28:29]
	v_pk_fma_f32 v[28:29], v[56:57], v[72:73], v[28:29]
	v_pk_fma_f32 v[28:29], v[58:59], v[74:75], v[28:29]
	v_add_f32_e32 v28, v28, v29
	s_nop 1
	v_add_f32_dpp v28, v28, v28 quad_perm:[1,0,3,2] row_mask:0xf bank_mask:0xf bound_ctrl:1
	s_nop 1
	v_add_f32_dpp v28, v28, v28 quad_perm:[2,3,0,1] row_mask:0xf bank_mask:0xf bound_ctrl:1
	s_nop 1
	v_add_f32_dpp v28, v28, v28 row_half_mirror row_mask:0xf bank_mask:0xf bound_ctrl:1
	v_cndmask_b32_e64 v78, 0, v28, s[0:1]
	v_mov_b32_e32 v28, v69
	v_pk_mul_f32 v[30:31], v[48:49], v[28:29] op_sel_hi:[1,0]
	v_pk_fma_f32 v[68:69], v[26:27], v[44:45], v[30:31]
	v_pk_mul_f32 v[26:27], v[50:51], v[28:29] op_sel_hi:[1,0]
	v_pk_fma_f32 v[76:77], v[24:25], v[46:47], v[26:27]
	v_pk_mul_f32 v[24:25], v[64:65], v[28:29] op_sel_hi:[1,0]
	v_pk_fma_f32 v[60:61], v[22:23], v[60:61], v[24:25]
	v_pk_mul_f32 v[22:23], v[66:67], v[28:29] op_sel_hi:[1,0]
	v_pk_fma_f32 v[6:7], v[6:7], v[62:63], v[22:23]
	v_pk_mul_f32 v[22:23], v[54:55], v[76:77]
	v_pk_fma_f32 v[22:23], v[52:53], v[68:69], v[22:23]
	v_pk_fma_f32 v[22:23], v[56:57], v[60:61], v[22:23]
	v_pk_fma_f32 v[22:23], v[58:59], v[6:7], v[22:23]
	v_add_f32_e32 v22, v22, v23
	s_nop 1
	v_add_f32_dpp v22, v22, v22 quad_perm:[1,0,3,2] row_mask:0xf bank_mask:0xf bound_ctrl:1
	s_nop 1
	v_add_f32_dpp v22, v22, v22 quad_perm:[2,3,0,1] row_mask:0xf bank_mask:0xf bound_ctrl:1
	s_nop 1
	v_add_f32_dpp v22, v22, v22 row_half_mirror row_mask:0xf bank_mask:0xf bound_ctrl:1
	v_cndmask_b32_e64 v79, 0, v22, s[0:1]
	ds_read_b128 v[22:25], v41 offset:4352
	ds_read_b128 v[26:29], v41 offset:8448
	ds_read2_b32 v[56:57], v43 offset0:64 offset1:96
	ds_read_b128 v[30:33], v41 offset:256
	ds_read_b128 v[44:47], v41 offset:272
	ds_read_b128 v[48:51], v41 offset:4368
	ds_read_b128 v[52:55], v41 offset:8464
	s_waitcnt lgkmcnt(4)
	v_pk_mul_f32 v[58:59], v[26:27], v[56:57] op_sel_hi:[1,0]
	s_waitcnt lgkmcnt(0)
	v_pk_mul_f32 v[62:63], v[52:53], v[56:57] op_sel_hi:[1,0]
	v_pk_fma_f32 v[34:35], v[34:35], v[22:23], v[58:59]
	v_pk_mul_f32 v[58:59], v[28:29], v[56:57] op_sel_hi:[1,0]
	v_pk_fma_f32 v[62:63], v[72:73], v[48:49], v[62:63]
	v_pk_fma_f32 v[58:59], v[70:71], v[24:25], v[58:59]
	v_pk_mul_f32 v[64:65], v[54:55], v[56:57] op_sel_hi:[1,0]
	v_pk_mul_f32 v[66:67], v[32:33], v[58:59]
	v_pk_fma_f32 v[64:65], v[74:75], v[50:51], v[64:65]
	v_pk_fma_f32 v[66:67], v[30:31], v[34:35], v[66:67]
	v_pk_fma_f32 v[66:67], v[44:45], v[62:63], v[66:67]
	v_pk_fma_f32 v[66:67], v[46:47], v[64:65], v[66:67]
	v_add_f32_e32 v56, v66, v67
	s_nop 1
	v_add_f32_dpp v56, v56, v56 quad_perm:[1,0,3,2] row_mask:0xf bank_mask:0xf bound_ctrl:1
	s_nop 1
	v_add_f32_dpp v56, v56, v56 quad_perm:[2,3,0,1] row_mask:0xf bank_mask:0xf bound_ctrl:1
	s_nop 1
	v_add_f32_dpp v56, v56, v56 row_half_mirror row_mask:0xf bank_mask:0xf bound_ctrl:1
	v_cndmask_b32_e64 v72, v78, v56, s[16:17]
	v_mov_b32_e32 v56, v57
	v_pk_mul_f32 v[26:27], v[26:27], v[56:57] op_sel_hi:[1,0]
	v_pk_fma_f32 v[66:67], v[68:69], v[22:23], v[26:27]
	v_pk_mul_f32 v[22:23], v[28:29], v[56:57] op_sel_hi:[1,0]
	v_pk_fma_f32 v[68:69], v[76:77], v[24:25], v[22:23]
	v_pk_mul_f32 v[22:23], v[52:53], v[56:57] op_sel_hi:[1,0]
	v_pk_fma_f32 v[60:61], v[60:61], v[48:49], v[22:23]
	v_pk_mul_f32 v[22:23], v[54:55], v[56:57] op_sel_hi:[1,0]
	v_pk_fma_f32 v[6:7], v[6:7], v[50:51], v[22:23]
	v_pk_mul_f32 v[22:23], v[32:33], v[68:69]
	v_pk_fma_f32 v[22:23], v[30:31], v[66:67], v[22:23]
	v_pk_fma_f32 v[22:23], v[44:45], v[60:61], v[22:23]
	v_pk_fma_f32 v[22:23], v[46:47], v[6:7], v[22:23]
	v_add_f32_e32 v22, v22, v23
	s_nop 1
	v_add_f32_dpp v22, v22, v22 quad_perm:[1,0,3,2] row_mask:0xf bank_mask:0xf bound_ctrl:1
	s_nop 1
	v_add_f32_dpp v22, v22, v22 quad_perm:[2,3,0,1] row_mask:0xf bank_mask:0xf bound_ctrl:1
	s_nop 1
	v_add_f32_dpp v22, v22, v22 row_half_mirror row_mask:0xf bank_mask:0xf bound_ctrl:1
	v_cndmask_b32_e64 v73, v79, v22, s[16:17]
	ds_read_b128 v[22:25], v41 offset:4608
	ds_read_b128 v[26:29], v41 offset:8704
	ds_read2_b32 v[56:57], v43 offset0:128 offset1:160
	ds_read_b128 v[30:33], v41 offset:512
	ds_read_b128 v[44:47], v41 offset:528
	ds_read_b128 v[48:51], v41 offset:4624
	ds_read_b128 v[52:55], v41 offset:8720
	s_waitcnt lgkmcnt(4)
	v_pk_mul_f32 v[70:71], v[26:27], v[56:57] op_sel_hi:[1,0]
	v_pk_fma_f32 v[34:35], v[34:35], v[22:23], v[70:71]
	v_pk_mul_f32 v[70:71], v[28:29], v[56:57] op_sel_hi:[1,0]
	v_pk_fma_f32 v[58:59], v[58:59], v[24:25], v[70:71]
	s_waitcnt lgkmcnt(0)
	v_pk_mul_f32 v[70:71], v[52:53], v[56:57] op_sel_hi:[1,0]
	v_pk_fma_f32 v[62:63], v[62:63], v[48:49], v[70:71]
	v_pk_mul_f32 v[70:71], v[54:55], v[56:57] op_sel_hi:[1,0]
	v_pk_fma_f32 v[64:65], v[64:65], v[50:51], v[70:71]
	v_pk_mul_f32 v[70:71], v[32:33], v[58:59]
	v_pk_fma_f32 v[70:71], v[30:31], v[34:35], v[70:71]
	v_pk_fma_f32 v[70:71], v[44:45], v[62:63], v[70:71]
	v_pk_fma_f32 v[70:71], v[46:47], v[64:65], v[70:71]
	v_add_f32_e32 v56, v70, v71
	s_nop 1
	v_add_f32_dpp v56, v56, v56 quad_perm:[1,0,3,2] row_mask:0xf bank_mask:0xf bound_ctrl:1
	s_nop 1
	v_add_f32_dpp v56, v56, v56 quad_perm:[2,3,0,1] row_mask:0xf bank_mask:0xf bound_ctrl:1
	s_nop 1
	v_add_f32_dpp v56, v56, v56 row_half_mirror row_mask:0xf bank_mask:0xf bound_ctrl:1
	v_cndmask_b32_e64 v72, v72, v56, s[4:5]
	v_mov_b32_e32 v56, v57
	v_pk_mul_f32 v[26:27], v[26:27], v[56:57] op_sel_hi:[1,0]
	v_pk_fma_f32 v[66:67], v[66:67], v[22:23], v[26:27]
	v_pk_mul_f32 v[22:23], v[28:29], v[56:57] op_sel_hi:[1,0]
	v_pk_fma_f32 v[68:69], v[68:69], v[24:25], v[22:23]
	v_pk_mul_f32 v[22:23], v[52:53], v[56:57] op_sel_hi:[1,0]
	v_pk_fma_f32 v[60:61], v[60:61], v[48:49], v[22:23]
	v_pk_mul_f32 v[22:23], v[54:55], v[56:57] op_sel_hi:[1,0]
	v_pk_fma_f32 v[6:7], v[6:7], v[50:51], v[22:23]
	v_pk_mul_f32 v[22:23], v[32:33], v[68:69]
	v_pk_fma_f32 v[22:23], v[30:31], v[66:67], v[22:23]
	v_pk_fma_f32 v[22:23], v[44:45], v[60:61], v[22:23]
	v_pk_fma_f32 v[22:23], v[46:47], v[6:7], v[22:23]
	v_add_f32_e32 v22, v22, v23
	s_nop 1
	v_add_f32_dpp v22, v22, v22 quad_perm:[1,0,3,2] row_mask:0xf bank_mask:0xf bound_ctrl:1
	s_nop 1
	v_add_f32_dpp v22, v22, v22 quad_perm:[2,3,0,1] row_mask:0xf bank_mask:0xf bound_ctrl:1
	s_nop 1
	v_add_f32_dpp v22, v22, v22 row_half_mirror row_mask:0xf bank_mask:0xf bound_ctrl:1
	v_cndmask_b32_e64 v73, v73, v22, s[4:5]
	ds_read_b128 v[22:25], v41 offset:4864
	ds_read_b128 v[26:29], v41 offset:8960
	ds_read2_b32 v[56:57], v43 offset0:192 offset1:224
	ds_read_b128 v[30:33], v41 offset:768
	ds_read_b128 v[44:47], v41 offset:784
	ds_read_b128 v[48:51], v41 offset:4880
	ds_read_b128 v[52:55], v41 offset:8976
	s_waitcnt lgkmcnt(4)
	v_pk_mul_f32 v[70:71], v[26:27], v[56:57] op_sel_hi:[1,0]
	v_pk_fma_f32 v[34:35], v[34:35], v[22:23], v[70:71]
	v_pk_mul_f32 v[70:71], v[28:29], v[56:57] op_sel_hi:[1,0]
	v_pk_fma_f32 v[58:59], v[58:59], v[24:25], v[70:71]
	s_waitcnt lgkmcnt(0)
	v_pk_mul_f32 v[70:71], v[52:53], v[56:57] op_sel_hi:[1,0]
	v_pk_fma_f32 v[62:63], v[62:63], v[48:49], v[70:71]
	v_pk_mul_f32 v[70:71], v[54:55], v[56:57] op_sel_hi:[1,0]
	v_mov_b32_e32 v56, v57
	v_pk_mul_f32 v[26:27], v[26:27], v[56:57] op_sel_hi:[1,0]
	v_pk_fma_f32 v[64:65], v[64:65], v[50:51], v[70:71]
	v_pk_fma_f32 v[66:67], v[66:67], v[22:23], v[26:27]
	v_pk_mul_f32 v[22:23], v[28:29], v[56:57] op_sel_hi:[1,0]
	v_pk_mul_f32 v[70:71], v[32:33], v[58:59]
	v_pk_fma_f32 v[68:69], v[68:69], v[24:25], v[22:23]
	v_pk_mul_f32 v[22:23], v[52:53], v[56:57] op_sel_hi:[1,0]
	v_pk_fma_f32 v[70:71], v[30:31], v[34:35], v[70:71]
	v_pk_fma_f32 v[60:61], v[60:61], v[48:49], v[22:23]
	v_pk_mul_f32 v[22:23], v[54:55], v[56:57] op_sel_hi:[1,0]
	v_pk_fma_f32 v[70:71], v[44:45], v[62:63], v[70:71]
	v_pk_fma_f32 v[6:7], v[6:7], v[50:51], v[22:23]
	v_pk_mul_f32 v[22:23], v[32:33], v[68:69]
	v_pk_fma_f32 v[70:71], v[46:47], v[64:65], v[70:71]
	v_pk_fma_f32 v[22:23], v[30:31], v[66:67], v[22:23]
	v_add_f32_e32 v43, v70, v71
	v_pk_fma_f32 v[22:23], v[44:45], v[60:61], v[22:23]
	v_pk_fma_f32 v[22:23], v[46:47], v[6:7], v[22:23]
	v_add_f32_dpp v43, v43, v43 quad_perm:[1,0,3,2] row_mask:0xf bank_mask:0xf bound_ctrl:1
	v_add_f32_e32 v22, v22, v23
	s_nop 0
	v_add_f32_dpp v43, v43, v43 quad_perm:[2,3,0,1] row_mask:0xf bank_mask:0xf bound_ctrl:1
	v_add_f32_dpp v22, v22, v22 quad_perm:[1,0,3,2] row_mask:0xf bank_mask:0xf bound_ctrl:1
	s_nop 0
	v_add_f32_dpp v43, v43, v43 row_half_mirror row_mask:0xf bank_mask:0xf bound_ctrl:1
	v_add_f32_dpp v22, v22, v22 quad_perm:[2,3,0,1] row_mask:0xf bank_mask:0xf bound_ctrl:1
	v_cndmask_b32_e64 v43, v72, v43, s[6:7]
	s_nop 0
	v_add_f32_dpp v22, v22, v22 row_half_mirror row_mask:0xf bank_mask:0xf bound_ctrl:1
	v_cndmask_b32_e64 v72, v73, v22, s[6:7]
	ds_read_b128 v[22:25], v41 offset:5120
	ds_read_b128 v[26:29], v41 offset:9216
	v_add_u32_e32 v73, 0x5400, v42
	ds_read2_b32 v[56:57], v73 offset1:32
	ds_read_b128 v[30:33], v41 offset:1024
	ds_read_b128 v[44:47], v41 offset:1040
	ds_read_b128 v[48:51], v41 offset:5136
	ds_read_b128 v[52:55], v41 offset:9232
	s_waitcnt lgkmcnt(4)
	v_pk_mul_f32 v[70:71], v[26:27], v[56:57] op_sel_hi:[1,0]
	v_pk_fma_f32 v[34:35], v[34:35], v[22:23], v[70:71]
	v_pk_mul_f32 v[70:71], v[28:29], v[56:57] op_sel_hi:[1,0]
	v_pk_fma_f32 v[58:59], v[58:59], v[24:25], v[70:71]
	s_waitcnt lgkmcnt(0)
	v_pk_mul_f32 v[70:71], v[52:53], v[56:57] op_sel_hi:[1,0]
	v_pk_fma_f32 v[62:63], v[62:63], v[48:49], v[70:71]
	v_pk_mul_f32 v[70:71], v[54:55], v[56:57] op_sel_hi:[1,0]
	v_pk_fma_f32 v[64:65], v[64:65], v[50:51], v[70:71]
	v_pk_mul_f32 v[70:71], v[32:33], v[58:59]
	v_pk_fma_f32 v[70:71], v[30:31], v[34:35], v[70:71]
	v_pk_fma_f32 v[70:71], v[44:45], v[62:63], v[70:71]
	v_pk_fma_f32 v[70:71], v[46:47], v[64:65], v[70:71]
	v_add_f32_e32 v56, v70, v71
	s_nop 1
	v_add_f32_dpp v56, v56, v56 quad_perm:[1,0,3,2] row_mask:0xf bank_mask:0xf bound_ctrl:1
	s_nop 1
	v_add_f32_dpp v56, v56, v56 quad_perm:[2,3,0,1] row_mask:0xf bank_mask:0xf bound_ctrl:1
	s_nop 1
	v_add_f32_dpp v56, v56, v56 row_half_mirror row_mask:0xf bank_mask:0xf bound_ctrl:1
	v_cndmask_b32_e64 v43, v43, v56, s[8:9]
	v_mov_b32_e32 v56, v57
	v_pk_mul_f32 v[26:27], v[26:27], v[56:57] op_sel_hi:[1,0]
	v_pk_fma_f32 v[66:67], v[66:67], v[22:23], v[26:27]
	v_pk_mul_f32 v[22:23], v[28:29], v[56:57] op_sel_hi:[1,0]
	v_pk_fma_f32 v[68:69], v[68:69], v[24:25], v[22:23]
	v_pk_mul_f32 v[22:23], v[52:53], v[56:57] op_sel_hi:[1,0]
	v_pk_fma_f32 v[60:61], v[60:61], v[48:49], v[22:23]
	v_pk_mul_f32 v[22:23], v[54:55], v[56:57] op_sel_hi:[1,0]
	v_pk_fma_f32 v[6:7], v[6:7], v[50:51], v[22:23]
	v_pk_mul_f32 v[22:23], v[32:33], v[68:69]
	v_pk_fma_f32 v[22:23], v[30:31], v[66:67], v[22:23]
	v_pk_fma_f32 v[22:23], v[44:45], v[60:61], v[22:23]
	v_pk_fma_f32 v[22:23], v[46:47], v[6:7], v[22:23]
	v_add_f32_e32 v22, v22, v23
	s_nop 1
	v_add_f32_dpp v22, v22, v22 quad_perm:[1,0,3,2] row_mask:0xf bank_mask:0xf bound_ctrl:1
	s_nop 1
	v_add_f32_dpp v22, v22, v22 quad_perm:[2,3,0,1] row_mask:0xf bank_mask:0xf bound_ctrl:1
	s_nop 1
	v_add_f32_dpp v22, v22, v22 row_half_mirror row_mask:0xf bank_mask:0xf bound_ctrl:1
	v_cndmask_b32_e64 v72, v72, v22, s[8:9]
	ds_read_b128 v[22:25], v41 offset:5376
	ds_read_b128 v[26:29], v41 offset:9472
	ds_read2_b32 v[56:57], v73 offset0:64 offset1:96
	ds_read_b128 v[30:33], v41 offset:1280
	ds_read_b128 v[44:47], v41 offset:1296
	ds_read_b128 v[48:51], v41 offset:5392
	ds_read_b128 v[52:55], v41 offset:9488
	s_waitcnt lgkmcnt(4)
	v_pk_mul_f32 v[70:71], v[26:27], v[56:57] op_sel_hi:[1,0]
	v_pk_fma_f32 v[34:35], v[34:35], v[22:23], v[70:71]
	v_pk_mul_f32 v[70:71], v[28:29], v[56:57] op_sel_hi:[1,0]
	v_pk_fma_f32 v[58:59], v[58:59], v[24:25], v[70:71]
	s_waitcnt lgkmcnt(0)
	v_pk_mul_f32 v[70:71], v[52:53], v[56:57] op_sel_hi:[1,0]
	v_pk_fma_f32 v[62:63], v[62:63], v[48:49], v[70:71]
	v_pk_mul_f32 v[70:71], v[54:55], v[56:57] op_sel_hi:[1,0]
	v_pk_fma_f32 v[64:65], v[64:65], v[50:51], v[70:71]
	v_pk_mul_f32 v[70:71], v[32:33], v[58:59]
	v_pk_fma_f32 v[70:71], v[30:31], v[34:35], v[70:71]
	v_pk_fma_f32 v[70:71], v[44:45], v[62:63], v[70:71]
	v_pk_fma_f32 v[70:71], v[46:47], v[64:65], v[70:71]
	v_add_f32_e32 v56, v70, v71
	s_nop 1
	v_add_f32_dpp v56, v56, v56 quad_perm:[1,0,3,2] row_mask:0xf bank_mask:0xf bound_ctrl:1
	s_nop 1
	v_add_f32_dpp v56, v56, v56 quad_perm:[2,3,0,1] row_mask:0xf bank_mask:0xf bound_ctrl:1
	s_nop 1
	v_add_f32_dpp v56, v56, v56 row_half_mirror row_mask:0xf bank_mask:0xf bound_ctrl:1
	v_cndmask_b32_e64 v43, v43, v56, s[10:11]
	v_mov_b32_e32 v56, v57
	v_pk_mul_f32 v[26:27], v[26:27], v[56:57] op_sel_hi:[1,0]
	v_pk_fma_f32 v[66:67], v[66:67], v[22:23], v[26:27]
	v_pk_mul_f32 v[22:23], v[28:29], v[56:57] op_sel_hi:[1,0]
	v_pk_fma_f32 v[68:69], v[68:69], v[24:25], v[22:23]
	v_pk_mul_f32 v[22:23], v[52:53], v[56:57] op_sel_hi:[1,0]
	v_pk_fma_f32 v[60:61], v[60:61], v[48:49], v[22:23]
	v_pk_mul_f32 v[22:23], v[54:55], v[56:57] op_sel_hi:[1,0]
	v_pk_fma_f32 v[6:7], v[6:7], v[50:51], v[22:23]
	v_pk_mul_f32 v[22:23], v[32:33], v[68:69]
	v_pk_fma_f32 v[22:23], v[30:31], v[66:67], v[22:23]
	v_pk_fma_f32 v[22:23], v[44:45], v[60:61], v[22:23]
	v_pk_fma_f32 v[22:23], v[46:47], v[6:7], v[22:23]
	v_add_f32_e32 v22, v22, v23
	s_nop 1
	v_add_f32_dpp v22, v22, v22 quad_perm:[1,0,3,2] row_mask:0xf bank_mask:0xf bound_ctrl:1
	s_nop 1
	v_add_f32_dpp v22, v22, v22 quad_perm:[2,3,0,1] row_mask:0xf bank_mask:0xf bound_ctrl:1
	s_nop 1
	v_add_f32_dpp v22, v22, v22 row_half_mirror row_mask:0xf bank_mask:0xf bound_ctrl:1
	v_cndmask_b32_e64 v72, v72, v22, s[10:11]
	ds_read_b128 v[22:25], v41 offset:5632
	ds_read_b128 v[26:29], v41 offset:9728
	ds_read2_b32 v[56:57], v73 offset0:128 offset1:160
	ds_read_b128 v[30:33], v41 offset:1536
	ds_read_b128 v[44:47], v41 offset:1552
	ds_read_b128 v[48:51], v41 offset:5648
	ds_read_b128 v[52:55], v41 offset:9744
	s_waitcnt lgkmcnt(4)
	v_pk_mul_f32 v[70:71], v[26:27], v[56:57] op_sel_hi:[1,0]
	v_pk_fma_f32 v[34:35], v[34:35], v[22:23], v[70:71]
	v_pk_mul_f32 v[70:71], v[28:29], v[56:57] op_sel_hi:[1,0]
	v_pk_fma_f32 v[58:59], v[58:59], v[24:25], v[70:71]
	s_waitcnt lgkmcnt(0)
	v_pk_mul_f32 v[70:71], v[52:53], v[56:57] op_sel_hi:[1,0]
	v_pk_fma_f32 v[62:63], v[62:63], v[48:49], v[70:71]
	v_pk_mul_f32 v[70:71], v[54:55], v[56:57] op_sel_hi:[1,0]
	v_pk_fma_f32 v[64:65], v[64:65], v[50:51], v[70:71]
	v_pk_mul_f32 v[70:71], v[32:33], v[58:59]
	v_pk_fma_f32 v[70:71], v[30:31], v[34:35], v[70:71]
	v_pk_fma_f32 v[70:71], v[44:45], v[62:63], v[70:71]
	v_pk_fma_f32 v[70:71], v[46:47], v[64:65], v[70:71]
	v_add_f32_e32 v56, v70, v71
	s_nop 1
	v_add_f32_dpp v56, v56, v56 quad_perm:[1,0,3,2] row_mask:0xf bank_mask:0xf bound_ctrl:1
	s_nop 1
	v_add_f32_dpp v56, v56, v56 quad_perm:[2,3,0,1] row_mask:0xf bank_mask:0xf bound_ctrl:1
	s_nop 1
	v_add_f32_dpp v56, v56, v56 row_half_mirror row_mask:0xf bank_mask:0xf bound_ctrl:1
	v_cndmask_b32_e64 v43, v43, v56, s[12:13]
	v_mov_b32_e32 v56, v57
	v_pk_mul_f32 v[26:27], v[26:27], v[56:57] op_sel_hi:[1,0]
	v_pk_fma_f32 v[66:67], v[66:67], v[22:23], v[26:27]
	v_pk_mul_f32 v[22:23], v[28:29], v[56:57] op_sel_hi:[1,0]
	v_pk_fma_f32 v[68:69], v[68:69], v[24:25], v[22:23]
	v_pk_mul_f32 v[22:23], v[52:53], v[56:57] op_sel_hi:[1,0]
	v_pk_fma_f32 v[60:61], v[60:61], v[48:49], v[22:23]
	v_pk_mul_f32 v[22:23], v[54:55], v[56:57] op_sel_hi:[1,0]
	v_pk_fma_f32 v[6:7], v[6:7], v[50:51], v[22:23]
	v_pk_mul_f32 v[22:23], v[32:33], v[68:69]
	v_pk_fma_f32 v[22:23], v[30:31], v[66:67], v[22:23]
	v_pk_fma_f32 v[22:23], v[44:45], v[60:61], v[22:23]
	v_pk_fma_f32 v[22:23], v[46:47], v[6:7], v[22:23]
	v_add_f32_e32 v22, v22, v23
	s_nop 1
	v_add_f32_dpp v22, v22, v22 quad_perm:[1,0,3,2] row_mask:0xf bank_mask:0xf bound_ctrl:1
	s_nop 1
	v_add_f32_dpp v22, v22, v22 quad_perm:[2,3,0,1] row_mask:0xf bank_mask:0xf bound_ctrl:1
	s_nop 1
	v_add_f32_dpp v22, v22, v22 row_half_mirror row_mask:0xf bank_mask:0xf bound_ctrl:1
	v_cndmask_b32_e64 v72, v72, v22, s[12:13]
	ds_read_b128 v[22:25], v41 offset:5888
	ds_read_b128 v[26:29], v41 offset:9984
	ds_read2_b32 v[56:57], v73 offset0:192 offset1:224
	ds_read_b128 v[30:33], v41 offset:1792
	ds_read_b128 v[44:47], v41 offset:1808
	ds_read_b128 v[48:51], v41 offset:5904
	ds_read_b128 v[52:55], v41 offset:10000
	s_waitcnt lgkmcnt(4)
	v_pk_mul_f32 v[70:71], v[26:27], v[56:57] op_sel_hi:[1,0]
	v_pk_fma_f32 v[34:35], v[34:35], v[22:23], v[70:71]
	v_pk_mul_f32 v[70:71], v[28:29], v[56:57] op_sel_hi:[1,0]
	v_pk_fma_f32 v[58:59], v[58:59], v[24:25], v[70:71]
	s_waitcnt lgkmcnt(0)
	v_pk_mul_f32 v[70:71], v[52:53], v[56:57] op_sel_hi:[1,0]
	v_pk_fma_f32 v[62:63], v[62:63], v[48:49], v[70:71]
	v_pk_mul_f32 v[70:71], v[54:55], v[56:57] op_sel_hi:[1,0]
	v_pk_fma_f32 v[64:65], v[64:65], v[50:51], v[70:71]
	v_pk_mul_f32 v[70:71], v[32:33], v[58:59]
	v_pk_fma_f32 v[70:71], v[30:31], v[34:35], v[70:71]
	v_pk_fma_f32 v[70:71], v[44:45], v[62:63], v[70:71]
	v_pk_fma_f32 v[70:71], v[46:47], v[64:65], v[70:71]
	v_add_f32_e32 v56, v70, v71
	s_nop 1
	v_add_f32_dpp v56, v56, v56 quad_perm:[1,0,3,2] row_mask:0xf bank_mask:0xf bound_ctrl:1
	s_nop 1
	v_add_f32_dpp v56, v56, v56 quad_perm:[2,3,0,1] row_mask:0xf bank_mask:0xf bound_ctrl:1
	s_nop 1
	v_add_f32_dpp v56, v56, v56 row_half_mirror row_mask:0xf bank_mask:0xf bound_ctrl:1
	v_cndmask_b32_e64 v43, v43, v56, s[14:15]
	v_mov_b32_e32 v56, v57
	v_pk_mul_f32 v[26:27], v[26:27], v[56:57] op_sel_hi:[1,0]
	v_pk_fma_f32 v[66:67], v[66:67], v[22:23], v[26:27]
	v_pk_mul_f32 v[22:23], v[28:29], v[56:57] op_sel_hi:[1,0]
	v_pk_fma_f32 v[68:69], v[68:69], v[24:25], v[22:23]
	v_pk_mul_f32 v[22:23], v[52:53], v[56:57] op_sel_hi:[1,0]
	v_pk_fma_f32 v[60:61], v[60:61], v[48:49], v[22:23]
	v_pk_mul_f32 v[22:23], v[54:55], v[56:57] op_sel_hi:[1,0]
	v_pk_fma_f32 v[6:7], v[6:7], v[50:51], v[22:23]
	v_pk_mul_f32 v[22:23], v[32:33], v[68:69]
	v_pk_fma_f32 v[22:23], v[30:31], v[66:67], v[22:23]
	v_pk_fma_f32 v[22:23], v[44:45], v[60:61], v[22:23]
	v_pk_fma_f32 v[22:23], v[46:47], v[6:7], v[22:23]
	v_add_f32_e32 v22, v22, v23
	s_nop 1
	v_add_f32_dpp v22, v22, v22 quad_perm:[1,0,3,2] row_mask:0xf bank_mask:0xf bound_ctrl:1
	s_nop 1
	v_add_f32_dpp v22, v22, v22 quad_perm:[2,3,0,1] row_mask:0xf bank_mask:0xf bound_ctrl:1
	s_nop 1
	v_add_f32_dpp v22, v22, v22 row_half_mirror row_mask:0xf bank_mask:0xf bound_ctrl:1
	v_cndmask_b32_e64 v76, v72, v22, s[14:15]
	ds_read_b128 v[22:25], v41 offset:6144
	ds_read_b128 v[26:29], v41 offset:10240
	v_add_u32_e32 v72, 0x5800, v42
	ds_read2_b32 v[56:57], v72 offset1:32
	ds_read_b128 v[30:33], v41 offset:2048
	ds_read_b128 v[44:47], v41 offset:2064
	ds_read_b128 v[48:51], v41 offset:6160
	ds_read_b128 v[52:55], v41 offset:10256
	s_waitcnt lgkmcnt(4)
	v_pk_mul_f32 v[70:71], v[26:27], v[56:57] op_sel_hi:[1,0]
	v_pk_fma_f32 v[34:35], v[34:35], v[22:23], v[70:71]
	v_pk_mul_f32 v[70:71], v[28:29], v[56:57] op_sel_hi:[1,0]
	v_pk_fma_f32 v[58:59], v[58:59], v[24:25], v[70:71]
	s_waitcnt lgkmcnt(0)
	v_pk_mul_f32 v[70:71], v[52:53], v[56:57] op_sel_hi:[1,0]
	v_pk_fma_f32 v[62:63], v[62:63], v[48:49], v[70:71]
	v_pk_mul_f32 v[70:71], v[54:55], v[56:57] op_sel_hi:[1,0]
	v_pk_fma_f32 v[64:65], v[64:65], v[50:51], v[70:71]
	v_pk_mul_f32 v[70:71], v[32:33], v[58:59]
	v_pk_fma_f32 v[70:71], v[30:31], v[34:35], v[70:71]
	v_pk_fma_f32 v[70:71], v[44:45], v[62:63], v[70:71]
	v_pk_fma_f32 v[70:71], v[46:47], v[64:65], v[70:71]
	v_add_f32_e32 v56, v70, v71
	s_nop 1
	v_add_f32_dpp v56, v56, v56 quad_perm:[1,0,3,2] row_mask:0xf bank_mask:0xf bound_ctrl:1
	s_nop 1
	v_add_f32_dpp v56, v56, v56 quad_perm:[2,3,0,1] row_mask:0xf bank_mask:0xf bound_ctrl:1
	s_nop 1
	v_add_f32_dpp v56, v56, v56 row_half_mirror row_mask:0xf bank_mask:0xf bound_ctrl:1
	v_cndmask_b32_e64 v73, 0, v56, s[0:1]
	v_mov_b32_e32 v56, v57
	v_pk_mul_f32 v[26:27], v[26:27], v[56:57] op_sel_hi:[1,0]
	v_pk_fma_f32 v[66:67], v[66:67], v[22:23], v[26:27]
	v_pk_mul_f32 v[22:23], v[28:29], v[56:57] op_sel_hi:[1,0]
	v_pk_fma_f32 v[68:69], v[68:69], v[24:25], v[22:23]
	v_pk_mul_f32 v[22:23], v[52:53], v[56:57] op_sel_hi:[1,0]
	v_pk_fma_f32 v[60:61], v[60:61], v[48:49], v[22:23]
	v_pk_mul_f32 v[22:23], v[54:55], v[56:57] op_sel_hi:[1,0]
	v_pk_fma_f32 v[6:7], v[6:7], v[50:51], v[22:23]
	v_pk_mul_f32 v[22:23], v[32:33], v[68:69]
	v_pk_fma_f32 v[22:23], v[30:31], v[66:67], v[22:23]
	v_pk_fma_f32 v[22:23], v[44:45], v[60:61], v[22:23]
	v_pk_fma_f32 v[22:23], v[46:47], v[6:7], v[22:23]
	v_add_f32_e32 v22, v22, v23
	s_nop 1
	v_add_f32_dpp v22, v22, v22 quad_perm:[1,0,3,2] row_mask:0xf bank_mask:0xf bound_ctrl:1
	s_nop 1
	v_add_f32_dpp v22, v22, v22 quad_perm:[2,3,0,1] row_mask:0xf bank_mask:0xf bound_ctrl:1
	s_nop 1
	v_add_f32_dpp v22, v22, v22 row_half_mirror row_mask:0xf bank_mask:0xf bound_ctrl:1
	v_cndmask_b32_e64 v74, 0, v22, s[0:1]
	ds_read_b128 v[22:25], v41 offset:6400
	ds_read_b128 v[26:29], v41 offset:10496
	ds_read2_b32 v[56:57], v72 offset0:64 offset1:96
	ds_read_b128 v[30:33], v41 offset:2304
	ds_read_b128 v[44:47], v41 offset:2320
	ds_read_b128 v[48:51], v41 offset:6416
	ds_read_b128 v[52:55], v41 offset:10512
	s_waitcnt lgkmcnt(4)
	v_pk_mul_f32 v[70:71], v[26:27], v[56:57] op_sel_hi:[1,0]
	v_pk_fma_f32 v[34:35], v[34:35], v[22:23], v[70:71]
	v_pk_mul_f32 v[70:71], v[28:29], v[56:57] op_sel_hi:[1,0]
	v_pk_fma_f32 v[58:59], v[58:59], v[24:25], v[70:71]
	s_waitcnt lgkmcnt(0)
	v_pk_mul_f32 v[70:71], v[52:53], v[56:57] op_sel_hi:[1,0]
	v_pk_fma_f32 v[62:63], v[62:63], v[48:49], v[70:71]
	v_pk_mul_f32 v[70:71], v[54:55], v[56:57] op_sel_hi:[1,0]
	v_pk_fma_f32 v[64:65], v[64:65], v[50:51], v[70:71]
	v_pk_mul_f32 v[70:71], v[32:33], v[58:59]
	v_pk_fma_f32 v[70:71], v[30:31], v[34:35], v[70:71]
	v_pk_fma_f32 v[70:71], v[44:45], v[62:63], v[70:71]
	v_pk_fma_f32 v[70:71], v[46:47], v[64:65], v[70:71]
	v_add_f32_e32 v56, v70, v71
	s_nop 1
	v_add_f32_dpp v56, v56, v56 quad_perm:[1,0,3,2] row_mask:0xf bank_mask:0xf bound_ctrl:1
	s_nop 1
	v_add_f32_dpp v56, v56, v56 quad_perm:[2,3,0,1] row_mask:0xf bank_mask:0xf bound_ctrl:1
	s_nop 1
	v_add_f32_dpp v56, v56, v56 row_half_mirror row_mask:0xf bank_mask:0xf bound_ctrl:1
	v_cndmask_b32_e64 v73, v73, v56, s[16:17]
	v_mov_b32_e32 v56, v57
	v_pk_mul_f32 v[26:27], v[26:27], v[56:57] op_sel_hi:[1,0]
	v_pk_fma_f32 v[66:67], v[66:67], v[22:23], v[26:27]
	v_pk_mul_f32 v[22:23], v[28:29], v[56:57] op_sel_hi:[1,0]
	v_pk_fma_f32 v[68:69], v[68:69], v[24:25], v[22:23]
	v_pk_mul_f32 v[22:23], v[52:53], v[56:57] op_sel_hi:[1,0]
	v_pk_fma_f32 v[60:61], v[60:61], v[48:49], v[22:23]
	v_pk_mul_f32 v[22:23], v[54:55], v[56:57] op_sel_hi:[1,0]
	v_pk_fma_f32 v[6:7], v[6:7], v[50:51], v[22:23]
	v_pk_mul_f32 v[22:23], v[32:33], v[68:69]
	v_pk_fma_f32 v[22:23], v[30:31], v[66:67], v[22:23]
	v_pk_fma_f32 v[22:23], v[44:45], v[60:61], v[22:23]
	v_pk_fma_f32 v[22:23], v[46:47], v[6:7], v[22:23]
	v_add_f32_e32 v22, v22, v23
	s_nop 1
	v_add_f32_dpp v22, v22, v22 quad_perm:[1,0,3,2] row_mask:0xf bank_mask:0xf bound_ctrl:1
	s_nop 1
	v_add_f32_dpp v22, v22, v22 quad_perm:[2,3,0,1] row_mask:0xf bank_mask:0xf bound_ctrl:1
	s_nop 1
	v_add_f32_dpp v22, v22, v22 row_half_mirror row_mask:0xf bank_mask:0xf bound_ctrl:1
	v_cndmask_b32_e64 v74, v74, v22, s[16:17]
	ds_read_b128 v[22:25], v41 offset:6656
	ds_read_b128 v[26:29], v41 offset:10752
	ds_read2_b32 v[56:57], v72 offset0:128 offset1:160
	ds_read_b128 v[30:33], v41 offset:2560
	ds_read_b128 v[44:47], v41 offset:2576
	ds_read_b128 v[48:51], v41 offset:6672
	ds_read_b128 v[52:55], v41 offset:10768
	s_waitcnt lgkmcnt(4)
	v_pk_mul_f32 v[70:71], v[26:27], v[56:57] op_sel_hi:[1,0]
	v_pk_fma_f32 v[34:35], v[34:35], v[22:23], v[70:71]
	v_pk_mul_f32 v[70:71], v[28:29], v[56:57] op_sel_hi:[1,0]
	v_pk_fma_f32 v[58:59], v[58:59], v[24:25], v[70:71]
	s_waitcnt lgkmcnt(0)
	v_pk_mul_f32 v[70:71], v[52:53], v[56:57] op_sel_hi:[1,0]
	v_pk_fma_f32 v[62:63], v[62:63], v[48:49], v[70:71]
	v_pk_mul_f32 v[70:71], v[54:55], v[56:57] op_sel_hi:[1,0]
	v_pk_fma_f32 v[64:65], v[64:65], v[50:51], v[70:71]
	v_pk_mul_f32 v[70:71], v[32:33], v[58:59]
	v_pk_fma_f32 v[70:71], v[30:31], v[34:35], v[70:71]
	v_pk_fma_f32 v[70:71], v[44:45], v[62:63], v[70:71]
	v_pk_fma_f32 v[70:71], v[46:47], v[64:65], v[70:71]
	v_add_f32_e32 v56, v70, v71
	s_nop 1
	v_add_f32_dpp v56, v56, v56 quad_perm:[1,0,3,2] row_mask:0xf bank_mask:0xf bound_ctrl:1
	s_nop 1
	v_add_f32_dpp v56, v56, v56 quad_perm:[2,3,0,1] row_mask:0xf bank_mask:0xf bound_ctrl:1
	s_nop 1
	v_add_f32_dpp v56, v56, v56 row_half_mirror row_mask:0xf bank_mask:0xf bound_ctrl:1
	v_cndmask_b32_e64 v73, v73, v56, s[4:5]
	v_mov_b32_e32 v56, v57
	v_pk_mul_f32 v[26:27], v[26:27], v[56:57] op_sel_hi:[1,0]
	v_pk_fma_f32 v[66:67], v[66:67], v[22:23], v[26:27]
	v_pk_mul_f32 v[22:23], v[28:29], v[56:57] op_sel_hi:[1,0]
	v_pk_fma_f32 v[68:69], v[68:69], v[24:25], v[22:23]
	v_pk_mul_f32 v[22:23], v[52:53], v[56:57] op_sel_hi:[1,0]
	v_pk_fma_f32 v[60:61], v[60:61], v[48:49], v[22:23]
	v_pk_mul_f32 v[22:23], v[54:55], v[56:57] op_sel_hi:[1,0]
	v_pk_fma_f32 v[6:7], v[6:7], v[50:51], v[22:23]
	v_pk_mul_f32 v[22:23], v[32:33], v[68:69]
	v_pk_fma_f32 v[22:23], v[30:31], v[66:67], v[22:23]
	v_pk_fma_f32 v[22:23], v[44:45], v[60:61], v[22:23]
	v_pk_fma_f32 v[22:23], v[46:47], v[6:7], v[22:23]
	v_add_f32_e32 v22, v22, v23
	s_nop 1
	v_add_f32_dpp v22, v22, v22 quad_perm:[1,0,3,2] row_mask:0xf bank_mask:0xf bound_ctrl:1
	s_nop 1
	v_add_f32_dpp v22, v22, v22 quad_perm:[2,3,0,1] row_mask:0xf bank_mask:0xf bound_ctrl:1
	s_nop 1
	v_add_f32_dpp v22, v22, v22 row_half_mirror row_mask:0xf bank_mask:0xf bound_ctrl:1
	v_cndmask_b32_e64 v74, v74, v22, s[4:5]
	ds_read_b128 v[22:25], v41 offset:6912
	ds_read_b128 v[26:29], v41 offset:11008
	ds_read2_b32 v[56:57], v72 offset0:192 offset1:224
	ds_read_b128 v[30:33], v41 offset:2816
	ds_read_b128 v[44:47], v41 offset:2832
	ds_read_b128 v[48:51], v41 offset:6928
	ds_read_b128 v[52:55], v41 offset:11024
	s_waitcnt lgkmcnt(4)
	v_pk_mul_f32 v[70:71], v[26:27], v[56:57] op_sel_hi:[1,0]
	v_pk_fma_f32 v[34:35], v[34:35], v[22:23], v[70:71]
	v_pk_mul_f32 v[70:71], v[28:29], v[56:57] op_sel_hi:[1,0]
	v_pk_fma_f32 v[58:59], v[58:59], v[24:25], v[70:71]
	s_waitcnt lgkmcnt(0)
	v_pk_mul_f32 v[70:71], v[52:53], v[56:57] op_sel_hi:[1,0]
	v_pk_fma_f32 v[62:63], v[62:63], v[48:49], v[70:71]
	v_pk_mul_f32 v[70:71], v[54:55], v[56:57] op_sel_hi:[1,0]
	v_pk_fma_f32 v[64:65], v[64:65], v[50:51], v[70:71]
	v_pk_mul_f32 v[70:71], v[32:33], v[58:59]
	v_pk_fma_f32 v[70:71], v[30:31], v[34:35], v[70:71]
	v_pk_fma_f32 v[70:71], v[44:45], v[62:63], v[70:71]
	v_pk_fma_f32 v[70:71], v[46:47], v[64:65], v[70:71]
	v_add_f32_e32 v56, v70, v71
	s_nop 1
	v_add_f32_dpp v56, v56, v56 quad_perm:[1,0,3,2] row_mask:0xf bank_mask:0xf bound_ctrl:1
	s_nop 1
	v_add_f32_dpp v56, v56, v56 quad_perm:[2,3,0,1] row_mask:0xf bank_mask:0xf bound_ctrl:1
	s_nop 1
	v_add_f32_dpp v56, v56, v56 row_half_mirror row_mask:0xf bank_mask:0xf bound_ctrl:1
	v_cndmask_b32_e64 v72, v73, v56, s[6:7]
	v_mov_b32_e32 v56, v57
	v_pk_mul_f32 v[26:27], v[26:27], v[56:57] op_sel_hi:[1,0]
	v_pk_fma_f32 v[66:67], v[66:67], v[22:23], v[26:27]
	v_pk_mul_f32 v[22:23], v[28:29], v[56:57] op_sel_hi:[1,0]
	v_pk_fma_f32 v[68:69], v[68:69], v[24:25], v[22:23]
	v_pk_mul_f32 v[22:23], v[52:53], v[56:57] op_sel_hi:[1,0]
	v_pk_fma_f32 v[60:61], v[60:61], v[48:49], v[22:23]
	v_pk_mul_f32 v[22:23], v[54:55], v[56:57] op_sel_hi:[1,0]
	v_pk_fma_f32 v[6:7], v[6:7], v[50:51], v[22:23]
	v_pk_mul_f32 v[22:23], v[32:33], v[68:69]
	v_pk_fma_f32 v[22:23], v[30:31], v[66:67], v[22:23]
	v_pk_fma_f32 v[22:23], v[44:45], v[60:61], v[22:23]
	v_pk_fma_f32 v[22:23], v[46:47], v[6:7], v[22:23]
	v_add_f32_e32 v22, v22, v23
	s_nop 1
	v_add_f32_dpp v22, v22, v22 quad_perm:[1,0,3,2] row_mask:0xf bank_mask:0xf bound_ctrl:1
	s_nop 1
	v_add_f32_dpp v22, v22, v22 quad_perm:[2,3,0,1] row_mask:0xf bank_mask:0xf bound_ctrl:1
	s_nop 1
	v_add_f32_dpp v22, v22, v22 row_half_mirror row_mask:0xf bank_mask:0xf bound_ctrl:1
	v_cndmask_b32_e64 v73, v74, v22, s[6:7]
	ds_read_b128 v[22:25], v41 offset:7168
	ds_read_b128 v[26:29], v41 offset:11264
	v_add_u32_e32 v74, 0x5c00, v42
	ds_read2_b32 v[56:57], v74 offset1:32
	ds_read_b128 v[30:33], v41 offset:3072
	ds_read_b128 v[44:47], v41 offset:3088
	ds_read_b128 v[48:51], v41 offset:7184
	ds_read_b128 v[52:55], v41 offset:11280
	s_waitcnt lgkmcnt(4)
	v_pk_mul_f32 v[70:71], v[26:27], v[56:57] op_sel_hi:[1,0]
	v_pk_fma_f32 v[34:35], v[34:35], v[22:23], v[70:71]
	v_pk_mul_f32 v[70:71], v[28:29], v[56:57] op_sel_hi:[1,0]
	v_pk_fma_f32 v[58:59], v[58:59], v[24:25], v[70:71]
	s_waitcnt lgkmcnt(0)
	v_pk_mul_f32 v[70:71], v[52:53], v[56:57] op_sel_hi:[1,0]
	v_pk_fma_f32 v[62:63], v[62:63], v[48:49], v[70:71]
	v_pk_mul_f32 v[70:71], v[54:55], v[56:57] op_sel_hi:[1,0]
	v_pk_fma_f32 v[64:65], v[64:65], v[50:51], v[70:71]
	v_pk_mul_f32 v[70:71], v[32:33], v[58:59]
	v_pk_fma_f32 v[70:71], v[30:31], v[34:35], v[70:71]
	v_pk_fma_f32 v[70:71], v[44:45], v[62:63], v[70:71]
	v_pk_fma_f32 v[70:71], v[46:47], v[64:65], v[70:71]
	v_add_f32_e32 v42, v70, v71
	s_nop 1
	v_add_f32_dpp v42, v42, v42 quad_perm:[1,0,3,2] row_mask:0xf bank_mask:0xf bound_ctrl:1
	s_nop 1
	v_add_f32_dpp v42, v42, v42 quad_perm:[2,3,0,1] row_mask:0xf bank_mask:0xf bound_ctrl:1
	s_nop 1
	v_add_f32_dpp v42, v42, v42 row_half_mirror row_mask:0xf bank_mask:0xf bound_ctrl:1
	v_cndmask_b32_e64 v72, v72, v42, s[8:9]
	v_mov_b32_e32 v42, v57
	v_pk_mul_f32 v[26:27], v[26:27], v[42:43] op_sel_hi:[1,0]
	v_pk_fma_f32 v[56:57], v[66:67], v[22:23], v[26:27]
	v_pk_mul_f32 v[22:23], v[28:29], v[42:43] op_sel_hi:[1,0]
	v_pk_fma_f32 v[66:67], v[68:69], v[24:25], v[22:23]
	v_pk_mul_f32 v[22:23], v[52:53], v[42:43] op_sel_hi:[1,0]
	v_pk_fma_f32 v[60:61], v[60:61], v[48:49], v[22:23]
	v_pk_mul_f32 v[22:23], v[54:55], v[42:43] op_sel_hi:[1,0]
	v_pk_fma_f32 v[6:7], v[6:7], v[50:51], v[22:23]
	v_pk_mul_f32 v[22:23], v[32:33], v[66:67]
	v_pk_fma_f32 v[22:23], v[30:31], v[56:57], v[22:23]
	v_pk_fma_f32 v[22:23], v[44:45], v[60:61], v[22:23]
	v_pk_fma_f32 v[22:23], v[46:47], v[6:7], v[22:23]
	v_add_f32_e32 v22, v22, v23
	s_nop 1
	v_add_f32_dpp v22, v22, v22 quad_perm:[1,0,3,2] row_mask:0xf bank_mask:0xf bound_ctrl:1
	s_nop 1
	v_add_f32_dpp v22, v22, v22 quad_perm:[2,3,0,1] row_mask:0xf bank_mask:0xf bound_ctrl:1
	s_nop 1
	v_add_f32_dpp v22, v22, v22 row_half_mirror row_mask:0xf bank_mask:0xf bound_ctrl:1
	v_cndmask_b32_e64 v73, v73, v22, s[8:9]
	ds_read_b128 v[22:25], v41 offset:7424
	ds_read_b128 v[26:29], v41 offset:11520
	ds_read2_b32 v[68:69], v74 offset0:64 offset1:96
	ds_read_b128 v[30:33], v41 offset:3328
	ds_read_b128 v[44:47], v41 offset:3344
	ds_read_b128 v[48:51], v41 offset:7440
	ds_read_b128 v[52:55], v41 offset:11536
	s_waitcnt lgkmcnt(4)
	v_pk_mul_f32 v[70:71], v[26:27], v[68:69] op_sel_hi:[1,0]
	v_pk_fma_f32 v[34:35], v[34:35], v[22:23], v[70:71]
	v_pk_mul_f32 v[70:71], v[28:29], v[68:69] op_sel_hi:[1,0]
	v_pk_fma_f32 v[58:59], v[58:59], v[24:25], v[70:71]
	s_waitcnt lgkmcnt(0)
	v_pk_mul_f32 v[70:71], v[52:53], v[68:69] op_sel_hi:[1,0]
	v_pk_fma_f32 v[62:63], v[62:63], v[48:49], v[70:71]
	v_pk_mul_f32 v[70:71], v[54:55], v[68:69] op_sel_hi:[1,0]
	v_pk_fma_f32 v[64:65], v[64:65], v[50:51], v[70:71]
	v_pk_mul_f32 v[70:71], v[32:33], v[58:59]
	v_pk_fma_f32 v[70:71], v[30:31], v[34:35], v[70:71]
	v_pk_fma_f32 v[70:71], v[44:45], v[62:63], v[70:71]
	v_pk_fma_f32 v[70:71], v[46:47], v[64:65], v[70:71]
	v_add_f32_e32 v42, v70, v71
	s_nop 1
	v_add_f32_dpp v42, v42, v42 quad_perm:[1,0,3,2] row_mask:0xf bank_mask:0xf bound_ctrl:1
	s_nop 1
	v_add_f32_dpp v42, v42, v42 quad_perm:[2,3,0,1] row_mask:0xf bank_mask:0xf bound_ctrl:1
	s_nop 1
	v_add_f32_dpp v42, v42, v42 row_half_mirror row_mask:0xf bank_mask:0xf bound_ctrl:1
	v_cndmask_b32_e64 v75, v72, v42, s[10:11]
	v_mov_b32_e32 v42, v69
	v_pk_mul_f32 v[26:27], v[26:27], v[42:43] op_sel_hi:[1,0]
	v_pk_fma_f32 v[56:57], v[56:57], v[22:23], v[26:27]
	v_pk_mul_f32 v[22:23], v[28:29], v[42:43] op_sel_hi:[1,0]
	v_pk_fma_f32 v[66:67], v[66:67], v[24:25], v[22:23]
	v_pk_mul_f32 v[22:23], v[52:53], v[42:43] op_sel_hi:[1,0]
	v_pk_fma_f32 v[60:61], v[60:61], v[48:49], v[22:23]
	v_pk_mul_f32 v[22:23], v[54:55], v[42:43] op_sel_hi:[1,0]
	v_pk_fma_f32 v[6:7], v[6:7], v[50:51], v[22:23]
	v_pk_mul_f32 v[22:23], v[32:33], v[66:67]
	v_pk_fma_f32 v[22:23], v[30:31], v[56:57], v[22:23]
	v_pk_fma_f32 v[22:23], v[44:45], v[60:61], v[22:23]
	v_pk_fma_f32 v[22:23], v[46:47], v[6:7], v[22:23]
	v_add_f32_e32 v22, v22, v23
	s_nop 1
	v_add_f32_dpp v22, v22, v22 quad_perm:[1,0,3,2] row_mask:0xf bank_mask:0xf bound_ctrl:1
	s_nop 1
	v_add_f32_dpp v22, v22, v22 quad_perm:[2,3,0,1] row_mask:0xf bank_mask:0xf bound_ctrl:1
	s_nop 1
	v_add_f32_dpp v22, v22, v22 row_half_mirror row_mask:0xf bank_mask:0xf bound_ctrl:1
	v_cndmask_b32_e64 v77, v73, v22, s[10:11]
	ds_read_b128 v[22:25], v41 offset:7680
	ds_read_b128 v[26:29], v41 offset:11776
	ds_read2_b32 v[68:69], v74 offset0:128 offset1:160
	ds_read_b128 v[30:33], v41 offset:3584
	ds_read_b128 v[44:47], v41 offset:3600
	ds_read_b128 v[48:51], v41 offset:7696
	ds_read_b128 v[52:55], v41 offset:11792
	s_waitcnt lgkmcnt(4)
	v_pk_mul_f32 v[70:71], v[26:27], v[68:69] op_sel_hi:[1,0]
	v_pk_fma_f32 v[34:35], v[34:35], v[22:23], v[70:71]
	v_pk_mul_f32 v[70:71], v[28:29], v[68:69] op_sel_hi:[1,0]
	v_pk_fma_f32 v[70:71], v[58:59], v[24:25], v[70:71]
	s_waitcnt lgkmcnt(0)
	v_pk_mul_f32 v[58:59], v[52:53], v[68:69] op_sel_hi:[1,0]
	v_pk_fma_f32 v[72:73], v[62:63], v[48:49], v[58:59]
	v_pk_mul_f32 v[58:59], v[54:55], v[68:69] op_sel_hi:[1,0]
	v_pk_fma_f32 v[64:65], v[64:65], v[50:51], v[58:59]
	v_pk_mul_f32 v[58:59], v[32:33], v[70:71]
	v_pk_fma_f32 v[58:59], v[30:31], v[34:35], v[58:59]
	v_pk_fma_f32 v[58:59], v[44:45], v[72:73], v[58:59]
	v_pk_fma_f32 v[58:59], v[46:47], v[64:65], v[58:59]
	v_add_f32_e32 v42, v58, v59
	s_nop 1
	v_add_f32_dpp v42, v42, v42 quad_perm:[1,0,3,2] row_mask:0xf bank_mask:0xf bound_ctrl:1
	s_nop 1
	v_add_f32_dpp v42, v42, v42 quad_perm:[2,3,0,1] row_mask:0xf bank_mask:0xf bound_ctrl:1
	s_nop 1
	v_add_f32_dpp v42, v42, v42 row_half_mirror row_mask:0xf bank_mask:0xf bound_ctrl:1
	v_cndmask_b32_e64 v78, v75, v42, s[12:13]
	v_mov_b32_e32 v42, v69
	v_pk_mul_f32 v[26:27], v[26:27], v[42:43] op_sel_hi:[1,0]
	v_pk_fma_f32 v[26:27], v[56:57], v[22:23], v[26:27]
	v_pk_mul_f32 v[22:23], v[28:29], v[42:43] op_sel_hi:[1,0]
	v_pk_fma_f32 v[66:67], v[66:67], v[24:25], v[22:23]
	v_pk_mul_f32 v[22:23], v[52:53], v[42:43] op_sel_hi:[1,0]
	v_pk_fma_f32 v[68:69], v[60:61], v[48:49], v[22:23]
	v_pk_mul_f32 v[22:23], v[54:55], v[42:43] op_sel_hi:[1,0]
	v_pk_fma_f32 v[6:7], v[6:7], v[50:51], v[22:23]
	v_pk_mul_f32 v[22:23], v[32:33], v[66:67]
	v_pk_fma_f32 v[22:23], v[30:31], v[26:27], v[22:23]
	v_pk_fma_f32 v[22:23], v[44:45], v[68:69], v[22:23]
	v_pk_fma_f32 v[22:23], v[46:47], v[6:7], v[22:23]
	v_add_f32_e32 v22, v22, v23
	s_nop 1
	v_add_f32_dpp v22, v22, v22 quad_perm:[1,0,3,2] row_mask:0xf bank_mask:0xf bound_ctrl:1
	s_nop 1
	v_add_f32_dpp v22, v22, v22 quad_perm:[2,3,0,1] row_mask:0xf bank_mask:0xf bound_ctrl:1
	s_nop 1
	v_add_f32_dpp v22, v22, v22 row_half_mirror row_mask:0xf bank_mask:0xf bound_ctrl:1
	v_cndmask_b32_e64 v77, v77, v22, s[12:13]
	ds_read_b128 v[22:25], v41 offset:7936
	ds_read_b128 v[44:47], v41 offset:12032
	ds_read2_b32 v[74:75], v74 offset0:192 offset1:224
	ds_read_b128 v[48:51], v41 offset:3840
	ds_read_b128 v[52:55], v41 offset:3856
	ds_read_b128 v[56:59], v41 offset:7952
	ds_read_b128 v[60:63], v41 offset:12048
	s_waitcnt lgkmcnt(4)
	v_mov_b32_e32 v42, v75
	v_pk_mul_f32 v[28:29], v[44:45], v[74:75] op_sel_hi:[1,0]
	v_pk_mul_f32 v[44:45], v[44:45], v[42:43] op_sel_hi:[1,0]
	v_pk_fma_f32 v[34:35], v[34:35], v[22:23], v[28:29]
	v_pk_mul_f32 v[28:29], v[46:47], v[74:75] op_sel_hi:[1,0]
	v_pk_fma_f32 v[26:27], v[26:27], v[22:23], v[44:45]
	v_pk_mul_f32 v[22:23], v[46:47], v[42:43] op_sel_hi:[1,0]
	v_pk_fma_f32 v[32:33], v[70:71], v[24:25], v[28:29]
	v_pk_fma_f32 v[24:25], v[66:67], v[24:25], v[22:23]
	s_waitcnt lgkmcnt(0)
	v_pk_mul_f32 v[44:45], v[62:63], v[42:43] op_sel_hi:[1,0]
	v_pk_mul_f32 v[22:23], v[60:61], v[42:43] op_sel_hi:[1,0]
	v_pk_fma_f32 v[6:7], v[6:7], v[58:59], v[44:45]
	v_pk_mul_f32 v[44:45], v[50:51], v[24:25]
	v_pk_fma_f32 v[22:23], v[68:69], v[56:57], v[22:23]
	v_pk_fma_f32 v[44:45], v[48:49], v[26:27], v[44:45]
	v_pk_mul_f32 v[28:29], v[60:61], v[74:75] op_sel_hi:[1,0]
	v_pk_fma_f32 v[44:45], v[52:53], v[22:23], v[44:45]
	v_pk_fma_f32 v[30:31], v[72:73], v[56:57], v[28:29]
	v_pk_mul_f32 v[28:29], v[62:63], v[74:75] op_sel_hi:[1,0]
	v_pk_fma_f32 v[44:45], v[54:55], v[6:7], v[44:45]
	v_pk_fma_f32 v[28:29], v[64:65], v[58:59], v[28:29]
	v_pk_mul_f32 v[64:65], v[50:51], v[32:33]
	v_add_f32_e32 v42, v44, v45
	v_pk_fma_f32 v[64:65], v[48:49], v[34:35], v[64:65]
	v_add_u32_e32 v44, 8, v37
	v_add_f32_dpp v42, v42, v42 quad_perm:[1,0,3,2] row_mask:0xf bank_mask:0xf bound_ctrl:1
	v_pk_fma_f32 v[64:65], v[52:53], v[30:31], v[64:65]
	s_nop 0
	v_add_f32_dpp v42, v42, v42 quad_perm:[2,3,0,1] row_mask:0xf bank_mask:0xf bound_ctrl:1
	v_pk_fma_f32 v[64:65], v[54:55], v[28:29], v[64:65]
	s_nop 0
	v_add_f32_dpp v42, v42, v42 row_half_mirror row_mask:0xf bank_mask:0xf bound_ctrl:1
	v_add_f32_e32 v41, v64, v65
	v_cndmask_b32_e64 v46, v77, v42, s[14:15]
	v_add_u32_e32 v42, s25, v11
	v_add_f32_dpp v41, v41, v41 quad_perm:[1,0,3,2] row_mask:0xf bank_mask:0xf bound_ctrl:1
	v_cndmask_b32_e64 v44, v44, v42, s[36:37]
	v_add_u32_e32 v42, 8, v42
	v_add_f32_dpp v41, v41, v41 quad_perm:[2,3,0,1] row_mask:0xf bank_mask:0xf bound_ctrl:1
	v_add_lshl_u32 v128, v44, s24, 10
	v_cndmask_b32_e64 v42, v37, v42, s[36:37]
	v_add_f32_dpp v41, v41, v41 row_half_mirror row_mask:0xf bank_mask:0xf bound_ctrl:1
	v_lshl_add_u64 v[44:45], v[4:5], 0, v[128:129]
	v_add_lshl_u32 v128, v42, s24, 10
	v_cndmask_b32_e64 v41, v78, v41, s[14:15]
	global_store_dword v[44:45], v43, off
	global_store_dword v[44:45], v76, off offset:128
	v_lshl_add_u64 v[42:43], v[4:5], 0, v[128:129]
	global_store_dword v[42:43], v41, off
	global_store_dword v[42:43], v46, off offset:128
	s_cbranch_vccnz .LBB0_414
	s_waitcnt vmcnt(5)
	v_lshlrev_b32_e32 v41, 16, v16
	v_mul_f32_e32 v41, 0xbfb8aa3b, v41
	v_exp_f32_e32 v41, v41
	v_lshlrev_b32_e32 v42, 16, v14
	v_and_b32_e32 v43, 0xffff0000, v14
	v_mul_f32_e32 v50, 0xbfb8aa3b, v42
	v_add_f32_e32 v41, 1.0, v41
	v_rcp_f32_e32 v46, v41
	v_and_b32_e32 v41, 0xffff0000, v16
	v_mul_f32_e32 v41, 0xbfb8aa3b, v41
	v_exp_f32_e32 v41, v41
	v_mul_f32_e32 v51, 0xbfb8aa3b, v43
	v_exp_f32_e32 v50, v50
	v_exp_f32_e32 v51, v51
	v_add_f32_e32 v41, 1.0, v41
	v_rcp_f32_e32 v47, v41
	v_lshlrev_b32_e32 v41, 16, v17
	v_mul_f32_e32 v41, 0xbfb8aa3b, v41
	v_exp_f32_e32 v41, v41
	v_add_f32_e32 v50, 1.0, v50
	v_add_f32_e32 v51, 1.0, v51
	v_rcp_f32_e32 v50, v50
	v_rcp_f32_e32 v51, v51
	v_lshlrev_b32_e32 v44, 16, v15
	v_and_b32_e32 v45, 0xffff0000, v15
	v_add_f32_e32 v41, 1.0, v41
	v_rcp_f32_e32 v48, v41
	v_and_b32_e32 v41, 0xffff0000, v17
	v_pk_mul_f32 v[42:43], v[50:51], v[42:43]
	v_mul_f32_e32 v50, 0xbfb8aa3b, v44
	v_mul_f32_e32 v51, 0xbfb8aa3b, v45
	v_mul_f32_e32 v41, 0xbfb8aa3b, v41
	v_exp_f32_e32 v50, v50
	v_exp_f32_e32 v51, v51
	v_exp_f32_e32 v41, v41
	s_bitcmp1_b32 s19, 0
	v_add_f32_e32 v50, 1.0, v50
	v_add_f32_e32 v51, 1.0, v51
	v_add_f32_e32 v41, 1.0, v41
	v_rcp_f32_e32 v50, v50
	v_rcp_f32_e32 v51, v51
	v_rcp_f32_e32 v49, v41
	s_cselect_b32 s20, 0x6000, 0
	s_add_i32 s20, s78, s20
	v_lshl_add_u32 v41, v36, 4, s20
	v_pk_mul_f32 v[44:45], v[50:51], v[44:45]
	ds_write_b128 v41, v[42:45]
	v_pk_fma_f32 v[42:43], v[12:13], v[46:47], v[0:1]
	v_pk_fma_f32 v[44:45], v[18:19], v[48:49], v[2:3]
	ds_write_b128 v41, v[42:45] offset:4096
	v_pk_add_f32 v[42:43], v[46:47], 1.0 op_sel_hi:[1,0] neg_lo:[1,0] neg_hi:[1,0]
	v_pk_add_f32 v[44:45], v[48:49], 1.0 op_sel_hi:[1,0] neg_lo:[1,0] neg_hi:[1,0]
	v_pk_mul_f32 v[42:43], v[12:13], v[42:43]
	v_pk_mul_f32 v[44:45], v[18:19], v[44:45]
	ds_write_b128 v41, v[42:45] offset:8192
	v_lshlrev_b32_e32 v41, 2, v10
	s_waitcnt vmcnt(4)
	v_lshlrev_b32_e32 v42, 16, v20
	v_and_b32_e32 v43, 0xffff0000, v20
	v_lshlrev_b32_e32 v44, 16, v21
	v_and_b32_e32 v45, 0xffff0000, v21
	v_add3_u32 v41, s20, v40, v41
	ds_write_b128 v41, v[42:45] offset:20480
	s_branch .LBB0_414

.LBB0_425:
	s_add_i32 s25, s26, 1
	s_bitcmp1_b32 s26, 0
	s_cselect_b32 s26, 0x6000, 0
	s_add_i32 s26, s78, s26
	v_add_u32_e32 v51, s26, v44
	ds_read_b128 v[54:57], v51
	ds_read_b128 v[58:61], v51 offset:16
	ds_read_b128 v[62:65], v51 offset:4096
	ds_read_b128 v[66:69], v51 offset:4112
	ds_read_b128 v[70:73], v51 offset:8192
	ds_read_b128 v[74:77], v51 offset:8208
	ds_read_b128 v[78:81], v51 offset:12288
	ds_read_b128 v[82:85], v51 offset:12304
	ds_read_b128 v[86:89], v51 offset:16384
	ds_read_b128 v[90:93], v51 offset:16400
	v_lshl_add_u32 v52, v16, 2, s26
	s_waitcnt lgkmcnt(3)
	v_pk_mul_f32 v[96:97], v[14:15], v[80:81]
	v_add_u32_e32 v53, 0x5000, v52
	v_pk_fma_f32 v[96:97], v[12:13], v[78:79], v[96:97]
	ds_read2_b32 v[94:95], v53 offset1:32
	s_waitcnt lgkmcnt(3)
	v_pk_fma_f32 v[96:97], v[8:9], v[82:83], v[96:97]
	s_andn2_b64 vcc, exec, s[18:19]
	v_pk_fma_f32 v[96:97], v[10:11], v[84:85], v[96:97]
	v_add_f32_e32 v96, v96, v97
	s_nop 1
	v_add_f32_dpp v96, v96, v96 quad_perm:[1,0,3,2] row_mask:0xf bank_mask:0xf bound_ctrl:1
	s_nop 1
	v_add_f32_dpp v96, v96, v96 quad_perm:[2,3,0,1] row_mask:0xf bank_mask:0xf bound_ctrl:1
	s_nop 1
	v_add_f32_dpp v96, v96, v96 row_half_mirror row_mask:0xf bank_mask:0xf bound_ctrl:1
	s_waitcnt lgkmcnt(2)
	v_pk_mul_f32 v[98:99], v[86:87], v[96:97] op_sel_hi:[1,0] neg_lo:[0,1] neg_hi:[0,1]
	v_pk_fma_f32 v[12:13], v[12:13], v[62:63], v[98:99]
	s_waitcnt lgkmcnt(0)
	v_pk_fma_f32 v[98:99], v[70:71], v[94:95], v[12:13] op_sel_hi:[1,0,1]
	v_pk_mul_f32 v[12:13], v[88:89], v[96:97] op_sel_hi:[1,0] neg_lo:[0,1] neg_hi:[0,1]
	v_pk_fma_f32 v[12:13], v[14:15], v[64:65], v[12:13]
	v_pk_fma_f32 v[100:101], v[72:73], v[94:95], v[12:13] op_sel_hi:[1,0,1]
	v_pk_mul_f32 v[12:13], v[90:91], v[96:97] op_sel_hi:[1,0] neg_lo:[0,1] neg_hi:[0,1]
	v_pk_fma_f32 v[8:9], v[8:9], v[66:67], v[12:13]
	v_pk_fma_f32 v[102:103], v[74:75], v[94:95], v[8:9] op_sel_hi:[1,0,1]
	v_pk_mul_f32 v[8:9], v[92:93], v[96:97] op_sel_hi:[1,0] neg_lo:[0,1] neg_hi:[0,1]
	v_pk_fma_f32 v[8:9], v[10:11], v[68:69], v[8:9]
	v_mov_b32_e32 v10, v95
	v_pk_fma_f32 v[96:97], v[76:77], v[94:95], v[8:9] op_sel_hi:[1,0,1]
	v_pk_mul_f32 v[8:9], v[56:57], v[100:101]
	v_pk_fma_f32 v[8:9], v[54:55], v[98:99], v[8:9]
	v_pk_fma_f32 v[8:9], v[58:59], v[102:103], v[8:9]
	v_pk_fma_f32 v[8:9], v[60:61], v[96:97], v[8:9]
	v_add_f32_e32 v8, v8, v9
	s_nop 1
	v_add_f32_dpp v8, v8, v8 quad_perm:[1,0,3,2] row_mask:0xf bank_mask:0xf bound_ctrl:1
	s_nop 1
	v_add_f32_dpp v8, v8, v8 quad_perm:[2,3,0,1] row_mask:0xf bank_mask:0xf bound_ctrl:1
	s_nop 1
	v_add_f32_dpp v8, v8, v8 row_half_mirror row_mask:0xf bank_mask:0xf bound_ctrl:1
	v_cndmask_b32_e64 v104, 0, v8, s[0:1]
	v_pk_mul_f32 v[8:9], v[6:7], v[80:81]
	v_pk_fma_f32 v[8:9], v[4:5], v[78:79], v[8:9]
	v_pk_fma_f32 v[8:9], v[0:1], v[82:83], v[8:9]
	v_pk_fma_f32 v[8:9], v[2:3], v[84:85], v[8:9]
	v_add_f32_e32 v8, v8, v9
	s_nop 1
	v_add_f32_dpp v8, v8, v8 quad_perm:[1,0,3,2] row_mask:0xf bank_mask:0xf bound_ctrl:1
	s_nop 1
	v_add_f32_dpp v8, v8, v8 quad_perm:[2,3,0,1] row_mask:0xf bank_mask:0xf bound_ctrl:1
	s_nop 1
	v_add_f32_dpp v8, v8, v8 row_half_mirror row_mask:0xf bank_mask:0xf bound_ctrl:1
	v_pk_mul_f32 v[12:13], v[86:87], v[8:9] op_sel_hi:[1,0] neg_lo:[0,1] neg_hi:[0,1]
	v_pk_fma_f32 v[4:5], v[4:5], v[62:63], v[12:13]
	v_pk_fma_f32 v[78:79], v[70:71], v[10:11], v[4:5] op_sel_hi:[1,0,1]
	v_pk_mul_f32 v[4:5], v[88:89], v[8:9] op_sel_hi:[1,0] neg_lo:[0,1] neg_hi:[0,1]
	v_pk_fma_f32 v[4:5], v[6:7], v[64:65], v[4:5]
	v_pk_fma_f32 v[80:81], v[72:73], v[10:11], v[4:5] op_sel_hi:[1,0,1]
	v_pk_mul_f32 v[4:5], v[90:91], v[8:9] op_sel_hi:[1,0] neg_lo:[0,1] neg_hi:[0,1]
	v_pk_fma_f32 v[0:1], v[0:1], v[66:67], v[4:5]
	v_pk_fma_f32 v[82:83], v[74:75], v[10:11], v[0:1] op_sel_hi:[1,0,1]
	v_pk_mul_f32 v[0:1], v[92:93], v[8:9] op_sel_hi:[1,0] neg_lo:[0,1] neg_hi:[0,1]
	v_pk_fma_f32 v[0:1], v[2:3], v[68:69], v[0:1]
	v_pk_fma_f32 v[84:85], v[76:77], v[10:11], v[0:1] op_sel_hi:[1,0,1]
	v_pk_mul_f32 v[0:1], v[56:57], v[80:81]
	v_pk_fma_f32 v[0:1], v[54:55], v[78:79], v[0:1]
	v_pk_fma_f32 v[0:1], v[58:59], v[82:83], v[0:1]
	v_pk_fma_f32 v[0:1], v[60:61], v[84:85], v[0:1]
	v_add_f32_e32 v0, v0, v1
	s_nop 1
	v_add_f32_dpp v0, v0, v0 quad_perm:[1,0,3,2] row_mask:0xf bank_mask:0xf bound_ctrl:1
	s_nop 1
	v_add_f32_dpp v0, v0, v0 quad_perm:[2,3,0,1] row_mask:0xf bank_mask:0xf bound_ctrl:1
	s_nop 1
	v_add_f32_dpp v0, v0, v0 row_half_mirror row_mask:0xf bank_mask:0xf bound_ctrl:1
	v_cndmask_b32_e64 v105, 0, v0, s[0:1]
	ds_read_b128 v[0:3], v51 offset:256
	ds_read_b128 v[4:7], v51 offset:272
	ds_read_b128 v[8:11], v51 offset:4352
	ds_read_b128 v[12:15], v51 offset:4368
	ds_read_b128 v[54:57], v51 offset:8448
	ds_read_b128 v[58:61], v51 offset:8464
	ds_read_b128 v[62:65], v51 offset:12544
	ds_read_b128 v[66:69], v51 offset:12560
	ds_read_b128 v[70:73], v51 offset:16640
	ds_read_b128 v[74:77], v51 offset:16656
	ds_read2_b32 v[86:87], v53 offset0:64 offset1:96
	s_waitcnt lgkmcnt(4)
	v_pk_mul_f32 v[88:89], v[100:101], v[64:65]
	v_pk_mul_f32 v[64:65], v[80:81], v[64:65]
	v_pk_fma_f32 v[88:89], v[98:99], v[62:63], v[88:89]
	v_pk_fma_f32 v[62:63], v[78:79], v[62:63], v[64:65]
	s_waitcnt lgkmcnt(3)
	v_pk_fma_f32 v[88:89], v[102:103], v[66:67], v[88:89]
	v_pk_fma_f32 v[62:63], v[82:83], v[66:67], v[62:63]
	v_pk_fma_f32 v[88:89], v[96:97], v[68:69], v[88:89]
	v_pk_fma_f32 v[62:63], v[84:85], v[68:69], v[62:63]
	v_add_f32_e32 v88, v88, v89
	v_add_f32_e32 v62, v62, v63
	s_waitcnt lgkmcnt(0)
	v_mov_b32_e32 v64, v87
	v_add_f32_dpp v88, v88, v88 quad_perm:[1,0,3,2] row_mask:0xf bank_mask:0xf bound_ctrl:1
	v_add_f32_dpp v62, v62, v62 quad_perm:[1,0,3,2] row_mask:0xf bank_mask:0xf bound_ctrl:1
	s_nop 0
	v_add_f32_dpp v88, v88, v88 quad_perm:[2,3,0,1] row_mask:0xf bank_mask:0xf bound_ctrl:1
	v_add_f32_dpp v62, v62, v62 quad_perm:[2,3,0,1] row_mask:0xf bank_mask:0xf bound_ctrl:1
	s_nop 0
	v_add_f32_dpp v88, v88, v88 row_half_mirror row_mask:0xf bank_mask:0xf bound_ctrl:1
	v_add_f32_dpp v62, v62, v62 row_half_mirror row_mask:0xf bank_mask:0xf bound_ctrl:1
	v_pk_mul_f32 v[90:91], v[70:71], v[88:89] op_sel_hi:[1,0] neg_lo:[0,1] neg_hi:[0,1]
	v_pk_mul_f32 v[66:67], v[70:71], v[62:63] op_sel_hi:[1,0] neg_lo:[0,1] neg_hi:[0,1]
	v_pk_fma_f32 v[90:91], v[98:99], v[8:9], v[90:91]
	v_pk_fma_f32 v[8:9], v[78:79], v[8:9], v[66:67]
	v_pk_mul_f32 v[92:93], v[72:73], v[88:89] op_sel_hi:[1,0] neg_lo:[0,1] neg_hi:[0,1]
	v_pk_fma_f32 v[78:79], v[54:55], v[64:65], v[8:9] op_sel_hi:[1,0,1]
	v_pk_mul_f32 v[8:9], v[72:73], v[62:63] op_sel_hi:[1,0] neg_lo:[0,1] neg_hi:[0,1]
	v_pk_fma_f32 v[92:93], v[100:101], v[10:11], v[92:93]
	v_pk_fma_f32 v[8:9], v[80:81], v[10:11], v[8:9]
	v_pk_fma_f32 v[92:93], v[56:57], v[86:87], v[92:93] op_sel_hi:[1,0,1]
	v_pk_fma_f32 v[80:81], v[56:57], v[64:65], v[8:9] op_sel_hi:[1,0,1]
	v_pk_mul_f32 v[8:9], v[74:75], v[62:63] op_sel_hi:[1,0] neg_lo:[0,1] neg_hi:[0,1]
	v_pk_mul_f32 v[94:95], v[74:75], v[88:89] op_sel_hi:[1,0] neg_lo:[0,1] neg_hi:[0,1]
	v_pk_mul_f32 v[88:89], v[76:77], v[88:89] op_sel_hi:[1,0] neg_lo:[0,1] neg_hi:[0,1]
	v_pk_fma_f32 v[8:9], v[82:83], v[12:13], v[8:9]
	v_pk_fma_f32 v[90:91], v[54:55], v[86:87], v[90:91] op_sel_hi:[1,0,1]
	v_pk_fma_f32 v[94:95], v[102:103], v[12:13], v[94:95]
	v_pk_fma_f32 v[88:89], v[96:97], v[14:15], v[88:89]
	v_pk_mul_f32 v[96:97], v[2:3], v[92:93]
	v_pk_fma_f32 v[82:83], v[58:59], v[64:65], v[8:9] op_sel_hi:[1,0,1]
	v_pk_mul_f32 v[8:9], v[76:77], v[62:63] op_sel_hi:[1,0] neg_lo:[0,1] neg_hi:[0,1]
	v_pk_mul_f32 v[2:3], v[2:3], v[80:81]
	v_pk_fma_f32 v[94:95], v[58:59], v[86:87], v[94:95] op_sel_hi:[1,0,1]
	v_pk_fma_f32 v[96:97], v[0:1], v[90:91], v[96:97]
	v_pk_fma_f32 v[8:9], v[84:85], v[14:15], v[8:9]
	v_pk_fma_f32 v[0:1], v[0:1], v[78:79], v[2:3]
	v_pk_fma_f32 v[88:89], v[60:61], v[86:87], v[88:89] op_sel_hi:[1,0,1]
	v_pk_fma_f32 v[96:97], v[4:5], v[94:95], v[96:97]
	v_pk_fma_f32 v[84:85], v[60:61], v[64:65], v[8:9] op_sel_hi:[1,0,1]
	v_pk_fma_f32 v[0:1], v[4:5], v[82:83], v[0:1]
	v_pk_fma_f32 v[96:97], v[6:7], v[88:89], v[96:97]
	v_pk_fma_f32 v[0:1], v[6:7], v[84:85], v[0:1]
	v_add_f32_e32 v86, v96, v97
	v_add_f32_e32 v0, v0, v1
	s_nop 0
	v_add_f32_dpp v86, v86, v86 quad_perm:[1,0,3,2] row_mask:0xf bank_mask:0xf bound_ctrl:1
	v_add_f32_dpp v0, v0, v0 quad_perm:[1,0,3,2] row_mask:0xf bank_mask:0xf bound_ctrl:1
	s_nop 0
	v_add_f32_dpp v86, v86, v86 quad_perm:[2,3,0,1] row_mask:0xf bank_mask:0xf bound_ctrl:1
	v_add_f32_dpp v0, v0, v0 quad_perm:[2,3,0,1] row_mask:0xf bank_mask:0xf bound_ctrl:1
	s_nop 0
	v_add_f32_dpp v86, v86, v86 row_half_mirror row_mask:0xf bank_mask:0xf bound_ctrl:1
	v_add_f32_dpp v0, v0, v0 row_half_mirror row_mask:0xf bank_mask:0xf bound_ctrl:1
	v_cndmask_b32_e64 v100, v104, v86, s[16:17]
	v_cndmask_b32_e64 v101, v105, v0, s[16:17]
	ds_read_b128 v[0:3], v51 offset:512
	ds_read_b128 v[4:7], v51 offset:528
	ds_read_b128 v[8:11], v51 offset:4608
	ds_read_b128 v[12:15], v51 offset:4624
	ds_read_b128 v[54:57], v51 offset:8704
	ds_read_b128 v[58:61], v51 offset:8720
	ds_read_b128 v[62:65], v51 offset:12800
	ds_read_b128 v[66:69], v51 offset:12816
	ds_read_b128 v[70:73], v51 offset:16896
	ds_read_b128 v[74:77], v51 offset:16912
	ds_read2_b32 v[86:87], v53 offset0:128 offset1:160
	s_waitcnt lgkmcnt(4)
	v_pk_mul_f32 v[96:97], v[92:93], v[64:65]
	v_pk_mul_f32 v[64:65], v[80:81], v[64:65]
	v_pk_fma_f32 v[96:97], v[90:91], v[62:63], v[96:97]
	v_pk_fma_f32 v[62:63], v[78:79], v[62:63], v[64:65]
	s_waitcnt lgkmcnt(3)
	v_pk_fma_f32 v[96:97], v[94:95], v[66:67], v[96:97]
	v_pk_fma_f32 v[62:63], v[82:83], v[66:67], v[62:63]
	v_pk_fma_f32 v[96:97], v[88:89], v[68:69], v[96:97]
	v_pk_fma_f32 v[62:63], v[84:85], v[68:69], v[62:63]
	v_add_f32_e32 v96, v96, v97
	v_add_f32_e32 v62, v62, v63
	s_waitcnt lgkmcnt(0)
	v_mov_b32_e32 v64, v87
	v_add_f32_dpp v96, v96, v96 quad_perm:[1,0,3,2] row_mask:0xf bank_mask:0xf bound_ctrl:1
	v_add_f32_dpp v62, v62, v62 quad_perm:[1,0,3,2] row_mask:0xf bank_mask:0xf bound_ctrl:1
	v_add_u32_e32 v104, 0x5c00, v52
	v_add_f32_dpp v96, v96, v96 quad_perm:[2,3,0,1] row_mask:0xf bank_mask:0xf bound_ctrl:1
	v_add_f32_dpp v62, v62, v62 quad_perm:[2,3,0,1] row_mask:0xf bank_mask:0xf bound_ctrl:1
	s_nop 0
	v_add_f32_dpp v96, v96, v96 row_half_mirror row_mask:0xf bank_mask:0xf bound_ctrl:1
	v_add_f32_dpp v62, v62, v62 row_half_mirror row_mask:0xf bank_mask:0xf bound_ctrl:1
	v_pk_mul_f32 v[98:99], v[70:71], v[96:97] op_sel_hi:[1,0] neg_lo:[0,1] neg_hi:[0,1]
	v_pk_mul_f32 v[66:67], v[70:71], v[62:63] op_sel_hi:[1,0] neg_lo:[0,1] neg_hi:[0,1]
	v_pk_fma_f32 v[90:91], v[90:91], v[8:9], v[98:99]
	v_pk_fma_f32 v[8:9], v[78:79], v[8:9], v[66:67]
	v_pk_mul_f32 v[98:99], v[72:73], v[96:97] op_sel_hi:[1,0] neg_lo:[0,1] neg_hi:[0,1]
	v_pk_fma_f32 v[78:79], v[54:55], v[64:65], v[8:9] op_sel_hi:[1,0,1]
	v_pk_mul_f32 v[8:9], v[72:73], v[62:63] op_sel_hi:[1,0] neg_lo:[0,1] neg_hi:[0,1]
	v_pk_fma_f32 v[92:93], v[92:93], v[10:11], v[98:99]
	v_pk_fma_f32 v[8:9], v[80:81], v[10:11], v[8:9]
	v_pk_fma_f32 v[92:93], v[56:57], v[86:87], v[92:93] op_sel_hi:[1,0,1]
	v_pk_fma_f32 v[80:81], v[56:57], v[64:65], v[8:9] op_sel_hi:[1,0,1]
	v_pk_mul_f32 v[8:9], v[74:75], v[62:63] op_sel_hi:[1,0] neg_lo:[0,1] neg_hi:[0,1]
	v_pk_mul_f32 v[98:99], v[74:75], v[96:97] op_sel_hi:[1,0] neg_lo:[0,1] neg_hi:[0,1]
	v_pk_mul_f32 v[96:97], v[76:77], v[96:97] op_sel_hi:[1,0] neg_lo:[0,1] neg_hi:[0,1]
	v_pk_fma_f32 v[8:9], v[82:83], v[12:13], v[8:9]
	v_pk_fma_f32 v[90:91], v[54:55], v[86:87], v[90:91] op_sel_hi:[1,0,1]
	v_pk_fma_f32 v[94:95], v[94:95], v[12:13], v[98:99]
	v_pk_fma_f32 v[88:89], v[88:89], v[14:15], v[96:97]
	v_pk_mul_f32 v[96:97], v[2:3], v[92:93]
	v_pk_fma_f32 v[82:83], v[58:59], v[64:65], v[8:9] op_sel_hi:[1,0,1]
	v_pk_mul_f32 v[8:9], v[76:77], v[62:63] op_sel_hi:[1,0] neg_lo:[0,1] neg_hi:[0,1]
	v_pk_mul_f32 v[2:3], v[2:3], v[80:81]
	v_pk_fma_f32 v[94:95], v[58:59], v[86:87], v[94:95] op_sel_hi:[1,0,1]
	v_pk_fma_f32 v[96:97], v[0:1], v[90:91], v[96:97]
	v_pk_fma_f32 v[8:9], v[84:85], v[14:15], v[8:9]
	v_pk_fma_f32 v[0:1], v[0:1], v[78:79], v[2:3]
	v_pk_fma_f32 v[88:89], v[60:61], v[86:87], v[88:89] op_sel_hi:[1,0,1]
	v_pk_fma_f32 v[96:97], v[4:5], v[94:95], v[96:97]
	v_pk_fma_f32 v[84:85], v[60:61], v[64:65], v[8:9] op_sel_hi:[1,0,1]
	v_pk_fma_f32 v[0:1], v[4:5], v[82:83], v[0:1]
	v_pk_fma_f32 v[96:97], v[6:7], v[88:89], v[96:97]
	v_pk_fma_f32 v[0:1], v[6:7], v[84:85], v[0:1]
	v_add_f32_e32 v86, v96, v97
	v_add_f32_e32 v0, v0, v1
	s_nop 0
	v_add_f32_dpp v86, v86, v86 quad_perm:[1,0,3,2] row_mask:0xf bank_mask:0xf bound_ctrl:1
	v_add_f32_dpp v0, v0, v0 quad_perm:[1,0,3,2] row_mask:0xf bank_mask:0xf bound_ctrl:1
	s_nop 0
	v_add_f32_dpp v86, v86, v86 quad_perm:[2,3,0,1] row_mask:0xf bank_mask:0xf bound_ctrl:1
	v_add_f32_dpp v0, v0, v0 quad_perm:[2,3,0,1] row_mask:0xf bank_mask:0xf bound_ctrl:1
	s_nop 0
	v_add_f32_dpp v86, v86, v86 row_half_mirror row_mask:0xf bank_mask:0xf bound_ctrl:1
	v_add_f32_dpp v0, v0, v0 row_half_mirror row_mask:0xf bank_mask:0xf bound_ctrl:1
	v_cndmask_b32_e64 v100, v100, v86, s[4:5]
	v_cndmask_b32_e64 v101, v101, v0, s[4:5]
	ds_read_b128 v[0:3], v51 offset:768
	ds_read_b128 v[4:7], v51 offset:784
	ds_read_b128 v[8:11], v51 offset:4864
	ds_read_b128 v[12:15], v51 offset:4880
	ds_read_b128 v[54:57], v51 offset:8960
	ds_read_b128 v[58:61], v51 offset:8976
	ds_read_b128 v[62:65], v51 offset:13056
	ds_read_b128 v[66:69], v51 offset:13072
	ds_read_b128 v[70:73], v51 offset:17152
	ds_read_b128 v[74:77], v51 offset:17168
	ds_read2_b32 v[86:87], v53 offset0:192 offset1:224
	s_waitcnt lgkmcnt(4)
	v_pk_mul_f32 v[96:97], v[92:93], v[64:65]
	v_pk_mul_f32 v[64:65], v[80:81], v[64:65]
	v_pk_fma_f32 v[96:97], v[90:91], v[62:63], v[96:97]
	v_pk_fma_f32 v[62:63], v[78:79], v[62:63], v[64:65]
	s_waitcnt lgkmcnt(3)
	v_pk_fma_f32 v[96:97], v[94:95], v[66:67], v[96:97]
	v_pk_fma_f32 v[62:63], v[82:83], v[66:67], v[62:63]
	v_pk_fma_f32 v[96:97], v[88:89], v[68:69], v[96:97]
	v_pk_fma_f32 v[62:63], v[84:85], v[68:69], v[62:63]
	v_add_f32_e32 v53, v96, v97
	v_add_f32_e32 v62, v62, v63
	s_waitcnt lgkmcnt(0)
	v_mov_b32_e32 v64, v87
	v_add_f32_dpp v53, v53, v53 quad_perm:[1,0,3,2] row_mask:0xf bank_mask:0xf bound_ctrl:1
	v_add_f32_dpp v62, v62, v62 quad_perm:[1,0,3,2] row_mask:0xf bank_mask:0xf bound_ctrl:1
	s_nop 0
	v_add_f32_dpp v53, v53, v53 quad_perm:[2,3,0,1] row_mask:0xf bank_mask:0xf bound_ctrl:1
	v_add_f32_dpp v62, v62, v62 quad_perm:[2,3,0,1] row_mask:0xf bank_mask:0xf bound_ctrl:1
	s_nop 0
	v_add_f32_dpp v96, v53, v53 row_half_mirror row_mask:0xf bank_mask:0xf bound_ctrl:1
	v_add_f32_dpp v62, v62, v62 row_half_mirror row_mask:0xf bank_mask:0xf bound_ctrl:1
	v_pk_mul_f32 v[98:99], v[70:71], v[96:97] op_sel_hi:[1,0] neg_lo:[0,1] neg_hi:[0,1]
	v_pk_mul_f32 v[66:67], v[70:71], v[62:63] op_sel_hi:[1,0] neg_lo:[0,1] neg_hi:[0,1]
	v_pk_fma_f32 v[90:91], v[90:91], v[8:9], v[98:99]
	v_pk_fma_f32 v[8:9], v[78:79], v[8:9], v[66:67]
	v_pk_mul_f32 v[98:99], v[72:73], v[96:97] op_sel_hi:[1,0] neg_lo:[0,1] neg_hi:[0,1]
	v_pk_fma_f32 v[78:79], v[54:55], v[64:65], v[8:9] op_sel_hi:[1,0,1]
	v_pk_mul_f32 v[8:9], v[72:73], v[62:63] op_sel_hi:[1,0] neg_lo:[0,1] neg_hi:[0,1]
	v_pk_fma_f32 v[92:93], v[92:93], v[10:11], v[98:99]
	v_pk_fma_f32 v[8:9], v[80:81], v[10:11], v[8:9]
	v_pk_fma_f32 v[92:93], v[56:57], v[86:87], v[92:93] op_sel_hi:[1,0,1]
	v_pk_fma_f32 v[80:81], v[56:57], v[64:65], v[8:9] op_sel_hi:[1,0,1]
	v_pk_mul_f32 v[8:9], v[74:75], v[62:63] op_sel_hi:[1,0] neg_lo:[0,1] neg_hi:[0,1]
	v_pk_mul_f32 v[98:99], v[74:75], v[96:97] op_sel_hi:[1,0] neg_lo:[0,1] neg_hi:[0,1]
	v_pk_mul_f32 v[96:97], v[76:77], v[96:97] op_sel_hi:[1,0] neg_lo:[0,1] neg_hi:[0,1]
	v_pk_fma_f32 v[8:9], v[82:83], v[12:13], v[8:9]
	v_pk_fma_f32 v[90:91], v[54:55], v[86:87], v[90:91] op_sel_hi:[1,0,1]
	v_pk_fma_f32 v[94:95], v[94:95], v[12:13], v[98:99]
	v_pk_fma_f32 v[88:89], v[88:89], v[14:15], v[96:97]
	v_pk_mul_f32 v[96:97], v[2:3], v[92:93]
	v_pk_fma_f32 v[82:83], v[58:59], v[64:65], v[8:9] op_sel_hi:[1,0,1]
	v_pk_mul_f32 v[8:9], v[76:77], v[62:63] op_sel_hi:[1,0] neg_lo:[0,1] neg_hi:[0,1]
	v_pk_mul_f32 v[2:3], v[2:3], v[80:81]
	v_pk_fma_f32 v[94:95], v[58:59], v[86:87], v[94:95] op_sel_hi:[1,0,1]
	v_pk_fma_f32 v[96:97], v[0:1], v[90:91], v[96:97]
	v_pk_fma_f32 v[8:9], v[84:85], v[14:15], v[8:9]
	v_pk_fma_f32 v[0:1], v[0:1], v[78:79], v[2:3]
	v_pk_fma_f32 v[88:89], v[60:61], v[86:87], v[88:89] op_sel_hi:[1,0,1]
	v_pk_fma_f32 v[96:97], v[4:5], v[94:95], v[96:97]
	v_pk_fma_f32 v[84:85], v[60:61], v[64:65], v[8:9] op_sel_hi:[1,0,1]
	v_pk_fma_f32 v[0:1], v[4:5], v[82:83], v[0:1]
	v_pk_fma_f32 v[96:97], v[6:7], v[88:89], v[96:97]
	v_pk_fma_f32 v[0:1], v[6:7], v[84:85], v[0:1]
	v_add_f32_e32 v53, v96, v97
	v_add_f32_e32 v0, v0, v1
	s_nop 0
	v_add_f32_dpp v53, v53, v53 quad_perm:[1,0,3,2] row_mask:0xf bank_mask:0xf bound_ctrl:1
	v_add_f32_dpp v0, v0, v0 quad_perm:[1,0,3,2] row_mask:0xf bank_mask:0xf bound_ctrl:1
	s_nop 0
	v_add_f32_dpp v53, v53, v53 quad_perm:[2,3,0,1] row_mask:0xf bank_mask:0xf bound_ctrl:1
	v_add_f32_dpp v0, v0, v0 quad_perm:[2,3,0,1] row_mask:0xf bank_mask:0xf bound_ctrl:1
	s_nop 0
	v_add_f32_dpp v53, v53, v53 row_half_mirror row_mask:0xf bank_mask:0xf bound_ctrl:1
	v_add_f32_dpp v0, v0, v0 row_half_mirror row_mask:0xf bank_mask:0xf bound_ctrl:1
	v_cndmask_b32_e64 v53, v100, v53, s[6:7]
	v_cndmask_b32_e64 v100, v101, v0, s[6:7]
	ds_read_b128 v[0:3], v51 offset:1024
	ds_read_b128 v[4:7], v51 offset:1040
	ds_read_b128 v[8:11], v51 offset:5120
	ds_read_b128 v[12:15], v51 offset:5136
	ds_read_b128 v[54:57], v51 offset:9216
	ds_read_b128 v[58:61], v51 offset:9232
	ds_read_b128 v[62:65], v51 offset:13312
	ds_read_b128 v[66:69], v51 offset:13328
	ds_read_b128 v[70:73], v51 offset:17408
	ds_read_b128 v[74:77], v51 offset:17424
	v_add_u32_e32 v101, 0x5400, v52
	s_waitcnt lgkmcnt(3)
	v_pk_mul_f32 v[96:97], v[92:93], v[64:65]
	v_pk_mul_f32 v[64:65], v[80:81], v[64:65]
	v_pk_fma_f32 v[96:97], v[90:91], v[62:63], v[96:97]
	v_pk_fma_f32 v[62:63], v[78:79], v[62:63], v[64:65]
	s_waitcnt lgkmcnt(2)
	v_pk_fma_f32 v[96:97], v[94:95], v[66:67], v[96:97]
	v_pk_fma_f32 v[62:63], v[82:83], v[66:67], v[62:63]
	v_pk_fma_f32 v[96:97], v[88:89], v[68:69], v[96:97]
	v_pk_fma_f32 v[62:63], v[84:85], v[68:69], v[62:63]
	ds_read2_b32 v[86:87], v101 offset1:32
	v_add_f32_e32 v96, v96, v97
	v_add_f32_e32 v62, v62, v63
	s_waitcnt lgkmcnt(0)
	v_mov_b32_e32 v64, v87
	v_add_f32_dpp v96, v96, v96 quad_perm:[1,0,3,2] row_mask:0xf bank_mask:0xf bound_ctrl:1
	v_add_f32_dpp v62, v62, v62 quad_perm:[1,0,3,2] row_mask:0xf bank_mask:0xf bound_ctrl:1
	s_nop 0
	v_add_f32_dpp v96, v96, v96 quad_perm:[2,3,0,1] row_mask:0xf bank_mask:0xf bound_ctrl:1
	v_add_f32_dpp v62, v62, v62 quad_perm:[2,3,0,1] row_mask:0xf bank_mask:0xf bound_ctrl:1
	s_nop 0
	v_add_f32_dpp v96, v96, v96 row_half_mirror row_mask:0xf bank_mask:0xf bound_ctrl:1
	v_add_f32_dpp v62, v62, v62 row_half_mirror row_mask:0xf bank_mask:0xf bound_ctrl:1
	v_pk_mul_f32 v[98:99], v[70:71], v[96:97] op_sel_hi:[1,0] neg_lo:[0,1] neg_hi:[0,1]
	v_pk_mul_f32 v[66:67], v[70:71], v[62:63] op_sel_hi:[1,0] neg_lo:[0,1] neg_hi:[0,1]
	v_pk_fma_f32 v[90:91], v[90:91], v[8:9], v[98:99]
	v_pk_fma_f32 v[8:9], v[78:79], v[8:9], v[66:67]
	v_pk_mul_f32 v[98:99], v[72:73], v[96:97] op_sel_hi:[1,0] neg_lo:[0,1] neg_hi:[0,1]
	v_pk_fma_f32 v[78:79], v[54:55], v[64:65], v[8:9] op_sel_hi:[1,0,1]
	v_pk_mul_f32 v[8:9], v[72:73], v[62:63] op_sel_hi:[1,0] neg_lo:[0,1] neg_hi:[0,1]
	v_pk_fma_f32 v[92:93], v[92:93], v[10:11], v[98:99]
	v_pk_fma_f32 v[8:9], v[80:81], v[10:11], v[8:9]
	v_pk_fma_f32 v[92:93], v[56:57], v[86:87], v[92:93] op_sel_hi:[1,0,1]
	v_pk_fma_f32 v[80:81], v[56:57], v[64:65], v[8:9] op_sel_hi:[1,0,1]
	v_pk_mul_f32 v[8:9], v[74:75], v[62:63] op_sel_hi:[1,0] neg_lo:[0,1] neg_hi:[0,1]
	v_pk_mul_f32 v[98:99], v[74:75], v[96:97] op_sel_hi:[1,0] neg_lo:[0,1] neg_hi:[0,1]
	v_pk_mul_f32 v[96:97], v[76:77], v[96:97] op_sel_hi:[1,0] neg_lo:[0,1] neg_hi:[0,1]
	v_pk_fma_f32 v[8:9], v[82:83], v[12:13], v[8:9]
	v_pk_fma_f32 v[90:91], v[54:55], v[86:87], v[90:91] op_sel_hi:[1,0,1]
	v_pk_fma_f32 v[94:95], v[94:95], v[12:13], v[98:99]
	v_pk_fma_f32 v[88:89], v[88:89], v[14:15], v[96:97]
	v_pk_mul_f32 v[96:97], v[2:3], v[92:93]
	v_pk_fma_f32 v[82:83], v[58:59], v[64:65], v[8:9] op_sel_hi:[1,0,1]
	v_pk_mul_f32 v[8:9], v[76:77], v[62:63] op_sel_hi:[1,0] neg_lo:[0,1] neg_hi:[0,1]
	v_pk_mul_f32 v[2:3], v[2:3], v[80:81]
	v_pk_fma_f32 v[94:95], v[58:59], v[86:87], v[94:95] op_sel_hi:[1,0,1]
	v_pk_fma_f32 v[96:97], v[0:1], v[90:91], v[96:97]
	v_pk_fma_f32 v[8:9], v[84:85], v[14:15], v[8:9]
	v_pk_fma_f32 v[0:1], v[0:1], v[78:79], v[2:3]
	v_pk_fma_f32 v[88:89], v[60:61], v[86:87], v[88:89] op_sel_hi:[1,0,1]
	v_pk_fma_f32 v[96:97], v[4:5], v[94:95], v[96:97]
	v_pk_fma_f32 v[84:85], v[60:61], v[64:65], v[8:9] op_sel_hi:[1,0,1]
	v_pk_fma_f32 v[0:1], v[4:5], v[82:83], v[0:1]
	v_pk_fma_f32 v[96:97], v[6:7], v[88:89], v[96:97]
	v_pk_fma_f32 v[0:1], v[6:7], v[84:85], v[0:1]
	v_add_f32_e32 v86, v96, v97
	v_add_f32_e32 v0, v0, v1
	s_nop 0
	v_add_f32_dpp v86, v86, v86 quad_perm:[1,0,3,2] row_mask:0xf bank_mask:0xf bound_ctrl:1
	v_add_f32_dpp v0, v0, v0 quad_perm:[1,0,3,2] row_mask:0xf bank_mask:0xf bound_ctrl:1
	s_nop 0
	v_add_f32_dpp v86, v86, v86 quad_perm:[2,3,0,1] row_mask:0xf bank_mask:0xf bound_ctrl:1
	v_add_f32_dpp v0, v0, v0 quad_perm:[2,3,0,1] row_mask:0xf bank_mask:0xf bound_ctrl:1
	s_nop 0
	v_add_f32_dpp v86, v86, v86 row_half_mirror row_mask:0xf bank_mask:0xf bound_ctrl:1
	v_add_f32_dpp v0, v0, v0 row_half_mirror row_mask:0xf bank_mask:0xf bound_ctrl:1
	v_cndmask_b32_e64 v53, v53, v86, s[8:9]
	v_cndmask_b32_e64 v100, v100, v0, s[8:9]
	ds_read_b128 v[0:3], v51 offset:1280
	ds_read_b128 v[4:7], v51 offset:1296
	ds_read_b128 v[8:11], v51 offset:5376
	ds_read_b128 v[12:15], v51 offset:5392
	ds_read_b128 v[54:57], v51 offset:9472
	ds_read_b128 v[58:61], v51 offset:9488
	ds_read_b128 v[62:65], v51 offset:13568
	ds_read_b128 v[66:69], v51 offset:13584
	ds_read_b128 v[70:73], v51 offset:17664
	ds_read_b128 v[74:77], v51 offset:17680
	ds_read2_b32 v[86:87], v101 offset0:64 offset1:96
	s_waitcnt lgkmcnt(4)
	v_pk_mul_f32 v[96:97], v[92:93], v[64:65]
	v_pk_mul_f32 v[64:65], v[80:81], v[64:65]
	v_pk_fma_f32 v[96:97], v[90:91], v[62:63], v[96:97]
	v_pk_fma_f32 v[62:63], v[78:79], v[62:63], v[64:65]
	s_waitcnt lgkmcnt(3)
	v_pk_fma_f32 v[96:97], v[94:95], v[66:67], v[96:97]
	v_pk_fma_f32 v[62:63], v[82:83], v[66:67], v[62:63]
	v_pk_fma_f32 v[96:97], v[88:89], v[68:69], v[96:97]
	v_pk_fma_f32 v[62:63], v[84:85], v[68:69], v[62:63]
	v_add_f32_e32 v96, v96, v97
	v_add_f32_e32 v62, v62, v63
	s_waitcnt lgkmcnt(0)
	v_mov_b32_e32 v64, v87
	v_add_f32_dpp v96, v96, v96 quad_perm:[1,0,3,2] row_mask:0xf bank_mask:0xf bound_ctrl:1
	v_add_f32_dpp v62, v62, v62 quad_perm:[1,0,3,2] row_mask:0xf bank_mask:0xf bound_ctrl:1
	s_nop 0
	v_add_f32_dpp v96, v96, v96 quad_perm:[2,3,0,1] row_mask:0xf bank_mask:0xf bound_ctrl:1
	v_add_f32_dpp v62, v62, v62 quad_perm:[2,3,0,1] row_mask:0xf bank_mask:0xf bound_ctrl:1
	s_nop 0
	v_add_f32_dpp v96, v96, v96 row_half_mirror row_mask:0xf bank_mask:0xf bound_ctrl:1
	v_add_f32_dpp v62, v62, v62 row_half_mirror row_mask:0xf bank_mask:0xf bound_ctrl:1
	v_pk_mul_f32 v[98:99], v[70:71], v[96:97] op_sel_hi:[1,0] neg_lo:[0,1] neg_hi:[0,1]
	v_pk_mul_f32 v[66:67], v[70:71], v[62:63] op_sel_hi:[1,0] neg_lo:[0,1] neg_hi:[0,1]
	v_pk_fma_f32 v[90:91], v[90:91], v[8:9], v[98:99]
	v_pk_fma_f32 v[8:9], v[78:79], v[8:9], v[66:67]
	v_pk_mul_f32 v[98:99], v[72:73], v[96:97] op_sel_hi:[1,0] neg_lo:[0,1] neg_hi:[0,1]
	v_pk_fma_f32 v[78:79], v[54:55], v[64:65], v[8:9] op_sel_hi:[1,0,1]
	v_pk_mul_f32 v[8:9], v[72:73], v[62:63] op_sel_hi:[1,0] neg_lo:[0,1] neg_hi:[0,1]
	v_pk_fma_f32 v[92:93], v[92:93], v[10:11], v[98:99]
	v_pk_fma_f32 v[8:9], v[80:81], v[10:11], v[8:9]
	v_pk_fma_f32 v[92:93], v[56:57], v[86:87], v[92:93] op_sel_hi:[1,0,1]
	v_pk_fma_f32 v[80:81], v[56:57], v[64:65], v[8:9] op_sel_hi:[1,0,1]
	v_pk_mul_f32 v[8:9], v[74:75], v[62:63] op_sel_hi:[1,0] neg_lo:[0,1] neg_hi:[0,1]
	v_pk_mul_f32 v[98:99], v[74:75], v[96:97] op_sel_hi:[1,0] neg_lo:[0,1] neg_hi:[0,1]
	v_pk_mul_f32 v[96:97], v[76:77], v[96:97] op_sel_hi:[1,0] neg_lo:[0,1] neg_hi:[0,1]
	v_pk_fma_f32 v[8:9], v[82:83], v[12:13], v[8:9]
	v_pk_fma_f32 v[90:91], v[54:55], v[86:87], v[90:91] op_sel_hi:[1,0,1]
	v_pk_fma_f32 v[94:95], v[94:95], v[12:13], v[98:99]
	v_pk_fma_f32 v[88:89], v[88:89], v[14:15], v[96:97]
	v_pk_mul_f32 v[96:97], v[2:3], v[92:93]
	v_pk_fma_f32 v[82:83], v[58:59], v[64:65], v[8:9] op_sel_hi:[1,0,1]
	v_pk_mul_f32 v[8:9], v[76:77], v[62:63] op_sel_hi:[1,0] neg_lo:[0,1] neg_hi:[0,1]
	v_pk_mul_f32 v[2:3], v[2:3], v[80:81]
	v_pk_fma_f32 v[94:95], v[58:59], v[86:87], v[94:95] op_sel_hi:[1,0,1]
	v_pk_fma_f32 v[96:97], v[0:1], v[90:91], v[96:97]
	v_pk_fma_f32 v[8:9], v[84:85], v[14:15], v[8:9]
	v_pk_fma_f32 v[0:1], v[0:1], v[78:79], v[2:3]
	v_pk_fma_f32 v[88:89], v[60:61], v[86:87], v[88:89] op_sel_hi:[1,0,1]
	v_pk_fma_f32 v[96:97], v[4:5], v[94:95], v[96:97]
	v_pk_fma_f32 v[84:85], v[60:61], v[64:65], v[8:9] op_sel_hi:[1,0,1]
	v_pk_fma_f32 v[0:1], v[4:5], v[82:83], v[0:1]
	v_pk_fma_f32 v[96:97], v[6:7], v[88:89], v[96:97]
	v_pk_fma_f32 v[0:1], v[6:7], v[84:85], v[0:1]
	v_add_f32_e32 v86, v96, v97
	v_add_f32_e32 v0, v0, v1
	s_nop 0
	v_add_f32_dpp v86, v86, v86 quad_perm:[1,0,3,2] row_mask:0xf bank_mask:0xf bound_ctrl:1
	v_add_f32_dpp v0, v0, v0 quad_perm:[1,0,3,2] row_mask:0xf bank_mask:0xf bound_ctrl:1
	s_nop 0
	v_add_f32_dpp v86, v86, v86 quad_perm:[2,3,0,1] row_mask:0xf bank_mask:0xf bound_ctrl:1
	v_add_f32_dpp v0, v0, v0 quad_perm:[2,3,0,1] row_mask:0xf bank_mask:0xf bound_ctrl:1
	s_nop 0
	v_add_f32_dpp v86, v86, v86 row_half_mirror row_mask:0xf bank_mask:0xf bound_ctrl:1
	v_add_f32_dpp v0, v0, v0 row_half_mirror row_mask:0xf bank_mask:0xf bound_ctrl:1
	v_cndmask_b32_e64 v53, v53, v86, s[10:11]
	v_cndmask_b32_e64 v100, v100, v0, s[10:11]
	ds_read_b128 v[0:3], v51 offset:1536
	ds_read_b128 v[4:7], v51 offset:1552
	ds_read_b128 v[8:11], v51 offset:5632
	ds_read_b128 v[12:15], v51 offset:5648
	ds_read_b128 v[54:57], v51 offset:9728
	ds_read_b128 v[58:61], v51 offset:9744
	ds_read_b128 v[62:65], v51 offset:13824
	ds_read_b128 v[66:69], v51 offset:13840
	ds_read_b128 v[70:73], v51 offset:17920
	ds_read_b128 v[74:77], v51 offset:17936
	ds_read2_b32 v[86:87], v101 offset0:128 offset1:160
	s_waitcnt lgkmcnt(4)
	v_pk_mul_f32 v[96:97], v[92:93], v[64:65]
	v_pk_mul_f32 v[64:65], v[80:81], v[64:65]
	v_pk_fma_f32 v[96:97], v[90:91], v[62:63], v[96:97]
	v_pk_fma_f32 v[62:63], v[78:79], v[62:63], v[64:65]
	s_waitcnt lgkmcnt(3)
	v_pk_fma_f32 v[96:97], v[94:95], v[66:67], v[96:97]
	v_pk_fma_f32 v[62:63], v[82:83], v[66:67], v[62:63]
	v_pk_fma_f32 v[96:97], v[88:89], v[68:69], v[96:97]
	v_pk_fma_f32 v[62:63], v[84:85], v[68:69], v[62:63]
	v_add_f32_e32 v96, v96, v97
	v_add_f32_e32 v62, v62, v63
	s_waitcnt lgkmcnt(0)
	v_mov_b32_e32 v64, v87
	v_add_f32_dpp v96, v96, v96 quad_perm:[1,0,3,2] row_mask:0xf bank_mask:0xf bound_ctrl:1
	v_add_f32_dpp v62, v62, v62 quad_perm:[1,0,3,2] row_mask:0xf bank_mask:0xf bound_ctrl:1
	s_nop 0
	v_add_f32_dpp v96, v96, v96 quad_perm:[2,3,0,1] row_mask:0xf bank_mask:0xf bound_ctrl:1
	v_add_f32_dpp v62, v62, v62 quad_perm:[2,3,0,1] row_mask:0xf bank_mask:0xf bound_ctrl:1
	s_nop 0
	v_add_f32_dpp v96, v96, v96 row_half_mirror row_mask:0xf bank_mask:0xf bound_ctrl:1
	v_add_f32_dpp v62, v62, v62 row_half_mirror row_mask:0xf bank_mask:0xf bound_ctrl:1
	v_pk_mul_f32 v[98:99], v[70:71], v[96:97] op_sel_hi:[1,0] neg_lo:[0,1] neg_hi:[0,1]
	v_pk_mul_f32 v[66:67], v[70:71], v[62:63] op_sel_hi:[1,0] neg_lo:[0,1] neg_hi:[0,1]
	v_pk_fma_f32 v[90:91], v[90:91], v[8:9], v[98:99]
	v_pk_fma_f32 v[8:9], v[78:79], v[8:9], v[66:67]
	v_pk_mul_f32 v[98:99], v[72:73], v[96:97] op_sel_hi:[1,0] neg_lo:[0,1] neg_hi:[0,1]
	v_pk_fma_f32 v[78:79], v[54:55], v[64:65], v[8:9] op_sel_hi:[1,0,1]
	v_pk_mul_f32 v[8:9], v[72:73], v[62:63] op_sel_hi:[1,0] neg_lo:[0,1] neg_hi:[0,1]
	v_pk_fma_f32 v[92:93], v[92:93], v[10:11], v[98:99]
	v_pk_fma_f32 v[8:9], v[80:81], v[10:11], v[8:9]
	v_pk_fma_f32 v[92:93], v[56:57], v[86:87], v[92:93] op_sel_hi:[1,0,1]
	v_pk_fma_f32 v[80:81], v[56:57], v[64:65], v[8:9] op_sel_hi:[1,0,1]
	v_pk_mul_f32 v[8:9], v[74:75], v[62:63] op_sel_hi:[1,0] neg_lo:[0,1] neg_hi:[0,1]
	v_pk_mul_f32 v[98:99], v[74:75], v[96:97] op_sel_hi:[1,0] neg_lo:[0,1] neg_hi:[0,1]
	v_pk_mul_f32 v[96:97], v[76:77], v[96:97] op_sel_hi:[1,0] neg_lo:[0,1] neg_hi:[0,1]
	v_pk_fma_f32 v[8:9], v[82:83], v[12:13], v[8:9]
	v_pk_fma_f32 v[90:91], v[54:55], v[86:87], v[90:91] op_sel_hi:[1,0,1]
	v_pk_fma_f32 v[94:95], v[94:95], v[12:13], v[98:99]
	v_pk_fma_f32 v[88:89], v[88:89], v[14:15], v[96:97]
	v_pk_mul_f32 v[96:97], v[2:3], v[92:93]
	v_pk_fma_f32 v[82:83], v[58:59], v[64:65], v[8:9] op_sel_hi:[1,0,1]
	v_pk_mul_f32 v[8:9], v[76:77], v[62:63] op_sel_hi:[1,0] neg_lo:[0,1] neg_hi:[0,1]
	v_pk_mul_f32 v[2:3], v[2:3], v[80:81]
	v_pk_fma_f32 v[94:95], v[58:59], v[86:87], v[94:95] op_sel_hi:[1,0,1]
	v_pk_fma_f32 v[96:97], v[0:1], v[90:91], v[96:97]
	v_pk_fma_f32 v[8:9], v[84:85], v[14:15], v[8:9]
	v_pk_fma_f32 v[0:1], v[0:1], v[78:79], v[2:3]
	v_pk_fma_f32 v[88:89], v[60:61], v[86:87], v[88:89] op_sel_hi:[1,0,1]
	v_pk_fma_f32 v[96:97], v[4:5], v[94:95], v[96:97]
	v_pk_fma_f32 v[84:85], v[60:61], v[64:65], v[8:9] op_sel_hi:[1,0,1]
	v_pk_fma_f32 v[0:1], v[4:5], v[82:83], v[0:1]
	v_pk_fma_f32 v[96:97], v[6:7], v[88:89], v[96:97]
	v_pk_fma_f32 v[0:1], v[6:7], v[84:85], v[0:1]
	v_add_f32_e32 v86, v96, v97
	v_add_f32_e32 v0, v0, v1
	s_nop 0
	v_add_f32_dpp v86, v86, v86 quad_perm:[1,0,3,2] row_mask:0xf bank_mask:0xf bound_ctrl:1
	v_add_f32_dpp v0, v0, v0 quad_perm:[1,0,3,2] row_mask:0xf bank_mask:0xf bound_ctrl:1
	s_nop 0
	v_add_f32_dpp v86, v86, v86 quad_perm:[2,3,0,1] row_mask:0xf bank_mask:0xf bound_ctrl:1
	v_add_f32_dpp v0, v0, v0 quad_perm:[2,3,0,1] row_mask:0xf bank_mask:0xf bound_ctrl:1
	s_nop 0
	v_add_f32_dpp v86, v86, v86 row_half_mirror row_mask:0xf bank_mask:0xf bound_ctrl:1
	v_add_f32_dpp v0, v0, v0 row_half_mirror row_mask:0xf bank_mask:0xf bound_ctrl:1
	v_cndmask_b32_e64 v53, v53, v86, s[12:13]
	v_cndmask_b32_e64 v100, v100, v0, s[12:13]
	ds_read_b128 v[0:3], v51 offset:1792
	ds_read_b128 v[4:7], v51 offset:1808
	ds_read_b128 v[8:11], v51 offset:5888
	ds_read_b128 v[12:15], v51 offset:5904
	ds_read_b128 v[54:57], v51 offset:9984
	ds_read_b128 v[58:61], v51 offset:10000
	ds_read_b128 v[62:65], v51 offset:14080
	ds_read_b128 v[66:69], v51 offset:14096
	ds_read_b128 v[70:73], v51 offset:18176
	ds_read_b128 v[74:77], v51 offset:18192
	ds_read2_b32 v[86:87], v101 offset0:192 offset1:224
	s_waitcnt lgkmcnt(4)
	v_pk_mul_f32 v[96:97], v[92:93], v[64:65]
	v_pk_mul_f32 v[64:65], v[80:81], v[64:65]
	v_pk_fma_f32 v[96:97], v[90:91], v[62:63], v[96:97]
	v_pk_fma_f32 v[62:63], v[78:79], v[62:63], v[64:65]
	s_waitcnt lgkmcnt(3)
	v_pk_fma_f32 v[96:97], v[94:95], v[66:67], v[96:97]
	v_pk_fma_f32 v[62:63], v[82:83], v[66:67], v[62:63]
	v_pk_fma_f32 v[96:97], v[88:89], v[68:69], v[96:97]
	v_pk_fma_f32 v[62:63], v[84:85], v[68:69], v[62:63]
	v_add_f32_e32 v96, v96, v97
	v_add_f32_e32 v62, v62, v63
	s_waitcnt lgkmcnt(0)
	v_mov_b32_e32 v64, v87
	v_add_f32_dpp v96, v96, v96 quad_perm:[1,0,3,2] row_mask:0xf bank_mask:0xf bound_ctrl:1
	v_add_f32_dpp v62, v62, v62 quad_perm:[1,0,3,2] row_mask:0xf bank_mask:0xf bound_ctrl:1
	s_nop 0
	v_add_f32_dpp v96, v96, v96 quad_perm:[2,3,0,1] row_mask:0xf bank_mask:0xf bound_ctrl:1
	v_add_f32_dpp v62, v62, v62 quad_perm:[2,3,0,1] row_mask:0xf bank_mask:0xf bound_ctrl:1
	s_nop 0
	v_add_f32_dpp v96, v96, v96 row_half_mirror row_mask:0xf bank_mask:0xf bound_ctrl:1
	v_pk_mul_f32 v[98:99], v[70:71], v[96:97] op_sel_hi:[1,0] neg_lo:[0,1] neg_hi:[0,1]
	v_add_f32_dpp v62, v62, v62 row_half_mirror row_mask:0xf bank_mask:0xf bound_ctrl:1
	v_pk_fma_f32 v[90:91], v[90:91], v[8:9], v[98:99]
	v_pk_mul_f32 v[98:99], v[72:73], v[96:97] op_sel_hi:[1,0] neg_lo:[0,1] neg_hi:[0,1]
	v_pk_fma_f32 v[90:91], v[54:55], v[86:87], v[90:91] op_sel_hi:[1,0,1]
	v_pk_fma_f32 v[92:93], v[92:93], v[10:11], v[98:99]
	v_pk_mul_f32 v[98:99], v[74:75], v[96:97] op_sel_hi:[1,0] neg_lo:[0,1] neg_hi:[0,1]
	v_pk_fma_f32 v[92:93], v[56:57], v[86:87], v[92:93] op_sel_hi:[1,0,1]
	v_pk_mul_f32 v[96:97], v[76:77], v[96:97] op_sel_hi:[1,0] neg_lo:[0,1] neg_hi:[0,1]
	v_pk_fma_f32 v[94:95], v[94:95], v[12:13], v[98:99]
	v_pk_fma_f32 v[88:89], v[88:89], v[14:15], v[96:97]
	v_pk_mul_f32 v[96:97], v[2:3], v[92:93]
	v_pk_fma_f32 v[94:95], v[58:59], v[86:87], v[94:95] op_sel_hi:[1,0,1]
	v_pk_fma_f32 v[96:97], v[0:1], v[90:91], v[96:97]
	v_pk_fma_f32 v[88:89], v[60:61], v[86:87], v[88:89] op_sel_hi:[1,0,1]
	v_pk_fma_f32 v[96:97], v[4:5], v[94:95], v[96:97]
	v_pk_mul_f32 v[66:67], v[70:71], v[62:63] op_sel_hi:[1,0] neg_lo:[0,1] neg_hi:[0,1]
	v_pk_fma_f32 v[96:97], v[6:7], v[88:89], v[96:97]
	v_pk_fma_f32 v[8:9], v[78:79], v[8:9], v[66:67]
	v_add_f32_e32 v86, v96, v97
	s_nop 1
	v_add_f32_dpp v86, v86, v86 quad_perm:[1,0,3,2] row_mask:0xf bank_mask:0xf bound_ctrl:1
	s_nop 1
	v_add_f32_dpp v86, v86, v86 quad_perm:[2,3,0,1] row_mask:0xf bank_mask:0xf bound_ctrl:1
	s_nop 1
	v_add_f32_dpp v86, v86, v86 row_half_mirror row_mask:0xf bank_mask:0xf bound_ctrl:1
	v_cndmask_b32_e64 v53, v53, v86, s[14:15]
	v_pk_fma_f32 v[86:87], v[54:55], v[64:65], v[8:9] op_sel_hi:[1,0,1]
	v_pk_mul_f32 v[8:9], v[72:73], v[62:63] op_sel_hi:[1,0] neg_lo:[0,1] neg_hi:[0,1]
	v_add_u32_e32 v55, 0x5800, v52
	v_pk_fma_f32 v[8:9], v[80:81], v[10:11], v[8:9]
	v_pk_fma_f32 v[80:81], v[56:57], v[64:65], v[8:9] op_sel_hi:[1,0,1]
	v_pk_mul_f32 v[8:9], v[74:75], v[62:63] op_sel_hi:[1,0] neg_lo:[0,1] neg_hi:[0,1]
	v_pk_mul_f32 v[2:3], v[2:3], v[80:81]
	v_pk_fma_f32 v[8:9], v[82:83], v[12:13], v[8:9]
	v_pk_fma_f32 v[0:1], v[0:1], v[86:87], v[2:3]
	v_pk_fma_f32 v[82:83], v[58:59], v[64:65], v[8:9] op_sel_hi:[1,0,1]
	v_pk_mul_f32 v[8:9], v[76:77], v[62:63] op_sel_hi:[1,0] neg_lo:[0,1] neg_hi:[0,1]
	v_pk_fma_f32 v[0:1], v[4:5], v[82:83], v[0:1]
	v_pk_fma_f32 v[8:9], v[84:85], v[14:15], v[8:9]
	v_pk_fma_f32 v[84:85], v[60:61], v[64:65], v[8:9] op_sel_hi:[1,0,1]
	v_pk_fma_f32 v[0:1], v[6:7], v[84:85], v[0:1]
	v_add_f32_e32 v0, v0, v1
	s_nop 1
	v_add_f32_dpp v0, v0, v0 quad_perm:[1,0,3,2] row_mask:0xf bank_mask:0xf bound_ctrl:1
	s_nop 1
	v_add_f32_dpp v0, v0, v0 quad_perm:[2,3,0,1] row_mask:0xf bank_mask:0xf bound_ctrl:1
	s_nop 1
	v_add_f32_dpp v0, v0, v0 row_half_mirror row_mask:0xf bank_mask:0xf bound_ctrl:1
	v_cndmask_b32_e64 v54, v100, v0, s[14:15]
	ds_read_b128 v[0:3], v51 offset:2048
	ds_read_b128 v[4:7], v51 offset:2064
	ds_read_b128 v[8:11], v51 offset:6144
	ds_read_b128 v[12:15], v51 offset:6160
	ds_read_b128 v[56:59], v51 offset:10240
	ds_read_b128 v[60:63], v51 offset:10256
	ds_read_b128 v[64:67], v51 offset:14336
	ds_read_b128 v[68:71], v51 offset:14352
	ds_read_b128 v[72:75], v51 offset:18432
	ds_read_b128 v[76:79], v51 offset:18448
	ds_read2_b32 v[96:97], v55 offset1:32
	s_waitcnt lgkmcnt(4)
	v_pk_mul_f32 v[98:99], v[92:93], v[66:67]
	v_pk_mul_f32 v[66:67], v[80:81], v[66:67]
	v_pk_fma_f32 v[98:99], v[90:91], v[64:65], v[98:99]
	v_pk_fma_f32 v[64:65], v[86:87], v[64:65], v[66:67]
	s_waitcnt lgkmcnt(3)
	v_pk_fma_f32 v[98:99], v[94:95], v[68:69], v[98:99]
	v_pk_fma_f32 v[64:65], v[82:83], v[68:69], v[64:65]
	v_pk_fma_f32 v[98:99], v[88:89], v[70:71], v[98:99]
	v_pk_fma_f32 v[64:65], v[84:85], v[70:71], v[64:65]
	v_add_f32_e32 v98, v98, v99
	v_add_f32_e32 v64, v64, v65
	s_waitcnt lgkmcnt(0)
	v_mov_b32_e32 v66, v97
	v_add_f32_dpp v98, v98, v98 quad_perm:[1,0,3,2] row_mask:0xf bank_mask:0xf bound_ctrl:1
	v_add_f32_dpp v64, v64, v64 quad_perm:[1,0,3,2] row_mask:0xf bank_mask:0xf bound_ctrl:1
	s_nop 0
	v_add_f32_dpp v98, v98, v98 quad_perm:[2,3,0,1] row_mask:0xf bank_mask:0xf bound_ctrl:1
	v_add_f32_dpp v64, v64, v64 quad_perm:[2,3,0,1] row_mask:0xf bank_mask:0xf bound_ctrl:1
	s_nop 0
	v_add_f32_dpp v98, v98, v98 row_half_mirror row_mask:0xf bank_mask:0xf bound_ctrl:1
	v_add_f32_dpp v64, v64, v64 row_half_mirror row_mask:0xf bank_mask:0xf bound_ctrl:1
	v_pk_mul_f32 v[100:101], v[72:73], v[98:99] op_sel_hi:[1,0] neg_lo:[0,1] neg_hi:[0,1]
	v_pk_mul_f32 v[68:69], v[72:73], v[64:65] op_sel_hi:[1,0] neg_lo:[0,1] neg_hi:[0,1]
	v_pk_fma_f32 v[90:91], v[90:91], v[8:9], v[100:101]
	v_pk_fma_f32 v[8:9], v[86:87], v[8:9], v[68:69]
	v_pk_mul_f32 v[100:101], v[74:75], v[98:99] op_sel_hi:[1,0] neg_lo:[0,1] neg_hi:[0,1]
	v_pk_fma_f32 v[86:87], v[56:57], v[66:67], v[8:9] op_sel_hi:[1,0,1]
	v_pk_mul_f32 v[8:9], v[74:75], v[64:65] op_sel_hi:[1,0] neg_lo:[0,1] neg_hi:[0,1]
	v_pk_fma_f32 v[92:93], v[92:93], v[10:11], v[100:101]
	v_pk_fma_f32 v[8:9], v[80:81], v[10:11], v[8:9]
	v_pk_fma_f32 v[92:93], v[58:59], v[96:97], v[92:93] op_sel_hi:[1,0,1]
	v_pk_fma_f32 v[80:81], v[58:59], v[66:67], v[8:9] op_sel_hi:[1,0,1]
	v_pk_mul_f32 v[8:9], v[76:77], v[64:65] op_sel_hi:[1,0] neg_lo:[0,1] neg_hi:[0,1]
	v_pk_mul_f32 v[100:101], v[76:77], v[98:99] op_sel_hi:[1,0] neg_lo:[0,1] neg_hi:[0,1]
	v_pk_mul_f32 v[98:99], v[78:79], v[98:99] op_sel_hi:[1,0] neg_lo:[0,1] neg_hi:[0,1]
	v_pk_fma_f32 v[8:9], v[82:83], v[12:13], v[8:9]
	v_pk_fma_f32 v[90:91], v[56:57], v[96:97], v[90:91] op_sel_hi:[1,0,1]
	v_pk_fma_f32 v[94:95], v[94:95], v[12:13], v[100:101]
	v_pk_fma_f32 v[88:89], v[88:89], v[14:15], v[98:99]
	v_pk_mul_f32 v[98:99], v[2:3], v[92:93]
	v_pk_fma_f32 v[82:83], v[60:61], v[66:67], v[8:9] op_sel_hi:[1,0,1]
	v_pk_mul_f32 v[8:9], v[78:79], v[64:65] op_sel_hi:[1,0] neg_lo:[0,1] neg_hi:[0,1]
	v_pk_mul_f32 v[2:3], v[2:3], v[80:81]
	v_pk_fma_f32 v[94:95], v[60:61], v[96:97], v[94:95] op_sel_hi:[1,0,1]
	v_pk_fma_f32 v[98:99], v[0:1], v[90:91], v[98:99]
	v_pk_fma_f32 v[8:9], v[84:85], v[14:15], v[8:9]
	v_pk_fma_f32 v[0:1], v[0:1], v[86:87], v[2:3]
	v_pk_fma_f32 v[88:89], v[62:63], v[96:97], v[88:89] op_sel_hi:[1,0,1]
	v_pk_fma_f32 v[98:99], v[4:5], v[94:95], v[98:99]
	v_pk_fma_f32 v[84:85], v[62:63], v[66:67], v[8:9] op_sel_hi:[1,0,1]
	v_pk_fma_f32 v[0:1], v[4:5], v[82:83], v[0:1]
	v_pk_fma_f32 v[98:99], v[6:7], v[88:89], v[98:99]
	v_pk_fma_f32 v[0:1], v[6:7], v[84:85], v[0:1]
	v_add_f32_e32 v96, v98, v99
	v_add_f32_e32 v0, v0, v1
	s_nop 0
	v_add_f32_dpp v96, v96, v96 quad_perm:[1,0,3,2] row_mask:0xf bank_mask:0xf bound_ctrl:1
	v_add_f32_dpp v0, v0, v0 quad_perm:[1,0,3,2] row_mask:0xf bank_mask:0xf bound_ctrl:1
	s_nop 0
	v_add_f32_dpp v96, v96, v96 quad_perm:[2,3,0,1] row_mask:0xf bank_mask:0xf bound_ctrl:1
	v_add_f32_dpp v0, v0, v0 quad_perm:[2,3,0,1] row_mask:0xf bank_mask:0xf bound_ctrl:1
	s_nop 0
	v_add_f32_dpp v96, v96, v96 row_half_mirror row_mask:0xf bank_mask:0xf bound_ctrl:1
	v_add_f32_dpp v0, v0, v0 row_half_mirror row_mask:0xf bank_mask:0xf bound_ctrl:1
	v_cndmask_b32_e64 v102, 0, v96, s[0:1]
	v_cndmask_b32_e64 v103, 0, v0, s[0:1]
	ds_read_b128 v[0:3], v51 offset:2304
	ds_read_b128 v[4:7], v51 offset:2320
	ds_read_b128 v[8:11], v51 offset:6400
	ds_read_b128 v[12:15], v51 offset:6416
	ds_read_b128 v[56:59], v51 offset:10496
	ds_read_b128 v[60:63], v51 offset:10512
	ds_read_b128 v[64:67], v51 offset:14592
	ds_read_b128 v[68:71], v51 offset:14608
	ds_read_b128 v[72:75], v51 offset:18688
	ds_read_b128 v[76:79], v51 offset:18704
	ds_read2_b32 v[96:97], v55 offset0:64 offset1:96
	s_waitcnt lgkmcnt(4)
	v_pk_mul_f32 v[98:99], v[92:93], v[66:67]
	v_pk_mul_f32 v[66:67], v[80:81], v[66:67]
	v_pk_fma_f32 v[98:99], v[90:91], v[64:65], v[98:99]
	v_pk_fma_f32 v[64:65], v[86:87], v[64:65], v[66:67]
	s_waitcnt lgkmcnt(3)
	v_pk_fma_f32 v[98:99], v[94:95], v[68:69], v[98:99]
	v_pk_fma_f32 v[64:65], v[82:83], v[68:69], v[64:65]
	v_pk_fma_f32 v[98:99], v[88:89], v[70:71], v[98:99]
	v_pk_fma_f32 v[64:65], v[84:85], v[70:71], v[64:65]
	v_add_f32_e32 v98, v98, v99
	v_add_f32_e32 v64, v64, v65
	s_waitcnt lgkmcnt(0)
	v_mov_b32_e32 v66, v97
	v_add_f32_dpp v98, v98, v98 quad_perm:[1,0,3,2] row_mask:0xf bank_mask:0xf bound_ctrl:1
	v_add_f32_dpp v64, v64, v64 quad_perm:[1,0,3,2] row_mask:0xf bank_mask:0xf bound_ctrl:1
	s_nop 0
	v_add_f32_dpp v98, v98, v98 quad_perm:[2,3,0,1] row_mask:0xf bank_mask:0xf bound_ctrl:1
	v_add_f32_dpp v64, v64, v64 quad_perm:[2,3,0,1] row_mask:0xf bank_mask:0xf bound_ctrl:1
	s_nop 0
	v_add_f32_dpp v98, v98, v98 row_half_mirror row_mask:0xf bank_mask:0xf bound_ctrl:1
	v_add_f32_dpp v64, v64, v64 row_half_mirror row_mask:0xf bank_mask:0xf bound_ctrl:1
	v_pk_mul_f32 v[100:101], v[72:73], v[98:99] op_sel_hi:[1,0] neg_lo:[0,1] neg_hi:[0,1]
	v_pk_mul_f32 v[68:69], v[72:73], v[64:65] op_sel_hi:[1,0] neg_lo:[0,1] neg_hi:[0,1]
	v_pk_fma_f32 v[90:91], v[90:91], v[8:9], v[100:101]
	v_pk_fma_f32 v[8:9], v[86:87], v[8:9], v[68:69]
	v_pk_mul_f32 v[100:101], v[74:75], v[98:99] op_sel_hi:[1,0] neg_lo:[0,1] neg_hi:[0,1]
	v_pk_fma_f32 v[86:87], v[56:57], v[66:67], v[8:9] op_sel_hi:[1,0,1]
	v_pk_mul_f32 v[8:9], v[74:75], v[64:65] op_sel_hi:[1,0] neg_lo:[0,1] neg_hi:[0,1]
	v_pk_fma_f32 v[92:93], v[92:93], v[10:11], v[100:101]
	v_pk_fma_f32 v[8:9], v[80:81], v[10:11], v[8:9]
	v_pk_fma_f32 v[92:93], v[58:59], v[96:97], v[92:93] op_sel_hi:[1,0,1]
	v_pk_fma_f32 v[80:81], v[58:59], v[66:67], v[8:9] op_sel_hi:[1,0,1]
	v_pk_mul_f32 v[8:9], v[76:77], v[64:65] op_sel_hi:[1,0] neg_lo:[0,1] neg_hi:[0,1]
	v_pk_mul_f32 v[100:101], v[76:77], v[98:99] op_sel_hi:[1,0] neg_lo:[0,1] neg_hi:[0,1]
	v_pk_mul_f32 v[98:99], v[78:79], v[98:99] op_sel_hi:[1,0] neg_lo:[0,1] neg_hi:[0,1]
	v_pk_fma_f32 v[8:9], v[82:83], v[12:13], v[8:9]
	v_pk_fma_f32 v[90:91], v[56:57], v[96:97], v[90:91] op_sel_hi:[1,0,1]
	v_pk_fma_f32 v[94:95], v[94:95], v[12:13], v[100:101]
	v_pk_fma_f32 v[88:89], v[88:89], v[14:15], v[98:99]
	v_pk_mul_f32 v[98:99], v[2:3], v[92:93]
	v_pk_fma_f32 v[82:83], v[60:61], v[66:67], v[8:9] op_sel_hi:[1,0,1]
	v_pk_mul_f32 v[8:9], v[78:79], v[64:65] op_sel_hi:[1,0] neg_lo:[0,1] neg_hi:[0,1]
	v_pk_mul_f32 v[2:3], v[2:3], v[80:81]
	v_pk_fma_f32 v[94:95], v[60:61], v[96:97], v[94:95] op_sel_hi:[1,0,1]
	v_pk_fma_f32 v[98:99], v[0:1], v[90:91], v[98:99]
	v_pk_fma_f32 v[8:9], v[84:85], v[14:15], v[8:9]
	v_pk_fma_f32 v[0:1], v[0:1], v[86:87], v[2:3]
	v_pk_fma_f32 v[88:89], v[62:63], v[96:97], v[88:89] op_sel_hi:[1,0,1]
	v_pk_fma_f32 v[98:99], v[4:5], v[94:95], v[98:99]
	v_pk_fma_f32 v[84:85], v[62:63], v[66:67], v[8:9] op_sel_hi:[1,0,1]
	v_pk_fma_f32 v[0:1], v[4:5], v[82:83], v[0:1]
	v_pk_fma_f32 v[98:99], v[6:7], v[88:89], v[98:99]
	v_pk_fma_f32 v[0:1], v[6:7], v[84:85], v[0:1]
	v_add_f32_e32 v96, v98, v99
	v_add_f32_e32 v0, v0, v1
	s_nop 0
	v_add_f32_dpp v96, v96, v96 quad_perm:[1,0,3,2] row_mask:0xf bank_mask:0xf bound_ctrl:1
	v_add_f32_dpp v0, v0, v0 quad_perm:[1,0,3,2] row_mask:0xf bank_mask:0xf bound_ctrl:1
	s_nop 0
	v_add_f32_dpp v96, v96, v96 quad_perm:[2,3,0,1] row_mask:0xf bank_mask:0xf bound_ctrl:1
	v_add_f32_dpp v0, v0, v0 quad_perm:[2,3,0,1] row_mask:0xf bank_mask:0xf bound_ctrl:1
	s_nop 0
	v_add_f32_dpp v96, v96, v96 row_half_mirror row_mask:0xf bank_mask:0xf bound_ctrl:1
	v_add_f32_dpp v0, v0, v0 row_half_mirror row_mask:0xf bank_mask:0xf bound_ctrl:1
	v_cndmask_b32_e64 v102, v102, v96, s[16:17]
	v_cndmask_b32_e64 v103, v103, v0, s[16:17]
	ds_read_b128 v[0:3], v51 offset:2560
	ds_read_b128 v[4:7], v51 offset:2576
	ds_read_b128 v[8:11], v51 offset:6656
	ds_read_b128 v[12:15], v51 offset:6672
	ds_read_b128 v[56:59], v51 offset:10752
	ds_read_b128 v[60:63], v51 offset:10768
	ds_read_b128 v[64:67], v51 offset:14848
	ds_read_b128 v[68:71], v51 offset:14864
	ds_read_b128 v[72:75], v51 offset:18944
	ds_read_b128 v[76:79], v51 offset:18960
	ds_read2_b32 v[96:97], v55 offset0:128 offset1:160
	s_waitcnt lgkmcnt(4)
	v_pk_mul_f32 v[98:99], v[92:93], v[66:67]
	v_pk_mul_f32 v[66:67], v[80:81], v[66:67]
	v_pk_fma_f32 v[98:99], v[90:91], v[64:65], v[98:99]
	v_pk_fma_f32 v[64:65], v[86:87], v[64:65], v[66:67]
	s_waitcnt lgkmcnt(3)
	v_pk_fma_f32 v[98:99], v[94:95], v[68:69], v[98:99]
	v_pk_fma_f32 v[64:65], v[82:83], v[68:69], v[64:65]
	v_pk_fma_f32 v[98:99], v[88:89], v[70:71], v[98:99]
	v_pk_fma_f32 v[64:65], v[84:85], v[70:71], v[64:65]
	v_add_f32_e32 v98, v98, v99
	v_add_f32_e32 v64, v64, v65
	s_waitcnt lgkmcnt(0)
	v_mov_b32_e32 v66, v97
	v_add_f32_dpp v98, v98, v98 quad_perm:[1,0,3,2] row_mask:0xf bank_mask:0xf bound_ctrl:1
	v_add_f32_dpp v64, v64, v64 quad_perm:[1,0,3,2] row_mask:0xf bank_mask:0xf bound_ctrl:1
	s_nop 0
	v_add_f32_dpp v98, v98, v98 quad_perm:[2,3,0,1] row_mask:0xf bank_mask:0xf bound_ctrl:1
	v_add_f32_dpp v64, v64, v64 quad_perm:[2,3,0,1] row_mask:0xf bank_mask:0xf bound_ctrl:1
	s_nop 0
	v_add_f32_dpp v98, v98, v98 row_half_mirror row_mask:0xf bank_mask:0xf bound_ctrl:1
	v_add_f32_dpp v64, v64, v64 row_half_mirror row_mask:0xf bank_mask:0xf bound_ctrl:1
	v_pk_mul_f32 v[100:101], v[72:73], v[98:99] op_sel_hi:[1,0] neg_lo:[0,1] neg_hi:[0,1]
	v_pk_mul_f32 v[68:69], v[72:73], v[64:65] op_sel_hi:[1,0] neg_lo:[0,1] neg_hi:[0,1]
	v_pk_fma_f32 v[90:91], v[90:91], v[8:9], v[100:101]
	v_pk_fma_f32 v[8:9], v[86:87], v[8:9], v[68:69]
	v_pk_mul_f32 v[100:101], v[74:75], v[98:99] op_sel_hi:[1,0] neg_lo:[0,1] neg_hi:[0,1]
	v_pk_fma_f32 v[86:87], v[56:57], v[66:67], v[8:9] op_sel_hi:[1,0,1]
	v_pk_mul_f32 v[8:9], v[74:75], v[64:65] op_sel_hi:[1,0] neg_lo:[0,1] neg_hi:[0,1]
	v_pk_fma_f32 v[92:93], v[92:93], v[10:11], v[100:101]
	v_pk_fma_f32 v[8:9], v[80:81], v[10:11], v[8:9]
	v_pk_fma_f32 v[92:93], v[58:59], v[96:97], v[92:93] op_sel_hi:[1,0,1]
	v_pk_fma_f32 v[80:81], v[58:59], v[66:67], v[8:9] op_sel_hi:[1,0,1]
	v_pk_mul_f32 v[8:9], v[76:77], v[64:65] op_sel_hi:[1,0] neg_lo:[0,1] neg_hi:[0,1]
	v_pk_mul_f32 v[100:101], v[76:77], v[98:99] op_sel_hi:[1,0] neg_lo:[0,1] neg_hi:[0,1]
	v_pk_mul_f32 v[98:99], v[78:79], v[98:99] op_sel_hi:[1,0] neg_lo:[0,1] neg_hi:[0,1]
	v_pk_fma_f32 v[8:9], v[82:83], v[12:13], v[8:9]
	v_pk_fma_f32 v[90:91], v[56:57], v[96:97], v[90:91] op_sel_hi:[1,0,1]
	v_pk_fma_f32 v[94:95], v[94:95], v[12:13], v[100:101]
	v_pk_fma_f32 v[88:89], v[88:89], v[14:15], v[98:99]
	v_pk_mul_f32 v[98:99], v[2:3], v[92:93]
	v_pk_fma_f32 v[82:83], v[60:61], v[66:67], v[8:9] op_sel_hi:[1,0,1]
	v_pk_mul_f32 v[8:9], v[78:79], v[64:65] op_sel_hi:[1,0] neg_lo:[0,1] neg_hi:[0,1]
	v_pk_mul_f32 v[2:3], v[2:3], v[80:81]
	v_pk_fma_f32 v[94:95], v[60:61], v[96:97], v[94:95] op_sel_hi:[1,0,1]
	v_pk_fma_f32 v[98:99], v[0:1], v[90:91], v[98:99]
	v_pk_fma_f32 v[8:9], v[84:85], v[14:15], v[8:9]
	v_pk_fma_f32 v[0:1], v[0:1], v[86:87], v[2:3]
	v_pk_fma_f32 v[88:89], v[62:63], v[96:97], v[88:89] op_sel_hi:[1,0,1]
	v_pk_fma_f32 v[98:99], v[4:5], v[94:95], v[98:99]
	v_pk_fma_f32 v[84:85], v[62:63], v[66:67], v[8:9] op_sel_hi:[1,0,1]
	v_pk_fma_f32 v[0:1], v[4:5], v[82:83], v[0:1]
	v_pk_fma_f32 v[98:99], v[6:7], v[88:89], v[98:99]
	v_pk_fma_f32 v[0:1], v[6:7], v[84:85], v[0:1]
	v_add_f32_e32 v96, v98, v99
	v_add_f32_e32 v0, v0, v1
	s_nop 0
	v_add_f32_dpp v96, v96, v96 quad_perm:[1,0,3,2] row_mask:0xf bank_mask:0xf bound_ctrl:1
	v_add_f32_dpp v0, v0, v0 quad_perm:[1,0,3,2] row_mask:0xf bank_mask:0xf bound_ctrl:1
	s_nop 0
	v_add_f32_dpp v96, v96, v96 quad_perm:[2,3,0,1] row_mask:0xf bank_mask:0xf bound_ctrl:1
	v_add_f32_dpp v0, v0, v0 quad_perm:[2,3,0,1] row_mask:0xf bank_mask:0xf bound_ctrl:1
	s_nop 0
	v_add_f32_dpp v96, v96, v96 row_half_mirror row_mask:0xf bank_mask:0xf bound_ctrl:1
	v_add_f32_dpp v0, v0, v0 row_half_mirror row_mask:0xf bank_mask:0xf bound_ctrl:1
	v_cndmask_b32_e64 v102, v102, v96, s[4:5]
	v_cndmask_b32_e64 v103, v103, v0, s[4:5]
	ds_read_b128 v[0:3], v51 offset:2816
	ds_read_b128 v[4:7], v51 offset:2832
	ds_read_b128 v[8:11], v51 offset:6912
	ds_read_b128 v[12:15], v51 offset:6928
	ds_read_b128 v[56:59], v51 offset:11008
	ds_read_b128 v[60:63], v51 offset:11024
	ds_read_b128 v[64:67], v51 offset:15104
	ds_read_b128 v[68:71], v51 offset:15120
	ds_read_b128 v[72:75], v51 offset:19200
	ds_read_b128 v[76:79], v51 offset:19216
	ds_read2_b32 v[96:97], v55 offset0:192 offset1:224
	s_waitcnt lgkmcnt(4)
	v_pk_mul_f32 v[98:99], v[92:93], v[66:67]
	v_pk_mul_f32 v[66:67], v[80:81], v[66:67]
	v_pk_fma_f32 v[98:99], v[90:91], v[64:65], v[98:99]
	v_pk_fma_f32 v[64:65], v[86:87], v[64:65], v[66:67]
	s_waitcnt lgkmcnt(3)
	v_pk_fma_f32 v[98:99], v[94:95], v[68:69], v[98:99]
	v_pk_fma_f32 v[64:65], v[82:83], v[68:69], v[64:65]
	v_pk_fma_f32 v[98:99], v[88:89], v[70:71], v[98:99]
	v_pk_fma_f32 v[64:65], v[84:85], v[70:71], v[64:65]
	v_add_f32_e32 v55, v98, v99
	v_add_f32_e32 v64, v64, v65
	s_waitcnt lgkmcnt(0)
	v_mov_b32_e32 v66, v97
	v_add_f32_dpp v55, v55, v55 quad_perm:[1,0,3,2] row_mask:0xf bank_mask:0xf bound_ctrl:1
	v_add_f32_dpp v64, v64, v64 quad_perm:[1,0,3,2] row_mask:0xf bank_mask:0xf bound_ctrl:1
	s_nop 0
	v_add_f32_dpp v55, v55, v55 quad_perm:[2,3,0,1] row_mask:0xf bank_mask:0xf bound_ctrl:1
	v_add_f32_dpp v64, v64, v64 quad_perm:[2,3,0,1] row_mask:0xf bank_mask:0xf bound_ctrl:1
	s_nop 0
	v_add_f32_dpp v98, v55, v55 row_half_mirror row_mask:0xf bank_mask:0xf bound_ctrl:1
	v_add_f32_dpp v64, v64, v64 row_half_mirror row_mask:0xf bank_mask:0xf bound_ctrl:1
	v_pk_mul_f32 v[100:101], v[72:73], v[98:99] op_sel_hi:[1,0] neg_lo:[0,1] neg_hi:[0,1]
	v_pk_mul_f32 v[68:69], v[72:73], v[64:65] op_sel_hi:[1,0] neg_lo:[0,1] neg_hi:[0,1]
	v_pk_fma_f32 v[90:91], v[90:91], v[8:9], v[100:101]
	v_pk_fma_f32 v[8:9], v[86:87], v[8:9], v[68:69]
	v_pk_mul_f32 v[100:101], v[74:75], v[98:99] op_sel_hi:[1,0] neg_lo:[0,1] neg_hi:[0,1]
	v_pk_fma_f32 v[86:87], v[56:57], v[66:67], v[8:9] op_sel_hi:[1,0,1]
	v_pk_mul_f32 v[8:9], v[74:75], v[64:65] op_sel_hi:[1,0] neg_lo:[0,1] neg_hi:[0,1]
	v_pk_fma_f32 v[92:93], v[92:93], v[10:11], v[100:101]
	v_pk_fma_f32 v[8:9], v[80:81], v[10:11], v[8:9]
	v_pk_fma_f32 v[92:93], v[58:59], v[96:97], v[92:93] op_sel_hi:[1,0,1]
	v_pk_fma_f32 v[80:81], v[58:59], v[66:67], v[8:9] op_sel_hi:[1,0,1]
	v_pk_mul_f32 v[8:9], v[76:77], v[64:65] op_sel_hi:[1,0] neg_lo:[0,1] neg_hi:[0,1]
	v_pk_mul_f32 v[100:101], v[76:77], v[98:99] op_sel_hi:[1,0] neg_lo:[0,1] neg_hi:[0,1]
	v_pk_mul_f32 v[98:99], v[78:79], v[98:99] op_sel_hi:[1,0] neg_lo:[0,1] neg_hi:[0,1]
	v_pk_fma_f32 v[8:9], v[82:83], v[12:13], v[8:9]
	v_pk_fma_f32 v[90:91], v[56:57], v[96:97], v[90:91] op_sel_hi:[1,0,1]
	v_pk_fma_f32 v[88:89], v[88:89], v[14:15], v[98:99]
	v_pk_mul_f32 v[98:99], v[2:3], v[92:93]
	v_pk_fma_f32 v[82:83], v[60:61], v[66:67], v[8:9] op_sel_hi:[1,0,1]
	v_pk_mul_f32 v[8:9], v[78:79], v[64:65] op_sel_hi:[1,0] neg_lo:[0,1] neg_hi:[0,1]
	v_pk_mul_f32 v[2:3], v[2:3], v[80:81]
	v_pk_fma_f32 v[98:99], v[0:1], v[90:91], v[98:99]
	v_pk_fma_f32 v[8:9], v[84:85], v[14:15], v[8:9]
	v_pk_fma_f32 v[0:1], v[0:1], v[86:87], v[2:3]
	v_pk_fma_f32 v[84:85], v[62:63], v[66:67], v[8:9] op_sel_hi:[1,0,1]
	v_pk_fma_f32 v[0:1], v[4:5], v[82:83], v[0:1]
	v_pk_fma_f32 v[94:95], v[94:95], v[12:13], v[100:101]
	v_pk_fma_f32 v[0:1], v[6:7], v[84:85], v[0:1]
	v_pk_fma_f32 v[94:95], v[60:61], v[96:97], v[94:95] op_sel_hi:[1,0,1]
	v_add_f32_e32 v0, v0, v1
	v_pk_fma_f32 v[88:89], v[62:63], v[96:97], v[88:89] op_sel_hi:[1,0,1]
	v_pk_fma_f32 v[98:99], v[4:5], v[94:95], v[98:99]
	v_add_f32_dpp v0, v0, v0 quad_perm:[1,0,3,2] row_mask:0xf bank_mask:0xf bound_ctrl:1
	v_pk_fma_f32 v[98:99], v[6:7], v[88:89], v[98:99]
	s_nop 0
	v_add_f32_dpp v0, v0, v0 quad_perm:[2,3,0,1] row_mask:0xf bank_mask:0xf bound_ctrl:1
	v_add_f32_e32 v55, v98, v99
	s_nop 0
	v_add_f32_dpp v0, v0, v0 row_half_mirror row_mask:0xf bank_mask:0xf bound_ctrl:1
	v_cndmask_b32_e64 v100, v103, v0, s[6:7]
	ds_read_b128 v[0:3], v51 offset:3072
	ds_read_b128 v[4:7], v51 offset:3088
	ds_read_b128 v[8:11], v51 offset:7168
	ds_read_b128 v[12:15], v51 offset:7184
	ds_read_b128 v[56:59], v51 offset:11264
	ds_read_b128 v[60:63], v51 offset:11280
	ds_read_b128 v[64:67], v51 offset:15360
	ds_read_b128 v[68:71], v51 offset:15376
	ds_read_b128 v[72:75], v51 offset:19456
	ds_read_b128 v[76:79], v51 offset:19472
	ds_read2_b32 v[96:97], v104 offset1:32
	s_waitcnt lgkmcnt(4)
	v_pk_mul_f32 v[98:99], v[92:93], v[66:67]
	v_add_f32_dpp v55, v55, v55 quad_perm:[1,0,3,2] row_mask:0xf bank_mask:0xf bound_ctrl:1
	v_pk_fma_f32 v[98:99], v[90:91], v[64:65], v[98:99]
	v_pk_mul_f32 v[66:67], v[80:81], v[66:67]
	s_waitcnt lgkmcnt(3)
	v_pk_fma_f32 v[98:99], v[94:95], v[68:69], v[98:99]
	v_add_f32_dpp v55, v55, v55 quad_perm:[2,3,0,1] row_mask:0xf bank_mask:0xf bound_ctrl:1
	v_pk_fma_f32 v[98:99], v[88:89], v[70:71], v[98:99]
	v_pk_fma_f32 v[64:65], v[86:87], v[64:65], v[66:67]
	v_add_f32_e32 v52, v98, v99
	v_add_f32_dpp v55, v55, v55 row_half_mirror row_mask:0xf bank_mask:0xf bound_ctrl:1
	v_pk_fma_f32 v[64:65], v[82:83], v[68:69], v[64:65]
	v_add_f32_dpp v52, v52, v52 quad_perm:[1,0,3,2] row_mask:0xf bank_mask:0xf bound_ctrl:1
	v_cndmask_b32_e64 v55, v102, v55, s[6:7]
	v_pk_fma_f32 v[64:65], v[84:85], v[70:71], v[64:65]
	v_add_f32_dpp v52, v52, v52 quad_perm:[2,3,0,1] row_mask:0xf bank_mask:0xf bound_ctrl:1
	s_nop 1
	v_add_f32_dpp v52, v52, v52 row_half_mirror row_mask:0xf bank_mask:0xf bound_ctrl:1
	s_waitcnt lgkmcnt(2)
	v_pk_mul_f32 v[98:99], v[72:73], v[52:53] op_sel_hi:[1,0] neg_lo:[0,1] neg_hi:[0,1]
	v_pk_fma_f32 v[90:91], v[90:91], v[8:9], v[98:99]
	v_pk_mul_f32 v[98:99], v[74:75], v[52:53] op_sel_hi:[1,0] neg_lo:[0,1] neg_hi:[0,1]
	s_waitcnt lgkmcnt(0)
	v_pk_fma_f32 v[90:91], v[56:57], v[96:97], v[90:91] op_sel_hi:[1,0,1]
	v_pk_fma_f32 v[92:93], v[92:93], v[10:11], v[98:99]
	v_pk_mul_f32 v[98:99], v[76:77], v[52:53] op_sel_hi:[1,0] neg_lo:[0,1] neg_hi:[0,1]
	v_pk_fma_f32 v[92:93], v[58:59], v[96:97], v[92:93] op_sel_hi:[1,0,1]
	v_pk_fma_f32 v[94:95], v[94:95], v[12:13], v[98:99]
	v_pk_mul_f32 v[98:99], v[78:79], v[52:53] op_sel_hi:[1,0] neg_lo:[0,1] neg_hi:[0,1]
	v_pk_fma_f32 v[94:95], v[60:61], v[96:97], v[94:95] op_sel_hi:[1,0,1]
	v_pk_fma_f32 v[88:89], v[88:89], v[14:15], v[98:99]
	v_pk_mul_f32 v[98:99], v[2:3], v[92:93]
	v_pk_fma_f32 v[88:89], v[62:63], v[96:97], v[88:89] op_sel_hi:[1,0,1]
	v_pk_fma_f32 v[98:99], v[0:1], v[90:91], v[98:99]
	v_pk_fma_f32 v[98:99], v[4:5], v[94:95], v[98:99]
	v_pk_fma_f32 v[98:99], v[6:7], v[88:89], v[98:99]
	v_add_f32_e32 v52, v98, v99
	s_nop 1
	v_add_f32_dpp v52, v52, v52 quad_perm:[1,0,3,2] row_mask:0xf bank_mask:0xf bound_ctrl:1
	s_nop 1
	v_add_f32_dpp v52, v52, v52 quad_perm:[2,3,0,1] row_mask:0xf bank_mask:0xf bound_ctrl:1
	s_nop 1
	v_add_f32_dpp v52, v52, v52 row_half_mirror row_mask:0xf bank_mask:0xf bound_ctrl:1
	v_cndmask_b32_e64 v55, v55, v52, s[8:9]
	v_add_f32_e32 v52, v64, v65
	v_mov_b32_e32 v64, v97
	s_nop 0
	v_add_f32_dpp v52, v52, v52 quad_perm:[1,0,3,2] row_mask:0xf bank_mask:0xf bound_ctrl:1
	s_nop 1
	v_add_f32_dpp v52, v52, v52 quad_perm:[2,3,0,1] row_mask:0xf bank_mask:0xf bound_ctrl:1
	s_nop 1
	v_add_f32_dpp v52, v52, v52 row_half_mirror row_mask:0xf bank_mask:0xf bound_ctrl:1
	v_pk_mul_f32 v[66:67], v[72:73], v[52:53] op_sel_hi:[1,0] neg_lo:[0,1] neg_hi:[0,1]
	v_pk_fma_f32 v[8:9], v[86:87], v[8:9], v[66:67]
	v_pk_fma_f32 v[86:87], v[56:57], v[64:65], v[8:9] op_sel_hi:[1,0,1]
	v_pk_mul_f32 v[8:9], v[74:75], v[52:53] op_sel_hi:[1,0] neg_lo:[0,1] neg_hi:[0,1]
	v_pk_fma_f32 v[8:9], v[80:81], v[10:11], v[8:9]
	v_pk_fma_f32 v[80:81], v[58:59], v[64:65], v[8:9] op_sel_hi:[1,0,1]
	v_pk_mul_f32 v[8:9], v[76:77], v[52:53] op_sel_hi:[1,0] neg_lo:[0,1] neg_hi:[0,1]
	v_pk_mul_f32 v[2:3], v[2:3], v[80:81]
	v_pk_fma_f32 v[8:9], v[82:83], v[12:13], v[8:9]
	v_pk_fma_f32 v[0:1], v[0:1], v[86:87], v[2:3]
	v_pk_fma_f32 v[82:83], v[60:61], v[64:65], v[8:9] op_sel_hi:[1,0,1]
	v_pk_mul_f32 v[8:9], v[78:79], v[52:53] op_sel_hi:[1,0] neg_lo:[0,1] neg_hi:[0,1]
	v_pk_fma_f32 v[0:1], v[4:5], v[82:83], v[0:1]
	v_pk_fma_f32 v[8:9], v[84:85], v[14:15], v[8:9]
	v_pk_fma_f32 v[84:85], v[62:63], v[64:65], v[8:9] op_sel_hi:[1,0,1]
	v_pk_fma_f32 v[0:1], v[6:7], v[84:85], v[0:1]
	v_add_f32_e32 v0, v0, v1
	s_nop 1
	v_add_f32_dpp v0, v0, v0 quad_perm:[1,0,3,2] row_mask:0xf bank_mask:0xf bound_ctrl:1
	s_nop 1
	v_add_f32_dpp v0, v0, v0 quad_perm:[2,3,0,1] row_mask:0xf bank_mask:0xf bound_ctrl:1
	s_nop 1
	v_add_f32_dpp v0, v0, v0 row_half_mirror row_mask:0xf bank_mask:0xf bound_ctrl:1
	v_cndmask_b32_e64 v100, v100, v0, s[8:9]
	ds_read_b128 v[0:3], v51 offset:3328
	ds_read_b128 v[4:7], v51 offset:3344
	ds_read_b128 v[8:11], v51 offset:7424
	ds_read_b128 v[12:15], v51 offset:7440
	ds_read_b128 v[56:59], v51 offset:11520
	ds_read_b128 v[60:63], v51 offset:11536
	ds_read_b128 v[64:67], v51 offset:15616
	ds_read_b128 v[68:71], v51 offset:15632
	ds_read_b128 v[72:75], v51 offset:19712
	ds_read_b128 v[76:79], v51 offset:19728
	ds_read2_b32 v[96:97], v104 offset0:64 offset1:96
	s_waitcnt lgkmcnt(4)
	v_pk_mul_f32 v[98:99], v[92:93], v[66:67]
	v_pk_mul_f32 v[66:67], v[80:81], v[66:67]
	v_pk_fma_f32 v[98:99], v[90:91], v[64:65], v[98:99]
	v_pk_fma_f32 v[64:65], v[86:87], v[64:65], v[66:67]
	s_waitcnt lgkmcnt(3)
	v_pk_fma_f32 v[98:99], v[94:95], v[68:69], v[98:99]
	v_pk_fma_f32 v[64:65], v[82:83], v[68:69], v[64:65]
	v_pk_fma_f32 v[98:99], v[88:89], v[70:71], v[98:99]
	v_pk_fma_f32 v[64:65], v[84:85], v[70:71], v[64:65]
	v_add_f32_e32 v52, v98, v99
	s_nop 1
	v_add_f32_dpp v52, v52, v52 quad_perm:[1,0,3,2] row_mask:0xf bank_mask:0xf bound_ctrl:1
	s_nop 1
	v_add_f32_dpp v52, v52, v52 quad_perm:[2,3,0,1] row_mask:0xf bank_mask:0xf bound_ctrl:1
	s_nop 1
	v_add_f32_dpp v52, v52, v52 row_half_mirror row_mask:0xf bank_mask:0xf bound_ctrl:1
	s_waitcnt lgkmcnt(2)
	v_pk_mul_f32 v[98:99], v[72:73], v[52:53] op_sel_hi:[1,0] neg_lo:[0,1] neg_hi:[0,1]
	v_pk_fma_f32 v[90:91], v[90:91], v[8:9], v[98:99]
	v_pk_mul_f32 v[98:99], v[74:75], v[52:53] op_sel_hi:[1,0] neg_lo:[0,1] neg_hi:[0,1]
	s_waitcnt lgkmcnt(0)
	v_pk_fma_f32 v[90:91], v[56:57], v[96:97], v[90:91] op_sel_hi:[1,0,1]
	v_pk_fma_f32 v[92:93], v[92:93], v[10:11], v[98:99]
	v_pk_mul_f32 v[98:99], v[76:77], v[52:53] op_sel_hi:[1,0] neg_lo:[0,1] neg_hi:[0,1]
	v_pk_fma_f32 v[92:93], v[58:59], v[96:97], v[92:93] op_sel_hi:[1,0,1]
	v_pk_fma_f32 v[94:95], v[94:95], v[12:13], v[98:99]
	v_pk_mul_f32 v[98:99], v[78:79], v[52:53] op_sel_hi:[1,0] neg_lo:[0,1] neg_hi:[0,1]
	v_pk_fma_f32 v[94:95], v[60:61], v[96:97], v[94:95] op_sel_hi:[1,0,1]
	v_pk_fma_f32 v[88:89], v[88:89], v[14:15], v[98:99]
	v_pk_mul_f32 v[98:99], v[2:3], v[92:93]
	v_pk_fma_f32 v[88:89], v[62:63], v[96:97], v[88:89] op_sel_hi:[1,0,1]
	v_pk_fma_f32 v[98:99], v[0:1], v[90:91], v[98:99]
	v_pk_fma_f32 v[98:99], v[4:5], v[94:95], v[98:99]
	v_pk_fma_f32 v[98:99], v[6:7], v[88:89], v[98:99]
	v_add_f32_e32 v52, v98, v99
	s_nop 1
	v_add_f32_dpp v52, v52, v52 quad_perm:[1,0,3,2] row_mask:0xf bank_mask:0xf bound_ctrl:1
	s_nop 1
	v_add_f32_dpp v52, v52, v52 quad_perm:[2,3,0,1] row_mask:0xf bank_mask:0xf bound_ctrl:1
	s_nop 1
	v_add_f32_dpp v52, v52, v52 row_half_mirror row_mask:0xf bank_mask:0xf bound_ctrl:1
	v_cndmask_b32_e64 v55, v55, v52, s[10:11]
	v_add_f32_e32 v52, v64, v65
	v_mov_b32_e32 v64, v97
	s_nop 0
	v_add_f32_dpp v52, v52, v52 quad_perm:[1,0,3,2] row_mask:0xf bank_mask:0xf bound_ctrl:1
	s_nop 1
	v_add_f32_dpp v52, v52, v52 quad_perm:[2,3,0,1] row_mask:0xf bank_mask:0xf bound_ctrl:1
	s_nop 1
	v_add_f32_dpp v52, v52, v52 row_half_mirror row_mask:0xf bank_mask:0xf bound_ctrl:1
	v_pk_mul_f32 v[66:67], v[72:73], v[52:53] op_sel_hi:[1,0] neg_lo:[0,1] neg_hi:[0,1]
	v_pk_fma_f32 v[8:9], v[86:87], v[8:9], v[66:67]
	v_pk_fma_f32 v[86:87], v[56:57], v[64:65], v[8:9] op_sel_hi:[1,0,1]
	v_pk_mul_f32 v[8:9], v[74:75], v[52:53] op_sel_hi:[1,0] neg_lo:[0,1] neg_hi:[0,1]
	v_pk_fma_f32 v[8:9], v[80:81], v[10:11], v[8:9]
	v_pk_fma_f32 v[80:81], v[58:59], v[64:65], v[8:9] op_sel_hi:[1,0,1]
	v_pk_mul_f32 v[8:9], v[76:77], v[52:53] op_sel_hi:[1,0] neg_lo:[0,1] neg_hi:[0,1]
	v_pk_mul_f32 v[2:3], v[2:3], v[80:81]
	v_pk_fma_f32 v[8:9], v[82:83], v[12:13], v[8:9]
	v_pk_fma_f32 v[0:1], v[0:1], v[86:87], v[2:3]
	v_pk_fma_f32 v[82:83], v[60:61], v[64:65], v[8:9] op_sel_hi:[1,0,1]
	v_pk_mul_f32 v[8:9], v[78:79], v[52:53] op_sel_hi:[1,0] neg_lo:[0,1] neg_hi:[0,1]
	v_pk_fma_f32 v[0:1], v[4:5], v[82:83], v[0:1]
	v_pk_fma_f32 v[8:9], v[84:85], v[14:15], v[8:9]
	v_pk_fma_f32 v[84:85], v[62:63], v[64:65], v[8:9] op_sel_hi:[1,0,1]
	v_pk_fma_f32 v[0:1], v[6:7], v[84:85], v[0:1]
	v_add_f32_e32 v0, v0, v1
	s_nop 1
	v_add_f32_dpp v0, v0, v0 quad_perm:[1,0,3,2] row_mask:0xf bank_mask:0xf bound_ctrl:1
	s_nop 1
	v_add_f32_dpp v0, v0, v0 quad_perm:[2,3,0,1] row_mask:0xf bank_mask:0xf bound_ctrl:1
	s_nop 1
	v_add_f32_dpp v0, v0, v0 row_half_mirror row_mask:0xf bank_mask:0xf bound_ctrl:1
	v_cndmask_b32_e64 v105, v100, v0, s[10:11]
	ds_read_b128 v[0:3], v51 offset:3584
	ds_read_b128 v[4:7], v51 offset:3600
	ds_read_b128 v[8:11], v51 offset:7680
	ds_read_b128 v[12:15], v51 offset:7696
	ds_read_b128 v[56:59], v51 offset:11776
	ds_read_b128 v[60:63], v51 offset:11792
	ds_read_b128 v[64:67], v51 offset:15872
	ds_read_b128 v[68:71], v51 offset:15888
	ds_read_b128 v[72:75], v51 offset:19968
	ds_read_b128 v[76:79], v51 offset:19984
	ds_read2_b32 v[96:97], v104 offset0:128 offset1:160
	s_waitcnt lgkmcnt(4)
	v_pk_mul_f32 v[98:99], v[92:93], v[66:67]
	v_pk_mul_f32 v[66:67], v[80:81], v[66:67]
	v_pk_fma_f32 v[98:99], v[90:91], v[64:65], v[98:99]
	v_pk_fma_f32 v[64:65], v[86:87], v[64:65], v[66:67]
	s_waitcnt lgkmcnt(3)
	v_pk_fma_f32 v[98:99], v[94:95], v[68:69], v[98:99]
	v_pk_fma_f32 v[64:65], v[82:83], v[68:69], v[64:65]
	v_pk_fma_f32 v[98:99], v[88:89], v[70:71], v[98:99]
	v_pk_fma_f32 v[64:65], v[84:85], v[70:71], v[64:65]
	v_add_f32_e32 v52, v98, v99
	s_nop 1
	v_add_f32_dpp v52, v52, v52 quad_perm:[1,0,3,2] row_mask:0xf bank_mask:0xf bound_ctrl:1
	s_nop 1
	v_add_f32_dpp v52, v52, v52 quad_perm:[2,3,0,1] row_mask:0xf bank_mask:0xf bound_ctrl:1
	s_nop 1
	v_add_f32_dpp v52, v52, v52 row_half_mirror row_mask:0xf bank_mask:0xf bound_ctrl:1
	s_waitcnt lgkmcnt(2)
	v_pk_mul_f32 v[98:99], v[72:73], v[52:53] op_sel_hi:[1,0] neg_lo:[0,1] neg_hi:[0,1]
	v_pk_fma_f32 v[90:91], v[90:91], v[8:9], v[98:99]
	v_pk_mul_f32 v[98:99], v[74:75], v[52:53] op_sel_hi:[1,0] neg_lo:[0,1] neg_hi:[0,1]
	s_waitcnt lgkmcnt(0)
	v_pk_fma_f32 v[90:91], v[56:57], v[96:97], v[90:91] op_sel_hi:[1,0,1]
	v_pk_fma_f32 v[92:93], v[92:93], v[10:11], v[98:99]
	v_pk_mul_f32 v[98:99], v[76:77], v[52:53] op_sel_hi:[1,0] neg_lo:[0,1] neg_hi:[0,1]
	v_pk_fma_f32 v[92:93], v[58:59], v[96:97], v[92:93] op_sel_hi:[1,0,1]
	v_pk_fma_f32 v[94:95], v[94:95], v[12:13], v[98:99]
	v_pk_mul_f32 v[98:99], v[78:79], v[52:53] op_sel_hi:[1,0] neg_lo:[0,1] neg_hi:[0,1]
	v_pk_fma_f32 v[94:95], v[60:61], v[96:97], v[94:95] op_sel_hi:[1,0,1]
	v_pk_fma_f32 v[88:89], v[88:89], v[14:15], v[98:99]
	v_pk_mul_f32 v[98:99], v[2:3], v[92:93]
	v_pk_fma_f32 v[88:89], v[62:63], v[96:97], v[88:89] op_sel_hi:[1,0,1]
	v_pk_fma_f32 v[98:99], v[0:1], v[90:91], v[98:99]
	v_pk_fma_f32 v[98:99], v[4:5], v[94:95], v[98:99]
	v_pk_fma_f32 v[98:99], v[6:7], v[88:89], v[98:99]
	v_add_f32_e32 v52, v98, v99
	s_nop 1
	v_add_f32_dpp v52, v52, v52 quad_perm:[1,0,3,2] row_mask:0xf bank_mask:0xf bound_ctrl:1
	s_nop 1
	v_add_f32_dpp v52, v52, v52 quad_perm:[2,3,0,1] row_mask:0xf bank_mask:0xf bound_ctrl:1
	s_nop 1
	v_add_f32_dpp v52, v52, v52 row_half_mirror row_mask:0xf bank_mask:0xf bound_ctrl:1
	v_cndmask_b32_e64 v55, v55, v52, s[12:13]
	v_add_f32_e32 v52, v64, v65
	v_mov_b32_e32 v64, v97
	s_nop 0
	v_add_f32_dpp v52, v52, v52 quad_perm:[1,0,3,2] row_mask:0xf bank_mask:0xf bound_ctrl:1
	s_nop 1
	v_add_f32_dpp v52, v52, v52 quad_perm:[2,3,0,1] row_mask:0xf bank_mask:0xf bound_ctrl:1
	s_nop 1
	v_add_f32_dpp v52, v52, v52 row_half_mirror row_mask:0xf bank_mask:0xf bound_ctrl:1
	v_pk_mul_f32 v[66:67], v[72:73], v[52:53] op_sel_hi:[1,0] neg_lo:[0,1] neg_hi:[0,1]
	v_pk_fma_f32 v[8:9], v[86:87], v[8:9], v[66:67]
	v_pk_fma_f32 v[96:97], v[56:57], v[64:65], v[8:9] op_sel_hi:[1,0,1]
	v_pk_mul_f32 v[8:9], v[74:75], v[52:53] op_sel_hi:[1,0] neg_lo:[0,1] neg_hi:[0,1]
	v_pk_fma_f32 v[8:9], v[80:81], v[10:11], v[8:9]
	v_pk_fma_f32 v[98:99], v[58:59], v[64:65], v[8:9] op_sel_hi:[1,0,1]
	v_pk_mul_f32 v[8:9], v[76:77], v[52:53] op_sel_hi:[1,0] neg_lo:[0,1] neg_hi:[0,1]
	v_pk_mul_f32 v[2:3], v[2:3], v[98:99]
	v_pk_fma_f32 v[8:9], v[82:83], v[12:13], v[8:9]
	v_pk_fma_f32 v[0:1], v[0:1], v[96:97], v[2:3]
	v_pk_fma_f32 v[100:101], v[60:61], v[64:65], v[8:9] op_sel_hi:[1,0,1]
	v_pk_mul_f32 v[8:9], v[78:79], v[52:53] op_sel_hi:[1,0] neg_lo:[0,1] neg_hi:[0,1]
	v_pk_fma_f32 v[0:1], v[4:5], v[100:101], v[0:1]
	v_pk_fma_f32 v[8:9], v[84:85], v[14:15], v[8:9]
	v_pk_fma_f32 v[102:103], v[62:63], v[64:65], v[8:9] op_sel_hi:[1,0,1]
	v_pk_fma_f32 v[0:1], v[6:7], v[102:103], v[0:1]
	v_add_f32_e32 v0, v0, v1
	s_nop 1
	v_add_f32_dpp v0, v0, v0 quad_perm:[1,0,3,2] row_mask:0xf bank_mask:0xf bound_ctrl:1
	s_nop 1
	v_add_f32_dpp v0, v0, v0 quad_perm:[2,3,0,1] row_mask:0xf bank_mask:0xf bound_ctrl:1
	s_nop 1
	v_add_f32_dpp v0, v0, v0 row_half_mirror row_mask:0xf bank_mask:0xf bound_ctrl:1
	v_cndmask_b32_e64 v106, v105, v0, s[12:13]
	ds_read_b128 v[56:59], v51 offset:3840
	ds_read_b128 v[60:63], v51 offset:3856
	ds_read_b128 v[0:3], v51 offset:7936
	ds_read_b128 v[64:67], v51 offset:7952
	ds_read_b128 v[4:7], v51 offset:12032
	ds_read_b128 v[68:71], v51 offset:12048
	ds_read_b128 v[72:75], v51 offset:16128
	ds_read_b128 v[76:79], v51 offset:16144
	ds_read_b128 v[80:83], v51 offset:20224
	ds_read_b128 v[84:87], v51 offset:20240
	ds_read2_b32 v[104:105], v104 offset0:192 offset1:224
	s_waitcnt lgkmcnt(4)
	v_pk_mul_f32 v[8:9], v[92:93], v[74:75]
	v_pk_mul_f32 v[74:75], v[98:99], v[74:75]
	v_pk_fma_f32 v[8:9], v[90:91], v[72:73], v[8:9]
	v_pk_fma_f32 v[72:73], v[96:97], v[72:73], v[74:75]
	s_waitcnt lgkmcnt(3)
	v_pk_fma_f32 v[8:9], v[94:95], v[76:77], v[8:9]
	v_pk_fma_f32 v[72:73], v[100:101], v[76:77], v[72:73]
	v_pk_fma_f32 v[8:9], v[88:89], v[78:79], v[8:9]
	v_pk_fma_f32 v[72:73], v[102:103], v[78:79], v[72:73]
	v_add_f32_e32 v8, v8, v9
	v_add_f32_e32 v52, v72, v73
	s_waitcnt lgkmcnt(0)
	v_mov_b32_e32 v72, v105
	v_add_f32_dpp v8, v8, v8 quad_perm:[1,0,3,2] row_mask:0xf bank_mask:0xf bound_ctrl:1
	v_add_f32_dpp v52, v52, v52 quad_perm:[1,0,3,2] row_mask:0xf bank_mask:0xf bound_ctrl:1
	s_nop 0
	v_add_f32_dpp v8, v8, v8 quad_perm:[2,3,0,1] row_mask:0xf bank_mask:0xf bound_ctrl:1
	v_add_f32_dpp v52, v52, v52 quad_perm:[2,3,0,1] row_mask:0xf bank_mask:0xf bound_ctrl:1
	s_nop 0
	v_add_f32_dpp v10, v8, v8 row_half_mirror row_mask:0xf bank_mask:0xf bound_ctrl:1
	v_add_f32_dpp v52, v52, v52 row_half_mirror row_mask:0xf bank_mask:0xf bound_ctrl:1
	v_pk_mul_f32 v[8:9], v[80:81], v[10:11] op_sel_hi:[1,0] neg_lo:[0,1] neg_hi:[0,1]
	v_pk_mul_f32 v[74:75], v[80:81], v[52:53] op_sel_hi:[1,0] neg_lo:[0,1] neg_hi:[0,1]
	v_pk_fma_f32 v[8:9], v[90:91], v[0:1], v[8:9]
	v_pk_fma_f32 v[0:1], v[96:97], v[0:1], v[74:75]
	v_pk_fma_f32 v[12:13], v[4:5], v[104:105], v[8:9] op_sel_hi:[1,0,1]
	v_pk_mul_f32 v[8:9], v[82:83], v[10:11] op_sel_hi:[1,0] neg_lo:[0,1] neg_hi:[0,1]
	v_pk_fma_f32 v[4:5], v[4:5], v[72:73], v[0:1] op_sel_hi:[1,0,1]
	v_pk_mul_f32 v[0:1], v[82:83], v[52:53] op_sel_hi:[1,0] neg_lo:[0,1] neg_hi:[0,1]
	v_pk_fma_f32 v[8:9], v[92:93], v[2:3], v[8:9]
	v_pk_fma_f32 v[0:1], v[98:99], v[2:3], v[0:1]
	v_pk_fma_f32 v[14:15], v[6:7], v[104:105], v[8:9] op_sel_hi:[1,0,1]
	v_pk_mul_f32 v[8:9], v[84:85], v[10:11] op_sel_hi:[1,0] neg_lo:[0,1] neg_hi:[0,1]
	v_pk_mul_f32 v[10:11], v[86:87], v[10:11] op_sel_hi:[1,0] neg_lo:[0,1] neg_hi:[0,1]
	v_pk_fma_f32 v[6:7], v[6:7], v[72:73], v[0:1] op_sel_hi:[1,0,1]
	v_pk_mul_f32 v[0:1], v[84:85], v[52:53] op_sel_hi:[1,0] neg_lo:[0,1] neg_hi:[0,1]
	v_pk_fma_f32 v[8:9], v[94:95], v[64:65], v[8:9]
	v_pk_fma_f32 v[10:11], v[88:89], v[66:67], v[10:11]
	v_pk_mul_f32 v[88:89], v[58:59], v[14:15]
	v_pk_fma_f32 v[0:1], v[100:101], v[64:65], v[0:1]
	v_pk_mul_f32 v[2:3], v[86:87], v[52:53] op_sel_hi:[1,0] neg_lo:[0,1] neg_hi:[0,1]
	v_pk_mul_f32 v[58:59], v[58:59], v[6:7]
	v_pk_fma_f32 v[8:9], v[68:69], v[104:105], v[8:9] op_sel_hi:[1,0,1]
	v_pk_fma_f32 v[88:89], v[56:57], v[12:13], v[88:89]
	v_pk_fma_f32 v[0:1], v[68:69], v[72:73], v[0:1] op_sel_hi:[1,0,1]
	v_pk_fma_f32 v[2:3], v[102:103], v[66:67], v[2:3]
	v_pk_fma_f32 v[56:57], v[56:57], v[4:5], v[58:59]
	v_pk_fma_f32 v[10:11], v[70:71], v[104:105], v[10:11] op_sel_hi:[1,0,1]
	v_pk_fma_f32 v[88:89], v[60:61], v[8:9], v[88:89]
	v_pk_fma_f32 v[2:3], v[70:71], v[72:73], v[2:3] op_sel_hi:[1,0,1]
	v_pk_fma_f32 v[56:57], v[60:61], v[0:1], v[56:57]
	v_pk_fma_f32 v[88:89], v[62:63], v[10:11], v[88:89]
	v_pk_fma_f32 v[56:57], v[62:63], v[2:3], v[56:57]
	v_add_f32_e32 v51, v88, v89
	v_add_f32_e32 v52, v56, v57
	v_add_u32_e32 v56, 8, v17
	v_add_f32_dpp v51, v51, v51 quad_perm:[1,0,3,2] row_mask:0xf bank_mask:0xf bound_ctrl:1
	v_add_f32_dpp v52, v52, v52 quad_perm:[1,0,3,2] row_mask:0xf bank_mask:0xf bound_ctrl:1
	s_nop 0
	v_add_f32_dpp v51, v51, v51 quad_perm:[2,3,0,1] row_mask:0xf bank_mask:0xf bound_ctrl:1
	v_add_f32_dpp v52, v52, v52 quad_perm:[2,3,0,1] row_mask:0xf bank_mask:0xf bound_ctrl:1
	s_nop 0
	v_add_f32_dpp v51, v51, v51 row_half_mirror row_mask:0xf bank_mask:0xf bound_ctrl:1
	v_add_f32_dpp v52, v52, v52 row_half_mirror row_mask:0xf bank_mask:0xf bound_ctrl:1
	v_cndmask_b32_e64 v51, v55, v51, s[14:15]
	v_cndmask_b32_e64 v55, v106, v52, s[14:15]
	v_add_u32_e32 v52, s24, v46
	v_cndmask_b32_e64 v56, v56, v52, s[36:37]
	v_add_u32_e32 v52, 8, v52
	v_add_lshl_u32 v128, v56, s20, 10
	v_cndmask_b32_e64 v52, v17, v52, s[36:37]
	v_lshl_add_u64 v[56:57], v[42:43], 0, v[128:129]
	v_add_lshl_u32 v128, v52, s20, 10
	global_store_dword v[56:57], v53, off
	global_store_dword v[56:57], v54, off offset:128
	v_lshl_add_u64 v[52:53], v[42:43], 0, v[128:129]
	global_store_dword v[52:53], v51, off
	global_store_dword v[52:53], v55, off offset:128
	s_cbranch_vccnz .LBB0_422
	s_bitcmp1_b32 s25, 0
	s_cselect_b32 s18, 0x6000, 0
	s_add_i32 s18, s78, s18
	s_waitcnt vmcnt(9)
	v_lshlrev_b32_e32 v52, 16, v18
	v_and_b32_e32 v53, 0xffff0000, v18
	v_lshlrev_b32_e32 v54, 16, v19
	v_and_b32_e32 v55, 0xffff0000, v19
	v_lshl_add_u32 v51, v45, 4, s18
	ds_write_b128 v51, v[52:55]
	s_waitcnt vmcnt(8)
	v_lshlrev_b32_e32 v52, 16, v20
	v_and_b32_e32 v53, 0xffff0000, v20
	v_lshlrev_b32_e32 v54, 16, v21
	v_and_b32_e32 v55, 0xffff0000, v21
	ds_write_b128 v51, v[52:55] offset:4096
	s_waitcnt vmcnt(7)
	v_lshlrev_b32_e32 v52, 16, v22
	v_and_b32_e32 v53, 0xffff0000, v22
	v_lshlrev_b32_e32 v54, 16, v23
	v_and_b32_e32 v55, 0xffff0000, v23
	ds_write_b128 v51, v[52:55] offset:8192
	s_waitcnt vmcnt(6)
	v_lshlrev_b32_e32 v52, 16, v24
	v_and_b32_e32 v53, 0xffff0000, v24
	v_lshlrev_b32_e32 v54, 16, v25
	v_and_b32_e32 v55, 0xffff0000, v25
	ds_write_b128 v51, v[52:55] offset:12288
	s_waitcnt vmcnt(5)
	v_lshlrev_b32_e32 v52, 16, v26
	v_and_b32_e32 v53, 0xffff0000, v26
	v_lshlrev_b32_e32 v54, 16, v27
	v_and_b32_e32 v55, 0xffff0000, v27
	ds_write_b128 v51, v[52:55] offset:16384
	s_waitcnt vmcnt(4)
	v_lshlrev_b32_e32 v52, 16, v28
	v_and_b32_e32 v53, 0xffff0000, v28
	v_lshlrev_b32_e32 v54, 16, v29
	v_and_b32_e32 v55, 0xffff0000, v29
	v_add3_u32 v51, s18, v49, v50
	ds_write_b128 v51, v[52:55] offset:20480
	s_branch .LBB0_422

.LBB0_437:
	s_bitcmp1_b32 s46, 0
	s_cselect_b32 s46, 0x6000, 0
	s_add_i32 s46, s78, s46
	v_lshl_add_u32 v32, v24, 2, s46
	v_add_u32_e32 v106, 0x5000, v32
	v_lshl_add_u32 v31, v23, 4, s46
	ds_read2_b32 v[100:101], v106 offset1:16
	ds_read_b128 v[32:35], v31
	ds_read_b128 v[36:39], v31 offset:256
	ds_read2_b32 v[102:103], v106 offset0:32 offset1:48
	ds_read_b128 v[40:43], v31 offset:512
	ds_read_b128 v[44:47], v31 offset:768
	ds_read_b128 v[48:51], v31 offset:8192
	ds_read_b128 v[52:55], v31 offset:1024
	ds_read_b128 v[56:59], v31 offset:4096
	ds_read2_b32 v[104:105], v106 offset0:64 offset1:80
	ds_read_b128 v[60:63], v31 offset:8448
	s_waitcnt lgkmcnt(4)
	v_pk_mul_f32 v[48:49], v[48:49], v[100:101] op_sel_hi:[1,0]
	ds_read_b128 v[64:67], v31 offset:4352
	ds_read_b128 v[72:75], v31 offset:4608
	s_waitcnt lgkmcnt(4)
	v_pk_fma_f32 v[16:17], v[16:17], v[56:57], v[48:49]
	ds_read_b128 v[68:71], v31 offset:8704
	ds_read_b128 v[76:79], v31 offset:8960
	v_mul_f32_e32 v33, v33, v17
	v_fmac_f32_e32 v33, v32, v16
	v_mov_b32_e32 v32, v101
	s_waitcnt lgkmcnt(4)
	v_pk_mul_f32 v[48:49], v[60:61], v[32:33] op_sel_hi:[1,0]
	ds_read_b128 v[80:83], v31 offset:4864
	ds_read_b128 v[88:91], v31 offset:5120
	s_waitcnt lgkmcnt(5)
	v_pk_fma_f32 v[16:17], v[16:17], v[64:65], v[48:49]
	ds_read_b128 v[84:87], v31 offset:9216
	ds_read_b128 v[92:95], v31 offset:9472
	v_mul_f32_e32 v48, v37, v17
	v_fmac_f32_e32 v48, v36, v16
	s_waitcnt lgkmcnt(5)
	v_pk_mul_f32 v[36:37], v[68:69], v[102:103] op_sel_hi:[1,0]
	ds_read_b128 v[96:99], v31 offset:5376
	v_pk_fma_f32 v[16:17], v[16:17], v[72:73], v[36:37]
	v_mov_b32_e32 v36, v103
	v_mul_f32_e32 v37, v41, v17
	v_fmac_f32_e32 v37, v40, v16
	s_waitcnt lgkmcnt(5)
	v_pk_mul_f32 v[40:41], v[76:77], v[36:37] op_sel_hi:[1,0]
	s_andn2_b64 vcc, exec, vcc
	s_waitcnt lgkmcnt(4)
	v_pk_fma_f32 v[16:17], v[16:17], v[80:81], v[40:41]
	s_waitcnt lgkmcnt(2)
	v_pk_mul_f32 v[40:41], v[84:85], v[104:105] op_sel_hi:[1,0]
	v_mul_f32_e32 v45, v45, v17
	v_fmac_f32_e32 v45, v44, v16
	v_pk_fma_f32 v[84:85], v[16:17], v[88:89], v[40:41]
	v_pk_mul_f32 v[16:17], v[50:51], v[100:101] op_sel_hi:[1,0]
	v_pk_mul_f32 v[50:51], v[86:87], v[104:105] op_sel_hi:[1,0]
	v_pk_fma_f32 v[14:15], v[14:15], v[58:59], v[16:17]
	v_mul_f32_e32 v53, v53, v85
	v_fmac_f32_e32 v33, v34, v14
	v_fmac_f32_e32 v33, v35, v15
	v_fmac_f32_e32 v53, v52, v84
	v_mov_b32_e32 v88, v105
	v_add_f32_dpp v16, v33, v33 quad_perm:[1,0,3,2] row_mask:0xf bank_mask:0xf bound_ctrl:1
	s_nop 1
	v_add_f32_dpp v16, v16, v16 quad_perm:[2,3,0,1] row_mask:0xf bank_mask:0xf bound_ctrl:1
	s_nop 1
	v_add_f32_dpp v16, v16, v16 row_half_mirror row_mask:0xf bank_mask:0xf bound_ctrl:1
	s_nop 1
	v_add_f32_dpp v16, v16, v16 row_mirror row_mask:0xf bank_mask:0xf bound_ctrl:1
	v_cndmask_b32_e64 v33, 0, v16, s[38:39]
	v_pk_mul_f32 v[16:17], v[62:63], v[32:33] op_sel_hi:[1,0]
	v_pk_fma_f32 v[14:15], v[14:15], v[66:67], v[16:17]
	v_fmac_f32_e32 v48, v38, v14
	v_fmac_f32_e32 v48, v39, v15
	s_nop 1
	v_add_f32_dpp v16, v48, v48 quad_perm:[1,0,3,2] row_mask:0xf bank_mask:0xf bound_ctrl:1
	s_nop 1
	v_add_f32_dpp v16, v16, v16 quad_perm:[2,3,0,1] row_mask:0xf bank_mask:0xf bound_ctrl:1
	s_nop 1
	v_add_f32_dpp v16, v16, v16 row_half_mirror row_mask:0xf bank_mask:0xf bound_ctrl:1
	s_nop 1
	v_add_f32_dpp v16, v16, v16 row_mirror row_mask:0xf bank_mask:0xf bound_ctrl:1
	v_cndmask_b32_e64 v32, v33, v16, s[4:5]
	v_pk_mul_f32 v[16:17], v[70:71], v[102:103] op_sel_hi:[1,0]
	v_pk_fma_f32 v[14:15], v[14:15], v[74:75], v[16:17]
	v_fmac_f32_e32 v37, v42, v14
	v_fmac_f32_e32 v37, v43, v15
	s_nop 1
	v_add_f32_dpp v16, v37, v37 quad_perm:[1,0,3,2] row_mask:0xf bank_mask:0xf bound_ctrl:1
	s_nop 1
	v_add_f32_dpp v16, v16, v16 quad_perm:[2,3,0,1] row_mask:0xf bank_mask:0xf bound_ctrl:1
	s_nop 1
	v_add_f32_dpp v16, v16, v16 row_half_mirror row_mask:0xf bank_mask:0xf bound_ctrl:1
	s_nop 1
	v_add_f32_dpp v16, v16, v16 row_mirror row_mask:0xf bank_mask:0xf bound_ctrl:1
	v_cndmask_b32_e64 v32, v32, v16, s[6:7]
	v_pk_mul_f32 v[16:17], v[78:79], v[36:37] op_sel_hi:[1,0]
	v_pk_fma_f32 v[48:49], v[14:15], v[82:83], v[16:17]
	v_fmac_f32_e32 v45, v46, v48
	v_pk_fma_f32 v[56:57], v[48:49], v[90:91], v[50:51]
	v_fmac_f32_e32 v45, v47, v49
	v_fmac_f32_e32 v53, v54, v56
	v_fmac_f32_e32 v53, v55, v57
	v_add_f32_dpp v14, v45, v45 quad_perm:[1,0,3,2] row_mask:0xf bank_mask:0xf bound_ctrl:1
	s_nop 0
	v_add_f32_dpp v48, v53, v53 quad_perm:[1,0,3,2] row_mask:0xf bank_mask:0xf bound_ctrl:1
	v_add_f32_dpp v14, v14, v14 quad_perm:[2,3,0,1] row_mask:0xf bank_mask:0xf bound_ctrl:1
	s_nop 0
	v_add_f32_dpp v48, v48, v48 quad_perm:[2,3,0,1] row_mask:0xf bank_mask:0xf bound_ctrl:1
	v_add_f32_dpp v14, v14, v14 row_half_mirror row_mask:0xf bank_mask:0xf bound_ctrl:1
	s_nop 0
	v_add_f32_dpp v48, v48, v48 row_half_mirror row_mask:0xf bank_mask:0xf bound_ctrl:1
	v_add_f32_dpp v14, v14, v14 row_mirror row_mask:0xf bank_mask:0xf bound_ctrl:1
	v_cndmask_b32_e64 v58, v32, v14, s[8:9]
	v_add_f32_dpp v48, v48, v48 row_mirror row_mask:0xf bank_mask:0xf bound_ctrl:1
	ds_read_b128 v[14:17], v31 offset:1280
	ds_read2_b32 v[82:83], v106 offset0:96 offset1:112
	ds_read_b128 v[32:35], v31 offset:1536
	ds_read_b128 v[36:39], v31 offset:1792
	ds_read2_b32 v[86:87], v106 offset0:128 offset1:144
	ds_read_b128 v[40:43], v31 offset:2048
	ds_read_b128 v[44:47], v31 offset:2304
	v_cndmask_b32_e64 v89, v58, v48, s[10:11]
	ds_read_b128 v[48:51], v31 offset:9728
	s_waitcnt lgkmcnt(9)
	v_pk_mul_f32 v[58:59], v[94:95], v[88:89] op_sel_hi:[1,0]
	ds_read_b128 v[52:55], v31 offset:5632
	ds_read_b128 v[60:63], v31 offset:5888
	s_waitcnt lgkmcnt(10)
	v_pk_fma_f32 v[90:91], v[56:57], v[98:99], v[58:59]
	ds_read_b128 v[56:59], v31 offset:9984
	ds_read_b128 v[64:67], v31 offset:10240
	ds_read_b128 v[68:71], v31 offset:6144
	s_waitcnt lgkmcnt(5)
	v_pk_mul_f32 v[50:51], v[50:51], v[82:83] op_sel_hi:[1,0]
	ds_read_b128 v[72:75], v31 offset:10496
	ds_read_b128 v[76:79], v31 offset:6400
	s_waitcnt lgkmcnt(6)
	v_pk_fma_f32 v[50:51], v[90:91], v[54:55], v[50:51]
	v_mov_b32_e32 v54, v83
	s_waitcnt lgkmcnt(4)
	v_pk_mul_f32 v[58:59], v[58:59], v[54:55] op_sel_hi:[1,0]
	v_pk_fma_f32 v[58:59], v[50:51], v[62:63], v[58:59]
	s_waitcnt lgkmcnt(3)
	v_pk_mul_f32 v[62:63], v[66:67], v[86:87] op_sel_hi:[1,0]
	v_mov_b32_e32 v66, v87
	s_waitcnt lgkmcnt(2)
	v_pk_fma_f32 v[62:63], v[58:59], v[70:71], v[62:63]
	s_waitcnt lgkmcnt(1)
	v_pk_mul_f32 v[70:71], v[74:75], v[66:67] op_sel_hi:[1,0]
	v_pk_mul_f32 v[74:75], v[92:93], v[88:89] op_sel_hi:[1,0]
	s_waitcnt lgkmcnt(0)
	v_pk_fma_f32 v[98:99], v[62:63], v[78:79], v[70:71]
	v_pk_fma_f32 v[74:75], v[84:85], v[96:97], v[74:75]
	v_pk_mul_f32 v[46:47], v[46:47], v[98:99]
	v_mul_f32_e32 v55, v15, v75
	v_fmac_f32_e32 v55, v14, v74
	v_pk_mul_f32 v[14:15], v[48:49], v[82:83] op_sel_hi:[1,0]
	ds_read_b128 v[78:81], v31 offset:2560
	ds_read2_b32 v[70:71], v106 offset0:160 offset1:176
	v_pk_fma_f32 v[14:15], v[74:75], v[52:53], v[14:15]
	v_mul_f32_e32 v52, v33, v15
	v_fmac_f32_e32 v52, v32, v14
	v_pk_mul_f32 v[32:33], v[56:57], v[54:55] op_sel_hi:[1,0]
	v_fmac_f32_e32 v55, v16, v90
	v_pk_fma_f32 v[14:15], v[14:15], v[60:61], v[32:33]
	v_pk_mul_f32 v[32:33], v[64:65], v[86:87] op_sel_hi:[1,0]
	v_mul_f32_e32 v37, v37, v15
	v_fmac_f32_e32 v37, v36, v14
	v_pk_fma_f32 v[14:15], v[14:15], v[68:69], v[32:33]
	v_pk_mul_f32 v[32:33], v[72:73], v[66:67] op_sel_hi:[1,0]
	v_fmac_f32_e32 v55, v17, v91
	v_fmac_f32_e32 v52, v34, v50
	v_mul_f32_e32 v36, v41, v15
	v_pk_fma_f32 v[48:49], v[14:15], v[76:77], v[32:33]
	v_add_f32_dpp v15, v55, v55 quad_perm:[1,0,3,2] row_mask:0xf bank_mask:0xf bound_ctrl:1
	v_fmac_f32_e32 v52, v35, v51
	v_fmac_f32_e32 v37, v38, v58
	v_add_f32_dpp v15, v15, v15 quad_perm:[2,3,0,1] row_mask:0xf bank_mask:0xf bound_ctrl:1
	v_add_f32_dpp v16, v52, v52 quad_perm:[1,0,3,2] row_mask:0xf bank_mask:0xf bound_ctrl:1
	v_fmac_f32_e32 v37, v39, v59
	v_add_f32_dpp v15, v15, v15 row_half_mirror row_mask:0xf bank_mask:0xf bound_ctrl:1
	v_add_f32_dpp v16, v16, v16 quad_perm:[2,3,0,1] row_mask:0xf bank_mask:0xf bound_ctrl:1
	v_fmac_f32_e32 v36, v40, v14
	v_add_f32_dpp v15, v15, v15 row_mirror row_mask:0xf bank_mask:0xf bound_ctrl:1
	v_add_f32_dpp v16, v16, v16 row_half_mirror row_mask:0xf bank_mask:0xf bound_ctrl:1
	v_cndmask_b32_e64 v15, v89, v15, s[12:13]
	v_mul_f32_e32 v14, v45, v49
	v_add_f32_dpp v16, v16, v16 row_mirror row_mask:0xf bank_mask:0xf bound_ctrl:1
	v_cndmask_b32_e64 v15, v15, v16, s[14:15]
	v_fmac_f32_e32 v36, v42, v62
	v_add_f32_dpp v16, v37, v37 quad_perm:[1,0,3,2] row_mask:0xf bank_mask:0xf bound_ctrl:1
	v_fmac_f32_e32 v14, v44, v48
	v_fmac_f32_e32 v36, v43, v63
	v_add_f32_dpp v16, v16, v16 quad_perm:[2,3,0,1] row_mask:0xf bank_mask:0xf bound_ctrl:1
	v_add_f32_e32 v14, v46, v14
	v_add_f32_e32 v14, v47, v14
	v_add_f32_dpp v16, v16, v16 row_half_mirror row_mask:0xf bank_mask:0xf bound_ctrl:1
	s_nop 0
	v_add_f32_dpp v14, v14, v14 quad_perm:[1,0,3,2] row_mask:0xf bank_mask:0xf bound_ctrl:1
	v_add_f32_dpp v16, v16, v16 row_mirror row_mask:0xf bank_mask:0xf bound_ctrl:1
	v_cndmask_b32_e64 v15, v15, v16, s[16:17]
	v_add_f32_dpp v14, v14, v14 quad_perm:[2,3,0,1] row_mask:0xf bank_mask:0xf bound_ctrl:1
	v_add_f32_dpp v16, v36, v36 quad_perm:[1,0,3,2] row_mask:0xf bank_mask:0xf bound_ctrl:1
	s_nop 0
	v_add_f32_dpp v33, v14, v14 row_half_mirror row_mask:0xf bank_mask:0xf bound_ctrl:1
	v_add_f32_dpp v16, v16, v16 quad_perm:[2,3,0,1] row_mask:0xf bank_mask:0xf bound_ctrl:1
	s_nop 0
	v_add_f32_dpp v33, v33, v33 row_mirror row_mask:0xf bank_mask:0xf bound_ctrl:1
	v_add_f32_dpp v16, v16, v16 row_half_mirror row_mask:0xf bank_mask:0xf bound_ctrl:1
	s_nop 1
	v_add_f32_dpp v16, v16, v16 row_mirror row_mask:0xf bank_mask:0xf bound_ctrl:1
	v_cndmask_b32_e64 v32, v15, v16, s[18:19]
	ds_read_b128 v[14:17], v31 offset:10752
	v_cndmask_b32_e64 v107, v32, v33, s[20:21]
	ds_read_b128 v[32:35], v31 offset:6656
	ds_read_b128 v[36:39], v31 offset:11008
	ds_read2_b32 v[102:103], v106 offset0:192 offset1:208
	ds_read2_b32 v[104:105], v106 offset0:224 offset1:240
	ds_read_b128 v[40:43], v31 offset:6912
	ds_read_b128 v[44:47], v31 offset:2816
	s_waitcnt lgkmcnt(6)
	v_pk_mul_f32 v[14:15], v[14:15], v[70:71] op_sel_hi:[1,0]
	v_pk_mul_f32 v[100:101], v[16:17], v[70:71] op_sel_hi:[1,0]
	s_waitcnt lgkmcnt(5)
	v_pk_fma_f32 v[14:15], v[48:49], v[32:33], v[14:15]
	ds_read_b128 v[48:51], v31 offset:11264
	v_mul_f32_e32 v33, v79, v15
	ds_read_b128 v[52:55], v31 offset:7168
	ds_read_b128 v[56:59], v31 offset:3072
	ds_read_b128 v[60:63], v31 offset:11520
	v_fmac_f32_e32 v33, v78, v14
	v_mov_b32_e32 v32, v71
	ds_read_b128 v[64:67], v31 offset:7424
	ds_read_b128 v[68:71], v31 offset:3328
	ds_read_b128 v[72:75], v31 offset:11776
	s_waitcnt lgkmcnt(11)
	v_pk_mul_f32 v[16:17], v[36:37], v[32:33] op_sel_hi:[1,0]
	ds_read_b128 v[76:79], v31 offset:7680
	ds_read_b128 v[82:85], v31 offset:3584
	ds_read_b128 v[86:89], v31 offset:12032
	s_waitcnt lgkmcnt(11)
	v_pk_fma_f32 v[14:15], v[14:15], v[40:41], v[16:17]
	ds_read_b128 v[90:93], v31 offset:7936
	ds_read_b128 v[94:97], v31 offset:3840
	s_waitcnt lgkmcnt(12)
	v_pk_mul_f32 v[36:37], v[44:45], v[14:15]
	s_waitcnt lgkmcnt(11)
	v_pk_mul_f32 v[16:17], v[48:49], v[102:103] op_sel_hi:[1,0]
	v_mov_b32_e32 v44, v103
	s_waitcnt lgkmcnt(10)
	v_pk_fma_f32 v[14:15], v[14:15], v[52:53], v[16:17]
	s_waitcnt lgkmcnt(8)
	v_pk_mul_f32 v[16:17], v[60:61], v[44:45] op_sel_hi:[1,0]
	v_pk_mul_f32 v[40:41], v[56:57], v[14:15]
	s_waitcnt lgkmcnt(7)
	v_pk_fma_f32 v[14:15], v[14:15], v[64:65], v[16:17]
	s_waitcnt lgkmcnt(5)
	v_pk_mul_f32 v[16:17], v[72:73], v[104:105] op_sel_hi:[1,0]
	v_mov_b32_e32 v56, v105
	v_pk_mul_f32 v[48:49], v[68:69], v[14:15]
	s_waitcnt lgkmcnt(4)
	v_pk_fma_f32 v[14:15], v[14:15], v[76:77], v[16:17]
	s_waitcnt lgkmcnt(2)
	v_pk_mul_f32 v[16:17], v[86:87], v[56:57] op_sel_hi:[1,0]
	v_pk_mul_f32 v[52:53], v[82:83], v[14:15]
	s_waitcnt lgkmcnt(1)
	v_pk_fma_f32 v[16:17], v[14:15], v[90:91], v[16:17]
	v_pk_fma_f32 v[14:15], v[98:99], v[34:35], v[100:101]
	s_waitcnt lgkmcnt(0)
	v_pk_mul_f32 v[60:61], v[94:95], v[16:17]
	v_pk_mul_f32 v[34:35], v[80:81], v[14:15]
	v_add_f32_e32 v31, v34, v33
	v_pk_mul_f32 v[32:33], v[38:39], v[32:33] op_sel_hi:[1,0]
	v_add_f32_e32 v34, v36, v37
	v_pk_fma_f32 v[14:15], v[14:15], v[42:43], v[32:33]
	v_add_f32_e32 v31, v35, v31
	v_pk_mul_f32 v[32:33], v[46:47], v[14:15]
	v_add_f32_e32 v32, v32, v34
	v_add_f32_dpp v31, v31, v31 quad_perm:[1,0,3,2] row_mask:0xf bank_mask:0xf bound_ctrl:1
	v_add_f32_e32 v32, v33, v32
	v_add_f32_e32 v34, v40, v41
	v_add_f32_dpp v31, v31, v31 quad_perm:[2,3,0,1] row_mask:0xf bank_mask:0xf bound_ctrl:1
	v_add_f32_dpp v32, v32, v32 quad_perm:[1,0,3,2] row_mask:0xf bank_mask:0xf bound_ctrl:1
	s_nop 0
	v_add_f32_dpp v31, v31, v31 row_half_mirror row_mask:0xf bank_mask:0xf bound_ctrl:1
	v_add_f32_dpp v32, v32, v32 quad_perm:[2,3,0,1] row_mask:0xf bank_mask:0xf bound_ctrl:1
	s_nop 0
	v_add_f32_dpp v31, v31, v31 row_mirror row_mask:0xf bank_mask:0xf bound_ctrl:1
	v_add_f32_dpp v32, v32, v32 row_half_mirror row_mask:0xf bank_mask:0xf bound_ctrl:1
	v_cndmask_b32_e64 v31, v107, v31, s[22:23]
	s_nop 0
	v_add_f32_dpp v32, v32, v32 row_mirror row_mask:0xf bank_mask:0xf bound_ctrl:1
	v_cndmask_b32_e64 v31, v31, v32, s[24:25]
	v_pk_mul_f32 v[32:33], v[50:51], v[102:103] op_sel_hi:[1,0]
	v_pk_fma_f32 v[14:15], v[14:15], v[54:55], v[32:33]
	v_pk_mul_f32 v[32:33], v[58:59], v[14:15]
	v_add_f32_e32 v32, v32, v34
	v_add_f32_e32 v32, v33, v32
	v_add_f32_e32 v34, v48, v49
	s_nop 0
	v_add_f32_dpp v32, v32, v32 quad_perm:[1,0,3,2] row_mask:0xf bank_mask:0xf bound_ctrl:1
	s_nop 1
	v_add_f32_dpp v32, v32, v32 quad_perm:[2,3,0,1] row_mask:0xf bank_mask:0xf bound_ctrl:1
	s_nop 1
	v_add_f32_dpp v32, v32, v32 row_half_mirror row_mask:0xf bank_mask:0xf bound_ctrl:1
	s_nop 1
	v_add_f32_dpp v32, v32, v32 row_mirror row_mask:0xf bank_mask:0xf bound_ctrl:1
	v_cndmask_b32_e64 v31, v31, v32, s[26:27]
	v_pk_mul_f32 v[32:33], v[62:63], v[44:45] op_sel_hi:[1,0]
	v_pk_fma_f32 v[14:15], v[14:15], v[66:67], v[32:33]
	v_pk_mul_f32 v[32:33], v[70:71], v[14:15]
	v_add_f32_e32 v32, v32, v34
	v_add_f32_e32 v32, v33, v32
	v_add_f32_e32 v34, v52, v53
	s_nop 0
	v_add_f32_dpp v32, v32, v32 quad_perm:[1,0,3,2] row_mask:0xf bank_mask:0xf bound_ctrl:1
	s_nop 1
	v_add_f32_dpp v32, v32, v32 quad_perm:[2,3,0,1] row_mask:0xf bank_mask:0xf bound_ctrl:1
	s_nop 1
	v_add_f32_dpp v32, v32, v32 row_half_mirror row_mask:0xf bank_mask:0xf bound_ctrl:1
	s_nop 1
	v_add_f32_dpp v32, v32, v32 row_mirror row_mask:0xf bank_mask:0xf bound_ctrl:1
	v_cndmask_b32_e64 v31, v31, v32, s[28:29]
	v_pk_mul_f32 v[32:33], v[74:75], v[104:105] op_sel_hi:[1,0]
	v_pk_fma_f32 v[14:15], v[14:15], v[78:79], v[32:33]
	v_pk_mul_f32 v[32:33], v[84:85], v[14:15]
	v_add_f32_e32 v32, v32, v34
	v_add_f32_e32 v32, v33, v32
	v_add_f32_e32 v34, v60, v61
	s_nop 0
	v_add_f32_dpp v32, v32, v32 quad_perm:[1,0,3,2] row_mask:0xf bank_mask:0xf bound_ctrl:1
	s_nop 1
	v_add_f32_dpp v32, v32, v32 quad_perm:[2,3,0,1] row_mask:0xf bank_mask:0xf bound_ctrl:1
	s_nop 1
	v_add_f32_dpp v32, v32, v32 row_half_mirror row_mask:0xf bank_mask:0xf bound_ctrl:1
	s_nop 1
	v_add_f32_dpp v32, v32, v32 row_mirror row_mask:0xf bank_mask:0xf bound_ctrl:1
	v_cndmask_b32_e64 v31, v31, v32, s[30:31]
	v_pk_mul_f32 v[32:33], v[88:89], v[56:57] op_sel_hi:[1,0]
	v_pk_fma_f32 v[14:15], v[14:15], v[92:93], v[32:33]
	v_pk_mul_f32 v[32:33], v[96:97], v[14:15]
	v_add_f32_e32 v32, v32, v34
	v_add_f32_e32 v32, v33, v32
	s_nop 1
	v_add_f32_dpp v32, v32, v32 quad_perm:[1,0,3,2] row_mask:0xf bank_mask:0xf bound_ctrl:1
	s_nop 1
	v_add_f32_dpp v32, v32, v32 quad_perm:[2,3,0,1] row_mask:0xf bank_mask:0xf bound_ctrl:1
	s_nop 1
	v_add_f32_dpp v32, v32, v32 row_half_mirror row_mask:0xf bank_mask:0xf bound_ctrl:1
	s_nop 1
	v_add_f32_dpp v32, v32, v32 row_mirror row_mask:0xf bank_mask:0xf bound_ctrl:1
	v_cndmask_b32_e64 v31, v31, v32, s[34:35]
	v_cndmask_b32_e64 v32, v27, v30, s[0:1]
	v_add_u32_e32 v32, s82, v32
	v_ashrrev_i32_e32 v33, 31, v32
	v_lshlrev_b64 v[32:33], 10, v[32:33]
	v_lshl_add_u64 v[32:33], v[18:19], 0, v[32:33]
	global_store_dword v[32:33], v31, off
	s_cbranch_vccnz .LBB0_439
	s_waitcnt vmcnt(2)
	v_lshlrev_b32_e32 v31, 16, v8
	v_mul_f32_e32 v31, 0xbfb8aa3b, v31
	v_exp_f32_e32 v31, v31
	v_lshlrev_b32_e32 v32, 16, v6
	v_and_b32_e32 v33, 0xffff0000, v6
	v_mul_f32_e32 v40, 0xbfb8aa3b, v32
	v_add_f32_e32 v31, 1.0, v31
	v_rcp_f32_e32 v36, v31
	v_and_b32_e32 v31, 0xffff0000, v8
	v_mul_f32_e32 v31, 0xbfb8aa3b, v31
	v_exp_f32_e32 v31, v31
	v_mul_f32_e32 v41, 0xbfb8aa3b, v33
	v_exp_f32_e32 v40, v40
	v_exp_f32_e32 v41, v41
	v_add_f32_e32 v31, 1.0, v31
	v_rcp_f32_e32 v37, v31
	v_lshlrev_b32_e32 v31, 16, v9
	v_mul_f32_e32 v31, 0xbfb8aa3b, v31
	v_exp_f32_e32 v31, v31
	v_add_f32_e32 v40, 1.0, v40
	v_add_f32_e32 v41, 1.0, v41
	v_rcp_f32_e32 v40, v40
	v_rcp_f32_e32 v41, v41
	v_lshlrev_b32_e32 v34, 16, v7
	v_and_b32_e32 v35, 0xffff0000, v7
	v_add_f32_e32 v31, 1.0, v31
	v_rcp_f32_e32 v38, v31
	v_and_b32_e32 v31, 0xffff0000, v9
	v_pk_mul_f32 v[32:33], v[40:41], v[32:33]
	v_mul_f32_e32 v40, 0xbfb8aa3b, v34
	v_mul_f32_e32 v41, 0xbfb8aa3b, v35
	v_mul_f32_e32 v31, 0xbfb8aa3b, v31
	v_exp_f32_e32 v40, v40
	v_exp_f32_e32 v41, v41
	v_exp_f32_e32 v31, v31
	s_bitcmp1_b32 s47, 0
	v_add_f32_e32 v40, 1.0, v40
	v_add_f32_e32 v41, 1.0, v41
	v_add_f32_e32 v31, 1.0, v31
	v_rcp_f32_e32 v40, v40
	v_rcp_f32_e32 v41, v41
	v_rcp_f32_e32 v39, v31
	s_cselect_b32 s46, 0x6000, 0
	s_add_i32 s46, s78, s46
	v_lshl_add_u32 v31, v22, 4, s46
	v_pk_mul_f32 v[34:35], v[40:41], v[34:35]
	ds_write_b128 v31, v[32:35]
	v_lshl_add_u32 v40, v25, 4, s46
	v_pk_fma_f32 v[32:33], v[10:11], v[36:37], v[0:1]
	v_pk_fma_f32 v[34:35], v[12:13], v[38:39], v[2:3]
	ds_write_b128 v40, v[32:35] offset:4096
	v_pk_add_f32 v[32:33], v[36:37], 1.0 op_sel_hi:[1,0] neg_lo:[1,0] neg_hi:[1,0]
	v_pk_add_f32 v[34:35], v[38:39], 1.0 op_sel_hi:[1,0] neg_lo:[1,0] neg_hi:[1,0]
	v_pk_mul_f32 v[32:33], v[10:11], v[32:33]
	v_pk_mul_f32 v[34:35], v[12:13], v[34:35]
	ds_write_b128 v40, v[32:35] offset:8192
	s_waitcnt vmcnt(1)
	v_lshlrev_b32_e32 v32, 16, v21
	v_add_u32_e32 v31, v31, v26
	ds_write_b32 v31, v32 offset:20480

.LBB0_453:
	s_bitcmp1_b32 s46, 0
	s_cselect_b32 s46, 0x6000, 0
	s_add_i32 s46, s78, s46
	v_lshl_add_u32 v41, v6, 4, s46
	ds_read_b128 v[30:33], v41
	ds_read_b128 v[44:47], v41 offset:12288
	v_lshl_add_u32 v42, v34, 2, s46
	v_add_u32_e32 v42, 0x5000, v42
	ds_read2_b32 v[72:73], v42 offset1:16
	ds_read_b128 v[48:51], v41 offset:12544
	s_andn2_b64 vcc, exec, s[96:97]
	s_waitcnt lgkmcnt(2)
	v_pk_mul_f32 v[44:45], v[0:1], v[44:45]
	v_pk_mul_f32 v[46:47], v[2:3], v[46:47]
	v_add_f32_e32 v43, v44, v45
	v_add_f32_e32 v43, v43, v46
	v_add_f32_e32 v43, v43, v47
	ds_read_b128 v[44:47], v41 offset:16384
	ds_read_b128 v[52:55], v41 offset:4096
	ds_read_b128 v[56:59], v41 offset:8192
	ds_read_b128 v[60:63], v41 offset:16640
	v_add_f32_dpp v43, v43, v43 quad_perm:[1,0,3,2] row_mask:0xf bank_mask:0xf bound_ctrl:1
	ds_read_b128 v[64:67], v41 offset:4352
	ds_read_b128 v[68:71], v41 offset:8448
	v_add_f32_dpp v43, v43, v43 quad_perm:[2,3,0,1] row_mask:0xf bank_mask:0xf bound_ctrl:1
	s_nop 1
	v_add_f32_dpp v43, v43, v43 row_half_mirror row_mask:0xf bank_mask:0xf bound_ctrl:1
	s_nop 1
	v_add_f32_dpp v74, v43, v43 row_mirror row_mask:0xf bank_mask:0xf bound_ctrl:1
	s_waitcnt lgkmcnt(5)
	v_pk_mul_f32 v[44:45], v[44:45], v[74:75] op_sel_hi:[1,0]
	s_waitcnt lgkmcnt(4)
	v_pk_fma_f32 v[0:1], v[0:1], v[52:53], v[44:45] neg_lo:[0,0,1] neg_hi:[0,0,1]
	s_waitcnt lgkmcnt(3)
	v_pk_fma_f32 v[106:107], v[56:57], v[72:73], v[0:1] op_sel_hi:[1,0,1]
	v_pk_mul_f32 v[0:1], v[46:47], v[74:75] op_sel_hi:[1,0]
	ds_read_b128 v[44:47], v41 offset:256
	v_pk_fma_f32 v[0:1], v[2:3], v[54:55], v[0:1] neg_lo:[0,0,1] neg_hi:[0,0,1]
	v_pk_fma_f32 v[74:75], v[58:59], v[72:73], v[0:1] op_sel_hi:[1,0,1]
	v_mul_f32_e32 v0, v31, v107
	v_fmac_f32_e32 v0, v30, v106
	v_fmac_f32_e32 v0, v32, v74
	v_fmac_f32_e32 v0, v33, v75
	v_pk_mul_f32 v[2:3], v[74:75], v[50:51]
	s_nop 0
	v_add_f32_dpp v0, v0, v0 quad_perm:[1,0,3,2] row_mask:0xf bank_mask:0xf bound_ctrl:1
	s_nop 1
	v_add_f32_dpp v0, v0, v0 quad_perm:[2,3,0,1] row_mask:0xf bank_mask:0xf bound_ctrl:1
	s_nop 1
	v_add_f32_dpp v0, v0, v0 row_half_mirror row_mask:0xf bank_mask:0xf bound_ctrl:1
	s_nop 1
	v_add_f32_dpp v0, v0, v0 row_mirror row_mask:0xf bank_mask:0xf bound_ctrl:1
	v_cndmask_b32_e64 v43, 0, v0, s[38:39]
	v_pk_mul_f32 v[0:1], v[106:107], v[48:49]
	v_add_f32_e32 v0, v0, v1
	v_add_f32_e32 v0, v0, v2
	v_add_f32_e32 v0, v0, v3
	s_nop 1
	v_add_f32_dpp v0, v0, v0 quad_perm:[1,0,3,2] row_mask:0xf bank_mask:0xf bound_ctrl:1
	s_nop 1
	v_add_f32_dpp v0, v0, v0 quad_perm:[2,3,0,1] row_mask:0xf bank_mask:0xf bound_ctrl:1
	s_nop 1
	v_add_f32_dpp v0, v0, v0 row_half_mirror row_mask:0xf bank_mask:0xf bound_ctrl:1
	s_nop 1
	v_add_f32_dpp v32, v0, v0 row_mirror row_mask:0xf bank_mask:0xf bound_ctrl:1
	ds_read2_b32 v[108:109], v42 offset0:32 offset1:48
	ds_read_b128 v[48:51], v41 offset:512
	ds_read_b128 v[52:55], v41 offset:768
	ds_read2_b32 v[30:31], v42 offset0:64 offset1:80
	ds_read_b128 v[0:3], v41 offset:9216
	ds_read_b128 v[56:59], v41 offset:12800
	s_waitcnt lgkmcnt(9)
	v_pk_mul_f32 v[62:63], v[62:63], v[32:33] op_sel_hi:[1,0]
	v_pk_mul_f32 v[32:33], v[60:61], v[32:33] op_sel_hi:[1,0]
	s_waitcnt lgkmcnt(8)
	v_pk_fma_f32 v[62:63], v[74:75], v[66:67], v[62:63] neg_lo:[0,0,1] neg_hi:[0,0,1]
	v_mov_b32_e32 v66, v73
	v_pk_fma_f32 v[32:33], v[106:107], v[64:65], v[32:33] neg_lo:[0,0,1] neg_hi:[0,0,1]
	s_waitcnt lgkmcnt(7)
	v_pk_fma_f32 v[62:63], v[70:71], v[66:67], v[62:63] op_sel_hi:[1,0,1]
	v_pk_fma_f32 v[32:33], v[68:69], v[66:67], v[32:33] op_sel_hi:[1,0,1]
	ds_read_b128 v[70:73], v41 offset:13056
	s_waitcnt lgkmcnt(7)
	v_mul_f32_e32 v60, v45, v33
	v_fmac_f32_e32 v60, v44, v32
	s_waitcnt lgkmcnt(1)
	v_pk_mul_f32 v[44:45], v[32:33], v[56:57]
	v_pk_mul_f32 v[58:59], v[62:63], v[58:59]
	v_add_f32_e32 v44, v44, v45
	v_fmac_f32_e32 v60, v46, v62
	v_add_f32_e32 v44, v44, v58
	v_fmac_f32_e32 v60, v47, v63
	v_add_f32_e32 v44, v44, v59
	ds_read_b128 v[74:77], v41 offset:4608
	ds_read_b128 v[78:81], v41 offset:4864
	ds_read_b128 v[82:85], v41 offset:8704
	ds_read_b128 v[86:89], v41 offset:8960
	ds_read_b128 v[90:93], v41 offset:16896
	ds_read_b128 v[94:97], v41 offset:17152
	v_add_f32_dpp v46, v60, v60 quad_perm:[1,0,3,2] row_mask:0xf bank_mask:0xf bound_ctrl:1
	v_add_f32_dpp v44, v44, v44 quad_perm:[1,0,3,2] row_mask:0xf bank_mask:0xf bound_ctrl:1
	v_mov_b32_e32 v110, v109
	v_add_f32_dpp v46, v46, v46 quad_perm:[2,3,0,1] row_mask:0xf bank_mask:0xf bound_ctrl:1
	v_add_f32_dpp v44, v44, v44 quad_perm:[2,3,0,1] row_mask:0xf bank_mask:0xf bound_ctrl:1
	ds_read_b128 v[98:101], v41 offset:5120
	ds_read_b128 v[102:105], v41 offset:17408
	v_add_f32_dpp v46, v46, v46 row_half_mirror row_mask:0xf bank_mask:0xf bound_ctrl:1
	v_add_f32_dpp v44, v44, v44 row_half_mirror row_mask:0xf bank_mask:0xf bound_ctrl:1
	s_nop 0
	v_add_f32_dpp v46, v46, v46 row_mirror row_mask:0xf bank_mask:0xf bound_ctrl:1
	v_add_f32_dpp v44, v44, v44 row_mirror row_mask:0xf bank_mask:0xf bound_ctrl:1
	v_cndmask_b32_e64 v43, v43, v46, s[4:5]
	s_waitcnt lgkmcnt(3)
	v_pk_mul_f32 v[46:47], v[90:91], v[44:45] op_sel_hi:[1,0]
	v_pk_mul_f32 v[44:45], v[92:93], v[44:45] op_sel_hi:[1,0]
	v_pk_fma_f32 v[32:33], v[32:33], v[74:75], v[46:47] neg_lo:[0,0,1] neg_hi:[0,0,1]
	v_pk_fma_f32 v[44:45], v[62:63], v[76:77], v[44:45] neg_lo:[0,0,1] neg_hi:[0,0,1]
	v_pk_fma_f32 v[32:33], v[82:83], v[108:109], v[32:33] op_sel_hi:[1,0,1]
	v_pk_fma_f32 v[44:45], v[84:85], v[108:109], v[44:45] op_sel_hi:[1,0,1]
	v_mul_f32_e32 v46, v49, v33
	v_fmac_f32_e32 v46, v48, v32
	v_fmac_f32_e32 v46, v50, v44
	v_fmac_f32_e32 v46, v51, v45
	v_pk_mul_f32 v[48:49], v[44:45], v[72:73]
	s_nop 0
	v_add_f32_dpp v46, v46, v46 quad_perm:[1,0,3,2] row_mask:0xf bank_mask:0xf bound_ctrl:1
	s_nop 1
	v_add_f32_dpp v46, v46, v46 quad_perm:[2,3,0,1] row_mask:0xf bank_mask:0xf bound_ctrl:1
	s_nop 1
	v_add_f32_dpp v46, v46, v46 row_half_mirror row_mask:0xf bank_mask:0xf bound_ctrl:1
	s_nop 1
	v_add_f32_dpp v46, v46, v46 row_mirror row_mask:0xf bank_mask:0xf bound_ctrl:1
	v_cndmask_b32_e64 v43, v43, v46, s[6:7]
	v_pk_mul_f32 v[46:47], v[32:33], v[70:71]
	v_add_f32_e32 v46, v46, v47
	v_add_f32_e32 v46, v46, v48
	v_add_f32_e32 v46, v46, v49
	s_nop 1
	v_add_f32_dpp v46, v46, v46 quad_perm:[1,0,3,2] row_mask:0xf bank_mask:0xf bound_ctrl:1
	s_nop 1
	v_add_f32_dpp v46, v46, v46 quad_perm:[2,3,0,1] row_mask:0xf bank_mask:0xf bound_ctrl:1
	s_nop 1
	v_add_f32_dpp v46, v46, v46 row_half_mirror row_mask:0xf bank_mask:0xf bound_ctrl:1
	s_nop 1
	v_add_f32_dpp v46, v46, v46 row_mirror row_mask:0xf bank_mask:0xf bound_ctrl:1
	s_waitcnt lgkmcnt(2)
	v_pk_mul_f32 v[48:49], v[94:95], v[46:47] op_sel_hi:[1,0]
	v_pk_mul_f32 v[46:47], v[96:97], v[46:47] op_sel_hi:[1,0]
	v_pk_fma_f32 v[32:33], v[32:33], v[78:79], v[48:49] neg_lo:[0,0,1] neg_hi:[0,0,1]
	v_pk_fma_f32 v[44:45], v[44:45], v[80:81], v[46:47] neg_lo:[0,0,1] neg_hi:[0,0,1]
	v_pk_fma_f32 v[32:33], v[86:87], v[110:111], v[32:33] op_sel_hi:[1,0,1]
	v_pk_fma_f32 v[56:57], v[88:89], v[110:111], v[44:45] op_sel_hi:[1,0,1]
	v_mul_f32_e32 v44, v53, v33
	v_fmac_f32_e32 v44, v52, v32
	v_fmac_f32_e32 v44, v54, v56
	v_fmac_f32_e32 v44, v55, v57
	ds_read_b128 v[52:55], v41 offset:5376
	s_nop 0
	v_add_f32_dpp v44, v44, v44 quad_perm:[1,0,3,2] row_mask:0xf bank_mask:0xf bound_ctrl:1
	s_nop 1
	v_add_f32_dpp v48, v44, v44 quad_perm:[2,3,0,1] row_mask:0xf bank_mask:0xf bound_ctrl:1
	ds_read_b128 v[44:47], v41 offset:13312
	s_waitcnt lgkmcnt(0)
	v_pk_mul_f32 v[44:45], v[32:33], v[44:45]
	v_pk_mul_f32 v[46:47], v[56:57], v[46:47]
	v_add_f32_e32 v44, v44, v45
	v_add_f32_e32 v44, v44, v46
	v_add_f32_e32 v44, v44, v47
	v_add_f32_dpp v48, v48, v48 row_half_mirror row_mask:0xf bank_mask:0xf bound_ctrl:1
	s_nop 0
	v_add_f32_dpp v44, v44, v44 quad_perm:[1,0,3,2] row_mask:0xf bank_mask:0xf bound_ctrl:1
	v_add_f32_dpp v48, v48, v48 row_mirror row_mask:0xf bank_mask:0xf bound_ctrl:1
	v_cndmask_b32_e64 v43, v43, v48, s[8:9]
	v_add_f32_dpp v44, v44, v44 quad_perm:[2,3,0,1] row_mask:0xf bank_mask:0xf bound_ctrl:1
	ds_read_b128 v[48:51], v41 offset:13568
	s_nop 0
	v_add_f32_dpp v44, v44, v44 row_half_mirror row_mask:0xf bank_mask:0xf bound_ctrl:1
	s_nop 1
	v_add_f32_dpp v58, v44, v44 row_mirror row_mask:0xf bank_mask:0xf bound_ctrl:1
	v_pk_mul_f32 v[60:61], v[102:103], v[58:59] op_sel_hi:[1,0]
	ds_read_b128 v[44:47], v41 offset:17664
	v_pk_fma_f32 v[76:77], v[32:33], v[98:99], v[60:61] neg_lo:[0,0,1] neg_hi:[0,0,1]
	v_pk_mul_f32 v[32:33], v[104:105], v[58:59] op_sel_hi:[1,0]
	v_pk_fma_f32 v[0:1], v[0:1], v[30:31], v[76:77] op_sel_hi:[1,0,1]
	v_pk_fma_f32 v[108:109], v[56:57], v[100:101], v[32:33] neg_lo:[0,0,1] neg_hi:[0,0,1]
	ds_read_b128 v[56:59], v41 offset:1024
	ds_read_b128 v[60:63], v41 offset:1280
	ds_read2_b32 v[110:111], v42 offset0:96 offset1:112
	ds_read_b128 v[64:67], v41 offset:1536
	ds_read_b128 v[68:71], v41 offset:1792
	ds_read2_b32 v[32:33], v42 offset0:128 offset1:144
	ds_read_b128 v[72:75], v41 offset:9472
	s_waitcnt lgkmcnt(6)
	v_mul_f32_e32 v57, v57, v1
	v_pk_mul_f32 v[48:49], v[0:1], v[48:49]
	v_pk_fma_f32 v[2:3], v[2:3], v[30:31], v[108:109] op_sel_hi:[1,0,1]
	v_fmac_f32_e32 v57, v56, v0
	v_mov_b32_e32 v56, v31
	v_pk_mul_f32 v[30:31], v[2:3], v[50:51]
	v_add_f32_e32 v48, v48, v49
	v_add_f32_e32 v30, v48, v30
	v_add_f32_e32 v30, v30, v31
	v_fmac_f32_e32 v57, v58, v2
	v_fmac_f32_e32 v57, v59, v3
	v_add_f32_dpp v30, v30, v30 quad_perm:[1,0,3,2] row_mask:0xf bank_mask:0xf bound_ctrl:1
	ds_read_b128 v[76:79], v41 offset:5632
	ds_read_b128 v[80:83], v41 offset:5888
	ds_read_b128 v[84:87], v41 offset:9728
	ds_read_b128 v[88:91], v41 offset:9984
	ds_read_b128 v[92:95], v41 offset:17920
	ds_read_b128 v[96:99], v41 offset:18176
	v_add_f32_dpp v30, v30, v30 quad_perm:[2,3,0,1] row_mask:0xf bank_mask:0xf bound_ctrl:1
	ds_read_b128 v[100:103], v41 offset:6144
	ds_read_b128 v[104:107], v41 offset:18432
	v_add_f32_dpp v30, v30, v30 row_half_mirror row_mask:0xf bank_mask:0xf bound_ctrl:1
	v_add_f32_dpp v50, v57, v57 quad_perm:[1,0,3,2] row_mask:0xf bank_mask:0xf bound_ctrl:1
	s_waitcnt lgkmcnt(12)
	v_mov_b32_e32 v112, v111
	v_add_f32_dpp v30, v30, v30 row_mirror row_mask:0xf bank_mask:0xf bound_ctrl:1
	v_pk_mul_f32 v[44:45], v[44:45], v[30:31] op_sel_hi:[1,0]
	v_add_f32_dpp v50, v50, v50 quad_perm:[2,3,0,1] row_mask:0xf bank_mask:0xf bound_ctrl:1
	v_pk_fma_f32 v[0:1], v[0:1], v[52:53], v[44:45] neg_lo:[0,0,1] neg_hi:[0,0,1]
	s_waitcnt lgkmcnt(8)
	v_pk_fma_f32 v[48:49], v[72:73], v[56:57], v[0:1] op_sel_hi:[1,0,1]
	v_pk_mul_f32 v[0:1], v[46:47], v[30:31] op_sel_hi:[1,0]
	v_add_f32_dpp v50, v50, v50 row_half_mirror row_mask:0xf bank_mask:0xf bound_ctrl:1
	v_pk_fma_f32 v[0:1], v[2:3], v[54:55], v[0:1] neg_lo:[0,0,1] neg_hi:[0,0,1]
	v_pk_fma_f32 v[30:31], v[74:75], v[56:57], v[0:1] op_sel_hi:[1,0,1]
	v_mul_f32_e32 v0, v61, v49
	v_fmac_f32_e32 v0, v60, v48
	v_fmac_f32_e32 v0, v62, v30
	v_fmac_f32_e32 v0, v63, v31
	v_add_f32_dpp v50, v50, v50 row_mirror row_mask:0xf bank_mask:0xf bound_ctrl:1
	v_cndmask_b32_e64 v43, v43, v50, s[10:11]
	v_add_f32_dpp v0, v0, v0 quad_perm:[1,0,3,2] row_mask:0xf bank_mask:0xf bound_ctrl:1
	s_nop 1
	v_add_f32_dpp v44, v0, v0 quad_perm:[2,3,0,1] row_mask:0xf bank_mask:0xf bound_ctrl:1
	ds_read_b128 v[0:3], v41 offset:13824
	s_nop 0
	v_add_f32_dpp v44, v44, v44 row_half_mirror row_mask:0xf bank_mask:0xf bound_ctrl:1
	s_nop 1
	v_add_f32_dpp v44, v44, v44 row_mirror row_mask:0xf bank_mask:0xf bound_ctrl:1
	v_cndmask_b32_e64 v43, v43, v44, s[12:13]
	ds_read_b128 v[44:47], v41 offset:14080
	s_waitcnt lgkmcnt(1)
	v_pk_mul_f32 v[0:1], v[48:49], v[0:1]
	v_pk_mul_f32 v[2:3], v[30:31], v[2:3]
	v_add_f32_e32 v0, v0, v1
	v_add_f32_e32 v0, v0, v2
	v_add_f32_e32 v0, v0, v3
	s_nop 1
	v_add_f32_dpp v0, v0, v0 quad_perm:[1,0,3,2] row_mask:0xf bank_mask:0xf bound_ctrl:1
	s_nop 1
	v_add_f32_dpp v0, v0, v0 quad_perm:[2,3,0,1] row_mask:0xf bank_mask:0xf bound_ctrl:1
	s_nop 1
	v_add_f32_dpp v0, v0, v0 row_half_mirror row_mask:0xf bank_mask:0xf bound_ctrl:1
	s_nop 1
	v_add_f32_dpp v0, v0, v0 row_mirror row_mask:0xf bank_mask:0xf bound_ctrl:1
	v_pk_mul_f32 v[2:3], v[92:93], v[0:1] op_sel_hi:[1,0]
	v_pk_mul_f32 v[0:1], v[94:95], v[0:1] op_sel_hi:[1,0]
	v_pk_fma_f32 v[2:3], v[48:49], v[76:77], v[2:3] neg_lo:[0,0,1] neg_hi:[0,0,1]
	v_pk_fma_f32 v[0:1], v[30:31], v[78:79], v[0:1] neg_lo:[0,0,1] neg_hi:[0,0,1]
	v_pk_fma_f32 v[2:3], v[84:85], v[110:111], v[2:3] op_sel_hi:[1,0,1]
	v_pk_fma_f32 v[0:1], v[86:87], v[110:111], v[0:1] op_sel_hi:[1,0,1]
	v_mul_f32_e32 v30, v65, v3
	v_fmac_f32_e32 v30, v64, v2
	v_fmac_f32_e32 v30, v66, v0
	v_fmac_f32_e32 v30, v67, v1
	s_nop 1
	v_add_f32_dpp v30, v30, v30 quad_perm:[1,0,3,2] row_mask:0xf bank_mask:0xf bound_ctrl:1
	s_nop 1
	v_add_f32_dpp v30, v30, v30 quad_perm:[2,3,0,1] row_mask:0xf bank_mask:0xf bound_ctrl:1
	s_nop 1
	v_add_f32_dpp v30, v30, v30 row_half_mirror row_mask:0xf bank_mask:0xf bound_ctrl:1
	s_nop 1
	v_add_f32_dpp v30, v30, v30 row_mirror row_mask:0xf bank_mask:0xf bound_ctrl:1
	v_cndmask_b32_e64 v43, v43, v30, s[14:15]
	s_waitcnt lgkmcnt(0)
	v_pk_mul_f32 v[30:31], v[2:3], v[44:45]
	v_pk_mul_f32 v[44:45], v[0:1], v[46:47]
	v_add_f32_e32 v30, v30, v31
	v_add_f32_e32 v30, v30, v44
	v_add_f32_e32 v30, v30, v45
	s_nop 1
	v_add_f32_dpp v30, v30, v30 quad_perm:[1,0,3,2] row_mask:0xf bank_mask:0xf bound_ctrl:1
	s_nop 1
	v_add_f32_dpp v30, v30, v30 quad_perm:[2,3,0,1] row_mask:0xf bank_mask:0xf bound_ctrl:1
	s_nop 1
	v_add_f32_dpp v30, v30, v30 row_half_mirror row_mask:0xf bank_mask:0xf bound_ctrl:1
	s_nop 1
	v_add_f32_dpp v30, v30, v30 row_mirror row_mask:0xf bank_mask:0xf bound_ctrl:1
	v_pk_mul_f32 v[44:45], v[96:97], v[30:31] op_sel_hi:[1,0]
	v_pk_fma_f32 v[2:3], v[2:3], v[80:81], v[44:45] neg_lo:[0,0,1] neg_hi:[0,0,1]
	v_pk_fma_f32 v[108:109], v[88:89], v[112:113], v[2:3] op_sel_hi:[1,0,1]
	v_pk_mul_f32 v[2:3], v[98:99], v[30:31] op_sel_hi:[1,0]
	v_pk_fma_f32 v[0:1], v[0:1], v[82:83], v[2:3] neg_lo:[0,0,1] neg_hi:[0,0,1]
	v_pk_fma_f32 v[30:31], v[90:91], v[112:113], v[0:1] op_sel_hi:[1,0,1]
	v_mul_f32_e32 v0, v69, v109
	v_fmac_f32_e32 v0, v68, v108
	v_fmac_f32_e32 v0, v70, v30
	v_fmac_f32_e32 v0, v71, v31
	s_nop 1
	v_add_f32_dpp v0, v0, v0 quad_perm:[1,0,3,2] row_mask:0xf bank_mask:0xf bound_ctrl:1
	s_nop 1
	v_add_f32_dpp v44, v0, v0 quad_perm:[2,3,0,1] row_mask:0xf bank_mask:0xf bound_ctrl:1
	ds_read_b128 v[0:3], v41 offset:14336
	s_nop 0
	v_add_f32_dpp v44, v44, v44 row_half_mirror row_mask:0xf bank_mask:0xf bound_ctrl:1
	s_nop 1
	v_add_f32_dpp v44, v44, v44 row_mirror row_mask:0xf bank_mask:0xf bound_ctrl:1
	v_cndmask_b32_e64 v43, v43, v44, s[16:17]
	ds_read_b128 v[44:47], v41 offset:14592
	s_waitcnt lgkmcnt(1)
	v_pk_mul_f32 v[0:1], v[108:109], v[0:1]
	v_pk_mul_f32 v[2:3], v[30:31], v[2:3]
	v_add_f32_e32 v0, v0, v1
	v_add_f32_e32 v0, v0, v2
	v_add_f32_e32 v0, v0, v3
	s_nop 1
	v_add_f32_dpp v0, v0, v0 quad_perm:[1,0,3,2] row_mask:0xf bank_mask:0xf bound_ctrl:1
	s_nop 1
	v_add_f32_dpp v0, v0, v0 quad_perm:[2,3,0,1] row_mask:0xf bank_mask:0xf bound_ctrl:1
	s_nop 1
	v_add_f32_dpp v0, v0, v0 row_half_mirror row_mask:0xf bank_mask:0xf bound_ctrl:1
	s_nop 1
	v_add_f32_dpp v48, v0, v0 row_mirror row_mask:0xf bank_mask:0xf bound_ctrl:1
	ds_read_b128 v[0:3], v41 offset:18688
	v_pk_mul_f32 v[104:105], v[104:105], v[48:49] op_sel_hi:[1,0]
	v_pk_mul_f32 v[64:65], v[106:107], v[48:49] op_sel_hi:[1,0]
	ds_read_b128 v[48:51], v41 offset:2048
	ds_read_b128 v[52:55], v41 offset:2304
	ds_read_b128 v[56:59], v41 offset:10240
	ds_read2_b32 v[106:107], v42 offset0:160 offset1:176
	ds_read_b128 v[60:63], v41 offset:6400
	v_pk_fma_f32 v[30:31], v[30:31], v[102:103], v[64:65] neg_lo:[0,0,1] neg_hi:[0,0,1]
	v_pk_fma_f32 v[100:101], v[108:109], v[100:101], v[104:105] neg_lo:[0,0,1] neg_hi:[0,0,1]
	s_waitcnt lgkmcnt(2)
	v_pk_fma_f32 v[30:31], v[58:59], v[32:33], v[30:31] op_sel_hi:[1,0,1]
	v_mov_b32_e32 v58, v33
	v_pk_fma_f32 v[32:33], v[56:57], v[32:33], v[100:101] op_sel_hi:[1,0,1]
	v_pk_mul_f32 v[46:47], v[30:31], v[46:47]
	v_pk_mul_f32 v[44:45], v[32:33], v[44:45]
	ds_read_b128 v[64:67], v41 offset:10496
	v_add_f32_e32 v44, v44, v45
	v_add_f32_e32 v44, v44, v46
	v_add_f32_e32 v44, v44, v47
	v_mul_f32_e32 v49, v49, v33
	v_fmac_f32_e32 v49, v48, v32
	v_add_f32_dpp v44, v44, v44 quad_perm:[1,0,3,2] row_mask:0xf bank_mask:0xf bound_ctrl:1
	v_fmac_f32_e32 v49, v50, v30
	v_fmac_f32_e32 v49, v51, v31
	v_add_f32_dpp v44, v44, v44 quad_perm:[2,3,0,1] row_mask:0xf bank_mask:0xf bound_ctrl:1
	ds_read_b128 v[68:71], v41 offset:2560
	ds_read_b128 v[72:75], v41 offset:2816
	ds_read_b128 v[76:79], v41 offset:6656
	ds_read_b128 v[80:83], v41 offset:6912
	ds_read_b128 v[84:87], v41 offset:10752
	ds_read_b128 v[88:91], v41 offset:11008
	ds_read_b128 v[92:95], v41 offset:18944
	ds_read_b128 v[96:99], v41 offset:19200
	v_add_f32_dpp v44, v44, v44 row_half_mirror row_mask:0xf bank_mask:0xf bound_ctrl:1
	v_add_f32_dpp v48, v49, v49 quad_perm:[1,0,3,2] row_mask:0xf bank_mask:0xf bound_ctrl:1
	s_waitcnt lgkmcnt(10)
	v_mov_b32_e32 v102, v107
	v_add_f32_dpp v44, v44, v44 row_mirror row_mask:0xf bank_mask:0xf bound_ctrl:1
	v_pk_mul_f32 v[0:1], v[0:1], v[44:45] op_sel_hi:[1,0]
	v_add_f32_dpp v48, v48, v48 quad_perm:[2,3,0,1] row_mask:0xf bank_mask:0xf bound_ctrl:1
	s_waitcnt lgkmcnt(9)
	v_pk_fma_f32 v[0:1], v[32:33], v[60:61], v[0:1] neg_lo:[0,0,1] neg_hi:[0,0,1]
	s_waitcnt lgkmcnt(8)
	v_pk_fma_f32 v[46:47], v[64:65], v[58:59], v[0:1] op_sel_hi:[1,0,1]
	v_pk_mul_f32 v[0:1], v[2:3], v[44:45] op_sel_hi:[1,0]
	v_mul_f32_e32 v2, v53, v47
	v_pk_fma_f32 v[0:1], v[30:31], v[62:63], v[0:1] neg_lo:[0,0,1] neg_hi:[0,0,1]
	v_fmac_f32_e32 v2, v52, v46
	v_pk_fma_f32 v[44:45], v[66:67], v[58:59], v[0:1] op_sel_hi:[1,0,1]
	v_add_f32_dpp v48, v48, v48 row_half_mirror row_mask:0xf bank_mask:0xf bound_ctrl:1
	v_pk_mul_f32 v[0:1], v[54:55], v[44:45]
	v_add_f32_e32 v0, v0, v2
	v_add_f32_e32 v0, v1, v0
	v_add_f32_dpp v48, v48, v48 row_mirror row_mask:0xf bank_mask:0xf bound_ctrl:1
	v_cndmask_b32_e64 v43, v43, v48, s[18:19]
	v_add_f32_dpp v0, v0, v0 quad_perm:[1,0,3,2] row_mask:0xf bank_mask:0xf bound_ctrl:1
	s_nop 1
	v_add_f32_dpp v30, v0, v0 quad_perm:[2,3,0,1] row_mask:0xf bank_mask:0xf bound_ctrl:1
	ds_read_b128 v[0:3], v41 offset:14848
	s_nop 0
	v_add_f32_dpp v30, v30, v30 row_half_mirror row_mask:0xf bank_mask:0xf bound_ctrl:1
	s_nop 1
	v_add_f32_dpp v30, v30, v30 row_mirror row_mask:0xf bank_mask:0xf bound_ctrl:1
	v_cndmask_b32_e64 v43, v43, v30, s[20:21]
	ds_read_b128 v[30:33], v41 offset:15104
	s_waitcnt lgkmcnt(1)
	v_pk_mul_f32 v[0:1], v[46:47], v[0:1]
	v_pk_mul_f32 v[2:3], v[44:45], v[2:3]
	v_add_f32_e32 v0, v0, v1
	v_add_f32_e32 v0, v0, v2
	v_add_f32_e32 v0, v0, v3
	s_nop 1
	v_add_f32_dpp v0, v0, v0 quad_perm:[1,0,3,2] row_mask:0xf bank_mask:0xf bound_ctrl:1
	s_nop 1
	v_add_f32_dpp v0, v0, v0 quad_perm:[2,3,0,1] row_mask:0xf bank_mask:0xf bound_ctrl:1
	s_nop 1
	v_add_f32_dpp v0, v0, v0 row_half_mirror row_mask:0xf bank_mask:0xf bound_ctrl:1
	s_nop 1
	v_add_f32_dpp v0, v0, v0 row_mirror row_mask:0xf bank_mask:0xf bound_ctrl:1
	v_pk_mul_f32 v[2:3], v[92:93], v[0:1] op_sel_hi:[1,0]
	v_pk_mul_f32 v[0:1], v[94:95], v[0:1] op_sel_hi:[1,0]
	v_pk_fma_f32 v[2:3], v[46:47], v[76:77], v[2:3] neg_lo:[0,0,1] neg_hi:[0,0,1]
	v_pk_fma_f32 v[0:1], v[44:45], v[78:79], v[0:1] neg_lo:[0,0,1] neg_hi:[0,0,1]
	v_pk_fma_f32 v[2:3], v[84:85], v[106:107], v[2:3] op_sel_hi:[1,0,1]
	v_pk_fma_f32 v[0:1], v[86:87], v[106:107], v[0:1] op_sel_hi:[1,0,1]
	s_waitcnt lgkmcnt(0)
	v_pk_mul_f32 v[30:31], v[2:3], v[30:31]
	v_pk_mul_f32 v[32:33], v[0:1], v[32:33]
	v_add_f32_e32 v30, v30, v31
	v_add_f32_e32 v30, v30, v32
	v_add_f32_e32 v30, v30, v33
	v_mul_f32_e32 v46, v69, v3
	v_fmac_f32_e32 v46, v68, v2
	v_add_f32_dpp v30, v30, v30 quad_perm:[1,0,3,2] row_mask:0xf bank_mask:0xf bound_ctrl:1
	v_pk_mul_f32 v[44:45], v[70:71], v[0:1]
	s_nop 0
	v_add_f32_dpp v30, v30, v30 quad_perm:[2,3,0,1] row_mask:0xf bank_mask:0xf bound_ctrl:1
	v_add_f32_e32 v44, v44, v46
	v_add_f32_e32 v44, v45, v44
	v_add_f32_dpp v30, v30, v30 row_half_mirror row_mask:0xf bank_mask:0xf bound_ctrl:1
	s_nop 0
	v_add_f32_dpp v44, v44, v44 quad_perm:[1,0,3,2] row_mask:0xf bank_mask:0xf bound_ctrl:1
	v_add_f32_dpp v30, v30, v30 row_mirror row_mask:0xf bank_mask:0xf bound_ctrl:1
	v_pk_mul_f32 v[32:33], v[96:97], v[30:31] op_sel_hi:[1,0]
	v_add_f32_dpp v44, v44, v44 quad_perm:[2,3,0,1] row_mask:0xf bank_mask:0xf bound_ctrl:1
	v_pk_fma_f32 v[2:3], v[2:3], v[80:81], v[32:33] neg_lo:[0,0,1] neg_hi:[0,0,1]
	v_pk_fma_f32 v[60:61], v[88:89], v[102:103], v[2:3] op_sel_hi:[1,0,1]
	v_pk_mul_f32 v[2:3], v[98:99], v[30:31] op_sel_hi:[1,0]
	v_add_f32_dpp v44, v44, v44 row_half_mirror row_mask:0xf bank_mask:0xf bound_ctrl:1
	v_pk_fma_f32 v[0:1], v[0:1], v[82:83], v[2:3] neg_lo:[0,0,1] neg_hi:[0,0,1]
	v_pk_fma_f32 v[88:89], v[90:91], v[102:103], v[0:1] op_sel_hi:[1,0,1]
	v_pk_mul_f32 v[0:1], v[72:73], v[60:61]
	v_pk_mul_f32 v[2:3], v[74:75], v[88:89]
	v_add_f32_e32 v0, v0, v1
	v_add_f32_e32 v0, v2, v0
	v_add_f32_e32 v0, v3, v0
	v_add_f32_dpp v44, v44, v44 row_mirror row_mask:0xf bank_mask:0xf bound_ctrl:1
	v_cndmask_b32_e64 v43, v43, v44, s[22:23]
	v_add_f32_dpp v0, v0, v0 quad_perm:[1,0,3,2] row_mask:0xf bank_mask:0xf bound_ctrl:1
	s_nop 1
	v_add_f32_dpp v0, v0, v0 quad_perm:[2,3,0,1] row_mask:0xf bank_mask:0xf bound_ctrl:1
	s_nop 1
	v_add_f32_dpp v30, v0, v0 row_half_mirror row_mask:0xf bank_mask:0xf bound_ctrl:1
	ds_read_b128 v[0:3], v41 offset:15360
	s_waitcnt lgkmcnt(0)
	v_pk_mul_f32 v[0:1], v[60:61], v[0:1]
	v_pk_mul_f32 v[2:3], v[88:89], v[2:3]
	v_add_f32_e32 v0, v0, v1
	v_add_f32_e32 v0, v0, v2
	v_add_f32_e32 v0, v0, v3
	v_add_f32_dpp v30, v30, v30 row_mirror row_mask:0xf bank_mask:0xf bound_ctrl:1
	v_cndmask_b32_e64 v97, v43, v30, s[24:25]
	v_add_f32_dpp v0, v0, v0 quad_perm:[1,0,3,2] row_mask:0xf bank_mask:0xf bound_ctrl:1
	ds_read2_b32 v[90:91], v42 offset0:192 offset1:208
	ds_read_b128 v[30:33], v41 offset:15616
	v_add_f32_dpp v43, v0, v0 quad_perm:[2,3,0,1] row_mask:0xf bank_mask:0xf bound_ctrl:1
	ds_read_b128 v[0:3], v41 offset:19456
	ds_read_b128 v[44:47], v41 offset:7168
	ds_read_b128 v[48:51], v41 offset:19712
	v_add_f32_dpp v43, v43, v43 row_half_mirror row_mask:0xf bank_mask:0xf bound_ctrl:1
	s_waitcnt lgkmcnt(4)
	v_mov_b32_e32 v96, v91
	v_add_f32_dpp v52, v43, v43 row_mirror row_mask:0xf bank_mask:0xf bound_ctrl:1
	s_waitcnt lgkmcnt(2)
	v_pk_mul_f32 v[62:63], v[0:1], v[52:53] op_sel_hi:[1,0]
	v_pk_mul_f32 v[92:93], v[2:3], v[52:53] op_sel_hi:[1,0]
	ds_read2_b32 v[94:95], v42 offset0:224 offset1:240
	ds_read_b128 v[0:3], v41 offset:11264
	ds_read_b128 v[52:55], v41 offset:3072
	ds_read_b128 v[56:59], v41 offset:7424
	s_waitcnt lgkmcnt(5)
	v_pk_fma_f32 v[60:61], v[60:61], v[44:45], v[62:63] neg_lo:[0,0,1] neg_hi:[0,0,1]
	v_pk_fma_f32 v[46:47], v[88:89], v[46:47], v[92:93] neg_lo:[0,0,1] neg_hi:[0,0,1]
	s_waitcnt lgkmcnt(2)
	v_pk_fma_f32 v[0:1], v[0:1], v[90:91], v[60:61] op_sel_hi:[1,0,1]
	v_pk_fma_f32 v[2:3], v[2:3], v[90:91], v[46:47] op_sel_hi:[1,0,1]
	v_pk_mul_f32 v[30:31], v[0:1], v[30:31]
	v_pk_mul_f32 v[32:33], v[2:3], v[32:33]
	v_add_f32_e32 v30, v30, v31
	v_add_f32_e32 v30, v30, v32
	v_add_f32_e32 v30, v30, v33
	ds_read_b128 v[42:45], v41 offset:11520
	ds_read_b128 v[60:63], v41 offset:3328
	v_add_f32_dpp v30, v30, v30 quad_perm:[1,0,3,2] row_mask:0xf bank_mask:0xf bound_ctrl:1
	s_waitcnt lgkmcnt(3)
	v_pk_mul_f32 v[52:53], v[52:53], v[0:1]
	v_pk_mul_f32 v[46:47], v[54:55], v[2:3]
	v_add_f32_dpp v30, v30, v30 quad_perm:[2,3,0,1] row_mask:0xf bank_mask:0xf bound_ctrl:1
	v_add_f32_e32 v52, v52, v53
	v_add_f32_e32 v46, v46, v52
	v_add_f32_dpp v30, v30, v30 row_half_mirror row_mask:0xf bank_mask:0xf bound_ctrl:1
	v_add_f32_e32 v46, v47, v46
	ds_read_b128 v[64:67], v41 offset:7680
	ds_read_b128 v[68:71], v41 offset:7936
	ds_read_b128 v[72:75], v41 offset:11776
	ds_read_b128 v[76:79], v41 offset:12032
	ds_read_b128 v[80:83], v41 offset:19968
	ds_read_b128 v[84:87], v41 offset:20224
	v_add_f32_dpp v30, v30, v30 row_mirror row_mask:0xf bank_mask:0xf bound_ctrl:1
	v_pk_mul_f32 v[32:33], v[48:49], v[30:31] op_sel_hi:[1,0]
	v_add_f32_dpp v46, v46, v46 quad_perm:[1,0,3,2] row_mask:0xf bank_mask:0xf bound_ctrl:1
	s_waitcnt lgkmcnt(8)
	v_pk_fma_f32 v[0:1], v[0:1], v[56:57], v[32:33] neg_lo:[0,0,1] neg_hi:[0,0,1]
	v_mov_b32_e32 v98, v95
	s_waitcnt lgkmcnt(7)
	v_pk_fma_f32 v[42:43], v[42:43], v[96:97], v[0:1] op_sel_hi:[1,0,1]
	v_pk_mul_f32 v[0:1], v[50:51], v[30:31] op_sel_hi:[1,0]
	v_add_f32_dpp v46, v46, v46 quad_perm:[2,3,0,1] row_mask:0xf bank_mask:0xf bound_ctrl:1
	v_pk_fma_f32 v[0:1], v[2:3], v[58:59], v[0:1] neg_lo:[0,0,1] neg_hi:[0,0,1]
	v_pk_fma_f32 v[44:45], v[44:45], v[96:97], v[0:1] op_sel_hi:[1,0,1]
	s_waitcnt lgkmcnt(6)
	v_pk_mul_f32 v[0:1], v[60:61], v[42:43]
	v_pk_mul_f32 v[2:3], v[62:63], v[44:45]
	v_add_f32_e32 v0, v0, v1
	v_add_f32_e32 v0, v2, v0
	v_add_f32_e32 v0, v3, v0
	v_add_f32_dpp v46, v46, v46 row_half_mirror row_mask:0xf bank_mask:0xf bound_ctrl:1
	s_nop 0
	v_add_f32_dpp v0, v0, v0 quad_perm:[1,0,3,2] row_mask:0xf bank_mask:0xf bound_ctrl:1
	v_add_f32_dpp v46, v46, v46 row_mirror row_mask:0xf bank_mask:0xf bound_ctrl:1
	v_cndmask_b32_e64 v46, v97, v46, s[26:27]
	v_add_f32_dpp v30, v0, v0 quad_perm:[2,3,0,1] row_mask:0xf bank_mask:0xf bound_ctrl:1
	ds_read_b128 v[0:3], v41 offset:15872
	s_nop 0
	v_add_f32_dpp v30, v30, v30 row_half_mirror row_mask:0xf bank_mask:0xf bound_ctrl:1
	s_nop 1
	v_add_f32_dpp v30, v30, v30 row_mirror row_mask:0xf bank_mask:0xf bound_ctrl:1
	v_cndmask_b32_e64 v50, v46, v30, s[28:29]
	ds_read_b128 v[30:33], v41 offset:16128
	s_waitcnt lgkmcnt(1)
	v_pk_mul_f32 v[0:1], v[42:43], v[0:1]
	v_pk_mul_f32 v[2:3], v[44:45], v[2:3]
	v_add_f32_e32 v0, v0, v1
	v_add_f32_e32 v0, v0, v2
	v_add_f32_e32 v0, v0, v3
	s_nop 1
	v_add_f32_dpp v0, v0, v0 quad_perm:[1,0,3,2] row_mask:0xf bank_mask:0xf bound_ctrl:1
	s_nop 1
	v_add_f32_dpp v0, v0, v0 quad_perm:[2,3,0,1] row_mask:0xf bank_mask:0xf bound_ctrl:1
	s_nop 1
	v_add_f32_dpp v0, v0, v0 row_half_mirror row_mask:0xf bank_mask:0xf bound_ctrl:1
	s_nop 1
	v_add_f32_dpp v46, v0, v0 row_mirror row_mask:0xf bank_mask:0xf bound_ctrl:1
	v_pk_mul_f32 v[0:1], v[80:81], v[46:47] op_sel_hi:[1,0]
	v_pk_fma_f32 v[0:1], v[42:43], v[64:65], v[0:1] neg_lo:[0,0,1] neg_hi:[0,0,1]
	v_pk_mul_f32 v[42:43], v[82:83], v[46:47] op_sel_hi:[1,0]
	v_pk_fma_f32 v[48:49], v[72:73], v[94:95], v[0:1] op_sel_hi:[1,0,1]
	ds_read_b128 v[0:3], v41 offset:3584
	v_pk_fma_f32 v[42:43], v[44:45], v[66:67], v[42:43] neg_lo:[0,0,1] neg_hi:[0,0,1]
	v_pk_fma_f32 v[46:47], v[74:75], v[94:95], v[42:43] op_sel_hi:[1,0,1]
	ds_read_b128 v[42:45], v41 offset:3840
	s_waitcnt lgkmcnt(1)
	v_pk_mul_f32 v[0:1], v[0:1], v[48:49]
	v_pk_mul_f32 v[2:3], v[2:3], v[46:47]
	v_add_f32_e32 v0, v0, v1
	v_add_f32_e32 v0, v2, v0
	v_add_f32_e32 v0, v3, v0
	v_pk_mul_f32 v[2:3], v[46:47], v[32:33]
	s_nop 0
	v_add_f32_dpp v0, v0, v0 quad_perm:[1,0,3,2] row_mask:0xf bank_mask:0xf bound_ctrl:1
	s_nop 1
	v_add_f32_dpp v0, v0, v0 quad_perm:[2,3,0,1] row_mask:0xf bank_mask:0xf bound_ctrl:1
	s_nop 1
	v_add_f32_dpp v0, v0, v0 row_half_mirror row_mask:0xf bank_mask:0xf bound_ctrl:1
	s_nop 1
	v_add_f32_dpp v0, v0, v0 row_mirror row_mask:0xf bank_mask:0xf bound_ctrl:1
	v_cndmask_b32_e64 v41, v50, v0, s[30:31]
	v_pk_mul_f32 v[0:1], v[48:49], v[30:31]
	v_add_f32_e32 v0, v0, v1
	v_add_f32_e32 v0, v0, v2
	v_add_f32_e32 v0, v0, v3
	s_nop 1
	v_add_f32_dpp v0, v0, v0 quad_perm:[1,0,3,2] row_mask:0xf bank_mask:0xf bound_ctrl:1
	s_nop 1
	v_add_f32_dpp v0, v0, v0 quad_perm:[2,3,0,1] row_mask:0xf bank_mask:0xf bound_ctrl:1
	s_nop 1
	v_add_f32_dpp v0, v0, v0 row_half_mirror row_mask:0xf bank_mask:0xf bound_ctrl:1
	s_nop 1
	v_add_f32_dpp v2, v0, v0 row_mirror row_mask:0xf bank_mask:0xf bound_ctrl:1
	v_pk_mul_f32 v[0:1], v[84:85], v[2:3] op_sel_hi:[1,0]
	v_pk_mul_f32 v[2:3], v[86:87], v[2:3] op_sel_hi:[1,0]
	v_pk_fma_f32 v[0:1], v[48:49], v[68:69], v[0:1] neg_lo:[0,0,1] neg_hi:[0,0,1]
	v_pk_fma_f32 v[2:3], v[46:47], v[70:71], v[2:3] neg_lo:[0,0,1] neg_hi:[0,0,1]
	v_pk_fma_f32 v[0:1], v[76:77], v[98:99], v[0:1] op_sel_hi:[1,0,1]
	v_pk_fma_f32 v[2:3], v[78:79], v[98:99], v[2:3] op_sel_hi:[1,0,1]
	s_waitcnt lgkmcnt(0)
	v_pk_mul_f32 v[30:31], v[42:43], v[0:1]
	v_pk_mul_f32 v[32:33], v[44:45], v[2:3]
	v_add_f32_e32 v30, v30, v31
	v_add_f32_e32 v30, v32, v30
	v_add_f32_e32 v30, v33, v30
	s_nop 1
	v_add_f32_dpp v30, v30, v30 quad_perm:[1,0,3,2] row_mask:0xf bank_mask:0xf bound_ctrl:1
	s_nop 1
	v_add_f32_dpp v30, v30, v30 quad_perm:[2,3,0,1] row_mask:0xf bank_mask:0xf bound_ctrl:1
	s_nop 1
	v_add_f32_dpp v30, v30, v30 row_half_mirror row_mask:0xf bank_mask:0xf bound_ctrl:1
	s_nop 1
	v_add_f32_dpp v30, v30, v30 row_mirror row_mask:0xf bank_mask:0xf bound_ctrl:1
	v_cndmask_b32_e64 v32, v41, v30, s[34:35]
	v_cndmask_b32_e64 v30, v5, v40, s[0:1]
	v_add_u32_e32 v30, s82, v30
	v_ashrrev_i32_e32 v31, 31, v30
	v_lshlrev_b64 v[30:31], 10, v[30:31]
	v_lshl_add_u64 v[30:31], v[28:29], 0, v[30:31]
	global_store_dword v[30:31], v32, off
	s_cbranch_vccnz .LBB0_455
	s_bitcmp1_b32 s33, 0
	s_cselect_b32 s46, 0x6000, 0
	s_add_i32 s46, s78, s46
	s_waitcnt vmcnt(6)
	v_lshlrev_b32_e32 v30, 16, v10
	v_and_b32_e32 v31, 0xffff0000, v10
	v_lshlrev_b32_e32 v32, 16, v11
	v_and_b32_e32 v33, 0xffff0000, v11
	v_lshl_add_u32 v41, v7, 4, s46
	ds_write_b128 v41, v[30:33]
	s_waitcnt vmcnt(5)
	v_lshlrev_b32_e32 v30, 16, v12
	v_and_b32_e32 v31, 0xffff0000, v12
	v_lshlrev_b32_e32 v32, 16, v13
	v_and_b32_e32 v33, 0xffff0000, v13
	v_lshl_add_u32 v42, v36, 4, s46
	ds_write_b128 v42, v[30:33] offset:4096
	s_waitcnt vmcnt(4)
	v_lshlrev_b32_e32 v30, 16, v14
	v_and_b32_e32 v31, 0xffff0000, v14
	v_lshlrev_b32_e32 v32, 16, v15
	v_and_b32_e32 v33, 0xffff0000, v15
	ds_write_b128 v42, v[30:33] offset:8192
	s_waitcnt vmcnt(3)
	v_lshlrev_b32_e32 v30, 16, v16
	v_and_b32_e32 v31, 0xffff0000, v16
	v_lshlrev_b32_e32 v32, 16, v17
	v_and_b32_e32 v33, 0xffff0000, v17
	ds_write_b128 v42, v[30:33] offset:12288
	s_waitcnt vmcnt(2)
	v_lshlrev_b32_e32 v30, 16, v18
	v_and_b32_e32 v31, 0xffff0000, v18
	v_lshlrev_b32_e32 v32, 16, v19
	v_and_b32_e32 v33, 0xffff0000, v19
	ds_write_b128 v42, v[30:33] offset:16384
	s_waitcnt vmcnt(1)
	v_lshlrev_b32_e32 v30, 16, v35
	v_add_u32_e32 v31, v41, v37
	ds_write_b32 v31, v30 offset:20480
